# nt hint also on the read-once f32 weight loads of all transpose-copy passes and on the K/V cache staging loads
# speedup vs baseline: 1.0057x; 1.0035x over previous
; __device__ __forceinline__ void tr_load(const TrItem& t, float (&tv)[32], int lane) {
;     const int nn = t.n0 + (lane & 31); const bool ok = nn < t.N;
;     const float* p = t.W + (size_t)(t.k0 + 32 * (lane >> 5)) * t.N + nn; const size_t st = (size_t)t.N;
; #pragma unroll
;     for (int i = 0; i < 32; ++i) { tv[i] = ok ? *p : 0.f; p += st; }
; }
.LBB0_14:
	s_load_dwordx4 s[16:19], s[6:7], 0x0
	v_cndmask_b32_e64 v1, 0, 1, s[8:9]
	v_cmp_ne_u32_e64 s[6:7], 1, v1
	s_andn2_b64 vcc, exec, s[8:9]
	v_and_b32_e32 v1, 31, v3
	v_and_b32_e32 v2, 32, v3
	s_cbranch_vccnz .LBB0_76
	v_add_u32_e32 v5, s36, v2
	v_add_u32_e32 v4, s5, v1
	v_mad_i64_i32 v[6:7], s[8:9], v5, s42, 0
	v_lshl_add_u64 v[6:7], v[6:7], 2, s[38:39]
	v_ashrrev_i32_e32 v5, 31, v4
	v_cmp_gt_i32_e32 vcc, s42, v4
	s_ashr_i32 s43, s42, 31
	v_lshl_add_u64 v[6:7], v[4:5], 2, v[6:7]
	v_mov_b32_e32 v5, 0
	v_mov_b32_e32 v4, 0
	s_and_saveexec_b64 s[8:9], vcc
	s_cbranch_execz .LBB0_17
	global_load_dword v4, v[6:7], off nt
.LBB0_17:
	s_or_b64 exec, exec, s[8:9]
	v_lshl_add_u64 v[6:7], s[42:43], 2, v[6:7]
	s_and_saveexec_b64 s[8:9], vcc
	s_cbranch_execz .LBB0_19
	global_load_dword v5, v[6:7], off nt
.LBB0_19:
	s_or_b64 exec, exec, s[8:9]
	v_lshl_add_u64 v[8:9], s[42:43], 2, v[6:7]
	v_mov_b32_e32 v7, 0
	v_mov_b32_e32 v6, 0
	s_and_saveexec_b64 s[8:9], vcc
	s_cbranch_execz .LBB0_21
	global_load_dword v6, v[8:9], off nt
.LBB0_21:
	s_or_b64 exec, exec, s[8:9]
	v_lshl_add_u64 v[8:9], s[42:43], 2, v[8:9]
	s_and_saveexec_b64 s[8:9], vcc
	s_cbranch_execz .LBB0_23
	global_load_dword v7, v[8:9], off nt
.LBB0_23:
	s_or_b64 exec, exec, s[8:9]
	v_lshl_add_u64 v[10:11], s[42:43], 2, v[8:9]
	v_mov_b32_e32 v9, 0
	v_mov_b32_e32 v8, 0
	s_and_saveexec_b64 s[8:9], vcc
	s_cbranch_execz .LBB0_25
	global_load_dword v8, v[10:11], off nt
.LBB0_25:
	s_or_b64 exec, exec, s[8:9]
	v_lshl_add_u64 v[10:11], s[42:43], 2, v[10:11]
	s_and_saveexec_b64 s[8:9], vcc
	s_cbranch_execz .LBB0_27
	global_load_dword v9, v[10:11], off nt
.LBB0_27:
	s_or_b64 exec, exec, s[8:9]
	v_lshl_add_u64 v[12:13], s[42:43], 2, v[10:11]
	v_mov_b32_e32 v11, 0
	v_mov_b32_e32 v10, 0
	s_and_saveexec_b64 s[8:9], vcc
	s_cbranch_execz .LBB0_29
	global_load_dword v10, v[12:13], off nt
.LBB0_29:
	s_or_b64 exec, exec, s[8:9]
	v_lshl_add_u64 v[12:13], s[42:43], 2, v[12:13]
	s_and_saveexec_b64 s[8:9], vcc
	s_cbranch_execz .LBB0_31
	global_load_dword v11, v[12:13], off nt
.LBB0_31:
	s_or_b64 exec, exec, s[8:9]
	v_lshl_add_u64 v[14:15], s[42:43], 2, v[12:13]
	v_mov_b32_e32 v13, 0
	v_mov_b32_e32 v12, 0
	s_and_saveexec_b64 s[8:9], vcc
	s_cbranch_execz .LBB0_33
	global_load_dword v12, v[14:15], off nt
.LBB0_33:
	s_or_b64 exec, exec, s[8:9]
	v_lshl_add_u64 v[14:15], s[42:43], 2, v[14:15]
	s_and_saveexec_b64 s[8:9], vcc
	s_cbranch_execz .LBB0_35
	global_load_dword v13, v[14:15], off nt
.LBB0_35:
	s_or_b64 exec, exec, s[8:9]
	v_lshl_add_u64 v[16:17], s[42:43], 2, v[14:15]
	v_mov_b32_e32 v15, 0
	v_mov_b32_e32 v14, 0
	s_and_saveexec_b64 s[8:9], vcc
	s_cbranch_execz .LBB0_37
	global_load_dword v14, v[16:17], off nt
.LBB0_37:
	s_or_b64 exec, exec, s[8:9]
	v_lshl_add_u64 v[16:17], s[42:43], 2, v[16:17]
	s_and_saveexec_b64 s[8:9], vcc
	s_cbranch_execz .LBB0_39
	global_load_dword v15, v[16:17], off nt
.LBB0_39:
	s_or_b64 exec, exec, s[8:9]
	v_lshl_add_u64 v[18:19], s[42:43], 2, v[16:17]
	v_mov_b32_e32 v17, 0
	v_mov_b32_e32 v16, 0
	s_and_saveexec_b64 s[8:9], vcc
	s_cbranch_execz .LBB0_41
	global_load_dword v16, v[18:19], off nt
.LBB0_41:
	s_or_b64 exec, exec, s[8:9]
	v_lshl_add_u64 v[18:19], s[42:43], 2, v[18:19]
	s_and_saveexec_b64 s[8:9], vcc
	s_cbranch_execz .LBB0_43
	global_load_dword v17, v[18:19], off nt
.LBB0_43:
	s_or_b64 exec, exec, s[8:9]
	v_lshl_add_u64 v[20:21], s[42:43], 2, v[18:19]
	v_mov_b32_e32 v19, 0
	v_mov_b32_e32 v18, 0
	s_and_saveexec_b64 s[8:9], vcc
	s_cbranch_execz .LBB0_45
	global_load_dword v18, v[20:21], off nt
.LBB0_45:
	s_or_b64 exec, exec, s[8:9]
	v_lshl_add_u64 v[20:21], s[42:43], 2, v[20:21]
	s_and_saveexec_b64 s[8:9], vcc
	s_cbranch_execz .LBB0_47
	global_load_dword v19, v[20:21], off nt
.LBB0_47:
	s_or_b64 exec, exec, s[8:9]
	v_lshl_add_u64 v[22:23], s[42:43], 2, v[20:21]
	v_mov_b32_e32 v21, 0
	v_mov_b32_e32 v20, 0
	s_and_saveexec_b64 s[8:9], vcc
	s_cbranch_execz .LBB0_49
	global_load_dword v20, v[22:23], off nt
.LBB0_49:
	s_or_b64 exec, exec, s[8:9]
	v_lshl_add_u64 v[22:23], s[42:43], 2, v[22:23]
	s_and_saveexec_b64 s[8:9], vcc
	s_cbranch_execz .LBB0_51
	global_load_dword v21, v[22:23], off nt
.LBB0_51:
	s_or_b64 exec, exec, s[8:9]
	v_lshl_add_u64 v[22:23], s[42:43], 2, v[22:23]
	v_mov_b32_e32 v25, 0
	v_mov_b32_e32 v24, 0
	s_and_saveexec_b64 s[8:9], vcc
	s_cbranch_execz .LBB0_53
	global_load_dword v24, v[22:23], off nt
.LBB0_53:
	s_or_b64 exec, exec, s[8:9]
	v_lshl_add_u64 v[22:23], s[42:43], 2, v[22:23]
	s_and_saveexec_b64 s[8:9], vcc
	s_cbranch_execz .LBB0_55
	global_load_dword v25, v[22:23], off nt
.LBB0_55:
	s_or_b64 exec, exec, s[8:9]
	v_lshl_add_u64 v[22:23], s[42:43], 2, v[22:23]
	v_mov_b32_e32 v31, 0
	v_mov_b32_e32 v30, 0
	s_and_saveexec_b64 s[8:9], vcc
	s_cbranch_execz .LBB0_57
	global_load_dword v30, v[22:23], off nt
.LBB0_57:
	s_or_b64 exec, exec, s[8:9]
	v_lshl_add_u64 v[22:23], s[42:43], 2, v[22:23]
	s_and_saveexec_b64 s[8:9], vcc
	s_cbranch_execz .LBB0_59
	global_load_dword v31, v[22:23], off nt
.LBB0_59:
	s_or_b64 exec, exec, s[8:9]
	v_lshl_add_u64 v[22:23], s[42:43], 2, v[22:23]
	v_mov_b32_e32 v33, 0
	v_mov_b32_e32 v32, 0
	s_and_saveexec_b64 s[8:9], vcc
	s_cbranch_execz .LBB0_61
	global_load_dword v32, v[22:23], off nt
.LBB0_61:
	s_or_b64 exec, exec, s[8:9]
	v_lshl_add_u64 v[22:23], s[42:43], 2, v[22:23]
	s_and_saveexec_b64 s[8:9], vcc
	s_cbranch_execz .LBB0_63
	global_load_dword v33, v[22:23], off nt
.LBB0_63:
	s_or_b64 exec, exec, s[8:9]
	v_lshl_add_u64 v[22:23], s[42:43], 2, v[22:23]
	v_mov_b32_e32 v39, 0
	v_mov_b32_e32 v38, 0
	s_and_saveexec_b64 s[8:9], vcc
	s_cbranch_execz .LBB0_65
	global_load_dword v38, v[22:23], off nt
.LBB0_65:
	s_or_b64 exec, exec, s[8:9]
	v_lshl_add_u64 v[22:23], s[42:43], 2, v[22:23]
	s_and_saveexec_b64 s[8:9], vcc
	s_cbranch_execz .LBB0_67
	global_load_dword v39, v[22:23], off nt
.LBB0_67:
	s_or_b64 exec, exec, s[8:9]
	v_lshl_add_u64 v[22:23], s[42:43], 2, v[22:23]
	v_mov_b32_e32 v45, 0
	v_mov_b32_e32 v44, 0
	s_and_saveexec_b64 s[8:9], vcc
	s_cbranch_execz .LBB0_69
	global_load_dword v44, v[22:23], off nt
.LBB0_69:
	s_or_b64 exec, exec, s[8:9]
	v_lshl_add_u64 v[22:23], s[42:43], 2, v[22:23]
	s_and_saveexec_b64 s[8:9], vcc
	s_cbranch_execz .LBB0_71
	global_load_dword v45, v[22:23], off nt
.LBB0_71:
	s_or_b64 exec, exec, s[8:9]
	v_lshl_add_u64 v[22:23], s[42:43], 2, v[22:23]
	v_mov_b32_e32 v53, 0
	v_mov_b32_e32 v52, 0
	s_and_saveexec_b64 s[8:9], vcc
	s_cbranch_execz .LBB0_73
	global_load_dword v52, v[22:23], off nt
.LBB0_73:
	s_or_b64 exec, exec, s[8:9]
	v_mov_b32_e32 v56, v53
	v_mov_b32_e32 v57, v53
	s_and_saveexec_b64 s[8:9], vcc
	s_cbranch_execz .LBB0_75
	s_lshl_b64 s[46:47], s[42:43], 2
	v_lshl_add_u64 v[22:23], v[22:23], 0, s[46:47]
	v_lshl_add_u64 v[26:27], v[22:23], 0, s[46:47]
	v_lshl_add_u64 v[28:29], v[26:27], 0, s[46:47]
	global_load_dword v53, v[22:23], off nt
	global_load_dword v56, v[26:27], off nt
	global_load_dword v57, v[28:29], off nt

; __device__ __forceinline__ void tr_load(const TrItem& t, float (&tv)[32], int lane) {
;     const int nn = t.n0 + (lane & 31); const bool ok = nn < t.N;
;     const float* p = t.W + (size_t)(t.k0 + 32 * (lane >> 5)) * t.N + nn; const size_t st = (size_t)t.N;
; #pragma unroll
;     for (int i = 0; i < 32; ++i) { tv[i] = ok ? *p : 0.f; p += st; }
; }
.LBB0_88:
	v_add_u32_e32 v29, s46, v2
	v_add_u32_e32 v34, s71, v1
	v_mad_i64_i32 v[36:37], s[8:9], v29, s52, 0
	v_lshl_add_u64 v[36:37], v[36:37], 2, s[48:49]
	v_ashrrev_i32_e32 v35, 31, v34
	v_cmp_gt_i32_e32 vcc, s52, v34
	v_lshl_add_u64 v[36:37], v[34:35], 2, v[36:37]
	v_mov_b32_e32 v35, 0
	v_mov_b32_e32 v34, 0
	s_and_saveexec_b64 s[8:9], vcc
	s_cbranch_execz .LBB0_90
	global_load_dword v34, v[36:37], off nt
.LBB0_90:
	s_or_b64 exec, exec, s[8:9]
	s_ashr_i32 s53, s52, 31
	v_lshl_add_u64 v[36:37], s[52:53], 2, v[36:37]
	s_and_saveexec_b64 s[8:9], vcc
	s_cbranch_execz .LBB0_92
	global_load_dword v35, v[36:37], off nt
.LBB0_92:
	s_or_b64 exec, exec, s[8:9]
	v_lshl_add_u64 v[40:41], s[52:53], 2, v[36:37]
	v_mov_b32_e32 v37, 0
	v_mov_b32_e32 v36, 0
	s_and_saveexec_b64 s[8:9], vcc
	s_cbranch_execz .LBB0_94
	global_load_dword v36, v[40:41], off nt
.LBB0_94:
	s_or_b64 exec, exec, s[8:9]
	v_lshl_add_u64 v[40:41], s[52:53], 2, v[40:41]
	s_and_saveexec_b64 s[8:9], vcc
	s_cbranch_execz .LBB0_96
	global_load_dword v37, v[40:41], off nt
.LBB0_96:
	s_or_b64 exec, exec, s[8:9]
	v_lshl_add_u64 v[42:43], s[52:53], 2, v[40:41]
	v_mov_b32_e32 v41, 0
	v_mov_b32_e32 v40, 0
	s_and_saveexec_b64 s[8:9], vcc
	s_cbranch_execz .LBB0_98
	global_load_dword v40, v[42:43], off nt
.LBB0_98:
	s_or_b64 exec, exec, s[8:9]
	v_lshl_add_u64 v[42:43], s[52:53], 2, v[42:43]
	s_and_saveexec_b64 s[8:9], vcc
	s_cbranch_execz .LBB0_100
	global_load_dword v41, v[42:43], off nt
.LBB0_100:
	s_or_b64 exec, exec, s[8:9]
	v_lshl_add_u64 v[46:47], s[52:53], 2, v[42:43]
	v_mov_b32_e32 v43, 0
	v_mov_b32_e32 v42, 0
	s_and_saveexec_b64 s[8:9], vcc
	s_cbranch_execz .LBB0_102
	global_load_dword v42, v[46:47], off nt
.LBB0_102:
	s_or_b64 exec, exec, s[8:9]
	v_lshl_add_u64 v[46:47], s[52:53], 2, v[46:47]
	s_and_saveexec_b64 s[8:9], vcc
	s_cbranch_execz .LBB0_104
	global_load_dword v43, v[46:47], off nt
.LBB0_104:
	s_or_b64 exec, exec, s[8:9]
	v_lshl_add_u64 v[48:49], s[52:53], 2, v[46:47]
	v_mov_b32_e32 v47, 0
	v_mov_b32_e32 v46, 0
	s_and_saveexec_b64 s[8:9], vcc
	s_cbranch_execz .LBB0_106
	global_load_dword v46, v[48:49], off nt
.LBB0_106:
	s_or_b64 exec, exec, s[8:9]
	v_lshl_add_u64 v[48:49], s[52:53], 2, v[48:49]
	s_and_saveexec_b64 s[8:9], vcc
	s_cbranch_execz .LBB0_108
	global_load_dword v47, v[48:49], off nt
.LBB0_108:
	s_or_b64 exec, exec, s[8:9]
	v_lshl_add_u64 v[50:51], s[52:53], 2, v[48:49]
	v_mov_b32_e32 v49, 0
	v_mov_b32_e32 v48, 0
	s_and_saveexec_b64 s[8:9], vcc
	s_cbranch_execz .LBB0_110
	global_load_dword v48, v[50:51], off nt
.LBB0_110:
	s_or_b64 exec, exec, s[8:9]
	v_lshl_add_u64 v[50:51], s[52:53], 2, v[50:51]
	s_and_saveexec_b64 s[8:9], vcc
	s_cbranch_execz .LBB0_112
	global_load_dword v49, v[50:51], off nt
.LBB0_112:
	s_or_b64 exec, exec, s[8:9]
	v_lshl_add_u64 v[54:55], s[52:53], 2, v[50:51]
	v_mov_b32_e32 v51, 0
	v_mov_b32_e32 v50, 0
	s_and_saveexec_b64 s[8:9], vcc
	s_cbranch_execz .LBB0_114
	global_load_dword v50, v[54:55], off nt
.LBB0_114:
	s_or_b64 exec, exec, s[8:9]
	v_lshl_add_u64 v[54:55], s[52:53], 2, v[54:55]
	s_and_saveexec_b64 s[8:9], vcc
	s_cbranch_execz .LBB0_116
	global_load_dword v51, v[54:55], off nt
.LBB0_116:
	s_or_b64 exec, exec, s[8:9]
	v_lshl_add_u64 v[58:59], s[52:53], 2, v[54:55]
	v_mov_b32_e32 v55, 0
	v_mov_b32_e32 v54, 0
	s_and_saveexec_b64 s[8:9], vcc
	s_cbranch_execz .LBB0_118
	global_load_dword v54, v[58:59], off nt
.LBB0_118:
	s_or_b64 exec, exec, s[8:9]
	v_lshl_add_u64 v[58:59], s[52:53], 2, v[58:59]
	s_and_saveexec_b64 s[8:9], vcc
	s_cbranch_execz .LBB0_120
	global_load_dword v55, v[58:59], off nt
.LBB0_120:
	s_or_b64 exec, exec, s[8:9]
	v_lshl_add_u64 v[60:61], s[52:53], 2, v[58:59]
	v_mov_b32_e32 v59, 0
	v_mov_b32_e32 v58, 0
	s_and_saveexec_b64 s[8:9], vcc
	s_cbranch_execz .LBB0_122
	global_load_dword v58, v[60:61], off nt
.LBB0_122:
	s_or_b64 exec, exec, s[8:9]
	v_lshl_add_u64 v[60:61], s[52:53], 2, v[60:61]
	s_and_saveexec_b64 s[8:9], vcc
	s_cbranch_execz .LBB0_124
	global_load_dword v59, v[60:61], off nt
.LBB0_124:
	s_or_b64 exec, exec, s[8:9]
	v_lshl_add_u64 v[62:63], s[52:53], 2, v[60:61]
	v_mov_b32_e32 v61, 0
	v_mov_b32_e32 v60, 0
	s_and_saveexec_b64 s[8:9], vcc
	s_cbranch_execz .LBB0_126
	global_load_dword v60, v[62:63], off nt
.LBB0_126:
	s_or_b64 exec, exec, s[8:9]
	v_lshl_add_u64 v[62:63], s[52:53], 2, v[62:63]
	s_and_saveexec_b64 s[8:9], vcc
	s_cbranch_execz .LBB0_128
	global_load_dword v61, v[62:63], off nt
.LBB0_128:
	s_or_b64 exec, exec, s[8:9]
	v_lshl_add_u64 v[64:65], s[52:53], 2, v[62:63]
	v_mov_b32_e32 v63, 0
	v_mov_b32_e32 v62, 0
	s_and_saveexec_b64 s[8:9], vcc
	s_cbranch_execz .LBB0_130
	global_load_dword v62, v[64:65], off nt
.LBB0_130:
	s_or_b64 exec, exec, s[8:9]
	v_lshl_add_u64 v[64:65], s[52:53], 2, v[64:65]
	s_and_saveexec_b64 s[8:9], vcc
	s_cbranch_execz .LBB0_132
	global_load_dword v63, v[64:65], off nt
.LBB0_132:
	s_or_b64 exec, exec, s[8:9]
	v_lshl_add_u64 v[66:67], s[52:53], 2, v[64:65]
	v_mov_b32_e32 v65, 0
	v_mov_b32_e32 v64, 0
	s_and_saveexec_b64 s[8:9], vcc
	s_cbranch_execz .LBB0_134
	global_load_dword v64, v[66:67], off nt
.LBB0_134:
	s_or_b64 exec, exec, s[8:9]
	v_lshl_add_u64 v[66:67], s[52:53], 2, v[66:67]
	s_and_saveexec_b64 s[8:9], vcc
	s_cbranch_execz .LBB0_136
	global_load_dword v65, v[66:67], off nt
.LBB0_136:
	s_or_b64 exec, exec, s[8:9]
	v_lshl_add_u64 v[68:69], s[52:53], 2, v[66:67]
	v_mov_b32_e32 v67, 0
	v_mov_b32_e32 v66, 0
	s_and_saveexec_b64 s[8:9], vcc
	s_cbranch_execz .LBB0_138
	global_load_dword v66, v[68:69], off nt
.LBB0_138:
	s_or_b64 exec, exec, s[8:9]
	v_lshl_add_u64 v[68:69], s[52:53], 2, v[68:69]
	s_and_saveexec_b64 s[8:9], vcc
	s_cbranch_execz .LBB0_140
	global_load_dword v67, v[68:69], off nt
.LBB0_140:
	s_or_b64 exec, exec, s[8:9]
	v_lshl_add_u64 v[70:71], s[52:53], 2, v[68:69]
	v_mov_b32_e32 v69, 0
	v_mov_b32_e32 v68, 0
	s_and_saveexec_b64 s[8:9], vcc
	s_cbranch_execz .LBB0_142
	global_load_dword v68, v[70:71], off nt
.LBB0_142:
	s_or_b64 exec, exec, s[8:9]
	v_lshl_add_u64 v[70:71], s[52:53], 2, v[70:71]
	s_and_saveexec_b64 s[8:9], vcc
	s_cbranch_execz .LBB0_144
	global_load_dword v69, v[70:71], off nt
.LBB0_144:
	s_or_b64 exec, exec, s[8:9]
	v_lshl_add_u64 v[74:75], s[52:53], 2, v[70:71]
	v_mov_b32_e32 v71, 0
	v_mov_b32_e32 v70, 0
	s_and_saveexec_b64 s[8:9], vcc
	s_cbranch_execz .LBB0_146
	global_load_dword v70, v[74:75], off nt
.LBB0_146:
	s_or_b64 exec, exec, s[8:9]
	v_mov_b32_e32 v73, 0
	v_mov_b32_e32 v72, 0
	s_and_saveexec_b64 s[8:9], vcc
	s_cbranch_execz .LBB0_148
	s_lshl_b64 s[64:65], s[52:53], 2
	v_lshl_add_u64 v[72:73], v[74:75], 0, s[64:65]
	v_lshl_add_u64 v[74:75], v[72:73], 0, s[64:65]
	v_lshl_add_u64 v[76:77], v[74:75], 0, s[64:65]
	global_load_dword v71, v[72:73], off nt
	s_nop 0
	global_load_dword v72, v[74:75], off nt
	global_load_dword v73, v[76:77], off nt

; __device__ __forceinline__ void tr_load(const TrItem& t, float (&tv)[32], int lane) {
;     const int nn = t.n0 + (lane & 31); const bool ok = nn < t.N;
;     const float* p = t.W + (size_t)(t.k0 + 32 * (lane >> 5)) * t.N + nn; const size_t st = (size_t)t.N;
; #pragma unroll
;     for (int i = 0; i < 32; ++i) { tv[i] = ok ? *p : 0.f; p += st; }
; }
.LBB0_191:
	v_add_u32_e32 v5, s36, v2
	v_add_u32_e32 v4, s5, v1
	v_mad_i64_i32 v[6:7], s[6:7], v5, s42, 0
	v_lshl_add_u64 v[6:7], v[6:7], 2, s[38:39]
	v_ashrrev_i32_e32 v5, 31, v4
	v_cmp_gt_i32_e32 vcc, s42, v4
	v_lshl_add_u64 v[6:7], v[4:5], 2, v[6:7]
	v_mov_b32_e32 v5, 0
	v_mov_b32_e32 v4, 0
	s_and_saveexec_b64 s[6:7], vcc
	s_cbranch_execz .LBB0_193
	global_load_dword v4, v[6:7], off nt
.LBB0_193:
	s_or_b64 exec, exec, s[6:7]
	s_ashr_i32 s43, s42, 31
	v_lshl_add_u64 v[6:7], s[42:43], 2, v[6:7]
	s_and_saveexec_b64 s[6:7], vcc
	s_cbranch_execz .LBB0_195
	global_load_dword v5, v[6:7], off nt
.LBB0_195:
	s_or_b64 exec, exec, s[6:7]
	v_lshl_add_u64 v[8:9], s[42:43], 2, v[6:7]
	v_mov_b32_e32 v7, 0
	v_mov_b32_e32 v6, 0
	s_and_saveexec_b64 s[6:7], vcc
	s_cbranch_execz .LBB0_197
	global_load_dword v6, v[8:9], off nt
.LBB0_197:
	s_or_b64 exec, exec, s[6:7]
	v_lshl_add_u64 v[8:9], s[42:43], 2, v[8:9]
	s_and_saveexec_b64 s[6:7], vcc
	s_cbranch_execz .LBB0_199
	global_load_dword v7, v[8:9], off nt
.LBB0_199:
	s_or_b64 exec, exec, s[6:7]
	v_lshl_add_u64 v[10:11], s[42:43], 2, v[8:9]
	v_mov_b32_e32 v9, 0
	v_mov_b32_e32 v8, 0
	s_and_saveexec_b64 s[6:7], vcc
	s_cbranch_execz .LBB0_201
	global_load_dword v8, v[10:11], off nt
.LBB0_201:
	s_or_b64 exec, exec, s[6:7]
	v_lshl_add_u64 v[10:11], s[42:43], 2, v[10:11]
	s_and_saveexec_b64 s[6:7], vcc
	s_cbranch_execz .LBB0_203
	global_load_dword v9, v[10:11], off nt
.LBB0_203:
	s_or_b64 exec, exec, s[6:7]
	v_lshl_add_u64 v[12:13], s[42:43], 2, v[10:11]
	v_mov_b32_e32 v11, 0
	v_mov_b32_e32 v10, 0
	s_and_saveexec_b64 s[6:7], vcc
	s_cbranch_execz .LBB0_205
	global_load_dword v10, v[12:13], off nt
.LBB0_205:
	s_or_b64 exec, exec, s[6:7]
	v_lshl_add_u64 v[12:13], s[42:43], 2, v[12:13]
	s_and_saveexec_b64 s[6:7], vcc
	s_cbranch_execz .LBB0_207
	global_load_dword v11, v[12:13], off nt
.LBB0_207:
	s_or_b64 exec, exec, s[6:7]
	v_lshl_add_u64 v[14:15], s[42:43], 2, v[12:13]
	v_mov_b32_e32 v13, 0
	v_mov_b32_e32 v12, 0
	s_and_saveexec_b64 s[6:7], vcc
	s_cbranch_execz .LBB0_209
	global_load_dword v12, v[14:15], off nt
.LBB0_209:
	s_or_b64 exec, exec, s[6:7]
	v_lshl_add_u64 v[14:15], s[42:43], 2, v[14:15]
	s_and_saveexec_b64 s[6:7], vcc
	s_cbranch_execz .LBB0_211
	global_load_dword v13, v[14:15], off nt
.LBB0_211:
	s_or_b64 exec, exec, s[6:7]
	v_lshl_add_u64 v[16:17], s[42:43], 2, v[14:15]
	v_mov_b32_e32 v15, 0
	v_mov_b32_e32 v14, 0
	s_and_saveexec_b64 s[6:7], vcc
	s_cbranch_execz .LBB0_213
	global_load_dword v14, v[16:17], off nt
.LBB0_213:
	s_or_b64 exec, exec, s[6:7]
	v_lshl_add_u64 v[16:17], s[42:43], 2, v[16:17]
	s_and_saveexec_b64 s[6:7], vcc
	s_cbranch_execz .LBB0_215
	global_load_dword v15, v[16:17], off nt
.LBB0_215:
	s_or_b64 exec, exec, s[6:7]
	v_lshl_add_u64 v[18:19], s[42:43], 2, v[16:17]
	v_mov_b32_e32 v17, 0
	v_mov_b32_e32 v16, 0
	s_and_saveexec_b64 s[6:7], vcc
	s_cbranch_execz .LBB0_217
	global_load_dword v16, v[18:19], off nt
.LBB0_217:
	s_or_b64 exec, exec, s[6:7]
	v_lshl_add_u64 v[18:19], s[42:43], 2, v[18:19]
	s_and_saveexec_b64 s[6:7], vcc
	s_cbranch_execz .LBB0_219
	global_load_dword v17, v[18:19], off nt
.LBB0_219:
	s_or_b64 exec, exec, s[6:7]
	v_lshl_add_u64 v[20:21], s[42:43], 2, v[18:19]
	v_mov_b32_e32 v19, 0
	v_mov_b32_e32 v18, 0
	s_and_saveexec_b64 s[6:7], vcc
	s_cbranch_execz .LBB0_221
	global_load_dword v18, v[20:21], off nt
.LBB0_221:
	s_or_b64 exec, exec, s[6:7]
	v_lshl_add_u64 v[20:21], s[42:43], 2, v[20:21]
	s_and_saveexec_b64 s[6:7], vcc
	s_cbranch_execz .LBB0_223
	global_load_dword v19, v[20:21], off nt
.LBB0_223:
	s_or_b64 exec, exec, s[6:7]
	v_lshl_add_u64 v[24:25], s[42:43], 2, v[20:21]
	v_mov_b32_e32 v21, 0
	v_mov_b32_e32 v20, 0
	s_and_saveexec_b64 s[6:7], vcc
	s_cbranch_execz .LBB0_225
	global_load_dword v20, v[24:25], off nt
.LBB0_225:
	s_or_b64 exec, exec, s[6:7]
	v_lshl_add_u64 v[24:25], s[42:43], 2, v[24:25]
	s_and_saveexec_b64 s[6:7], vcc
	s_cbranch_execz .LBB0_227
	global_load_dword v21, v[24:25], off nt
.LBB0_227:
	s_or_b64 exec, exec, s[6:7]
	v_lshl_add_u64 v[30:31], s[42:43], 2, v[24:25]
	v_mov_b32_e32 v25, 0
	v_mov_b32_e32 v24, 0
	s_and_saveexec_b64 s[6:7], vcc
	s_cbranch_execz .LBB0_229
	global_load_dword v24, v[30:31], off nt
.LBB0_229:
	s_or_b64 exec, exec, s[6:7]
	v_lshl_add_u64 v[30:31], s[42:43], 2, v[30:31]
	s_and_saveexec_b64 s[6:7], vcc
	s_cbranch_execz .LBB0_231
	global_load_dword v25, v[30:31], off nt
.LBB0_231:
	s_or_b64 exec, exec, s[6:7]
	v_lshl_add_u64 v[32:33], s[42:43], 2, v[30:31]
	v_mov_b32_e32 v31, 0
	v_mov_b32_e32 v30, 0
	s_and_saveexec_b64 s[6:7], vcc
	s_cbranch_execz .LBB0_233
	global_load_dword v30, v[32:33], off nt
.LBB0_233:
	s_or_b64 exec, exec, s[6:7]
	v_lshl_add_u64 v[32:33], s[42:43], 2, v[32:33]
	s_and_saveexec_b64 s[6:7], vcc
	s_cbranch_execz .LBB0_235
	global_load_dword v31, v[32:33], off nt
.LBB0_235:
	s_or_b64 exec, exec, s[6:7]
	v_lshl_add_u64 v[38:39], s[42:43], 2, v[32:33]
	v_mov_b32_e32 v33, 0
	v_mov_b32_e32 v32, 0
	s_and_saveexec_b64 s[6:7], vcc
	s_cbranch_execz .LBB0_237
	global_load_dword v32, v[38:39], off nt
.LBB0_237:
	s_or_b64 exec, exec, s[6:7]
	v_lshl_add_u64 v[38:39], s[42:43], 2, v[38:39]
	s_and_saveexec_b64 s[6:7], vcc
	s_cbranch_execz .LBB0_239
	global_load_dword v33, v[38:39], off nt
.LBB0_239:
	s_or_b64 exec, exec, s[6:7]
	v_lshl_add_u64 v[44:45], s[42:43], 2, v[38:39]
	v_mov_b32_e32 v39, 0
	v_mov_b32_e32 v38, 0
	s_and_saveexec_b64 s[6:7], vcc
	s_cbranch_execz .LBB0_241
	global_load_dword v38, v[44:45], off nt
.LBB0_241:
	s_or_b64 exec, exec, s[6:7]
	v_lshl_add_u64 v[44:45], s[42:43], 2, v[44:45]
	s_and_saveexec_b64 s[6:7], vcc
	s_cbranch_execz .LBB0_243
	global_load_dword v39, v[44:45], off nt
.LBB0_243:
	s_or_b64 exec, exec, s[6:7]
	v_lshl_add_u64 v[52:53], s[42:43], 2, v[44:45]
	v_mov_b32_e32 v45, 0
	v_mov_b32_e32 v44, 0
	s_and_saveexec_b64 s[6:7], vcc
	s_cbranch_execz .LBB0_245
	global_load_dword v44, v[52:53], off nt
.LBB0_245:
	s_or_b64 exec, exec, s[6:7]
	v_lshl_add_u64 v[52:53], s[42:43], 2, v[52:53]
	s_and_saveexec_b64 s[6:7], vcc
	s_cbranch_execz .LBB0_247
	global_load_dword v45, v[52:53], off nt
.LBB0_247:
	s_or_b64 exec, exec, s[6:7]
	v_lshl_add_u64 v[74:75], s[42:43], 2, v[52:53]
	v_mov_b32_e32 v52, 0
	s_and_saveexec_b64 s[6:7], vcc
	s_cbranch_execz .LBB0_249
	global_load_dword v52, v[74:75], off nt

; #define GAS __attribute__((address_space(1)))
; __global__ void __launch_bounds__(NTHR, 2) fwd_kernel(Args args) {
;     ...
;                 for (int u = 0; u < 16; u += 2) { f32x4 a[2][4], c[2][4]; int isv[2], b[2], j0[2]; bool ok[2];
; #pragma unroll
;                     for (int w2 = 0; w2 < 2; ++w2) { const int it = cbase + wave * 16 + u + w2; ok[w2] = it < NCI; isv[w2] = it >= 16 * (SKS / 4); const int r = isv[w2] ? it - 16 * (SKS / 4) : it; b[w2] = r / (SKS / 4); j0[w2] = 4 * (r % (SKS / 4));
;                         if (j0[w2] >= PAST && j0[w2] < PAST + 16) ok[w2] = false;
; #pragma unroll
;                         for (int e = 0; e < 4; ++e) if (ok[w2] && j0[w2] < PAST) { const float* src = (isv[w2] ? cache_v : cache_k) + (size_t)(b[w2] * PAST + j0[w2] + e) * 512 + lane * 8; a[w2][e] = *(const GAS f32x4*)src; c[w2][e] = *(const GAS f32x4*)(src + 4); } }
.LBB0_617:
	s_add_i32 s35, s5, s34
	s_cmpk_lt_i32 s35, 0x4200
	s_cselect_b64 s[10:11], -1, 0
	s_add_i32 s36, s35, 0xffffdf00
	s_cmpk_gt_i32 s35, 0x20ff
	s_cselect_b64 s[12:13], -1, 0
	s_and_b64 s[24:25], s[12:13], exec
	s_cselect_b32 s24, s36, s35
	s_mul_hi_i32 s25, s24, 0x3e0f83e1
	s_cselect_b32 s36, s30, s28
	s_cselect_b32 s37, s31, s29
	s_lshr_b32 s38, s25, 31
	s_ashr_i32 s46, s25, 7
	s_add_i32 s46, s46, s38
	s_mul_i32 s25, s46, 0x210
	s_sub_i32 s47, s24, s25
	s_lshl_b32 s43, s47, 2
	s_and_b32 s24, s47, -4
	s_cmpk_lg_i32 s24, 0x200
	s_cselect_b64 s[24:25], -1, 0
	s_and_b64 s[38:39], s[24:25], s[10:11]
	s_cmpk_lt_i32 s47, 0x200
	s_cselect_b64 s[10:11], -1, 0
	s_and_b64 s[40:41], s[10:11], s[38:39]
	s_lshl_b32 s24, s46, 11
	v_lshlrev_b32_e32 v72, 2, v70
	v_cndmask_b32_e64 v66, 0, 1, s[40:41]
	s_add_i32 s24, s24, s43
	v_cmp_ne_u32_e64 s[10:11], 1, v66
	s_andn2_b64 vcc, exec, s[40:41]
	v_lshl_add_u64 v[66:67], s[36:37], 0, v[72:73]
	s_cbranch_vccnz .LBB0_621
	s_ashr_i32 s25, s24, 31
	s_lshl_b64 s[36:37], s[24:25], 11
	s_waitcnt vmcnt(0)
	v_lshl_add_u64 v[34:35], v[66:67], 0, s[36:37]
	global_load_dwordx4 v[2:5], v[34:35], off offset:16 nt
	s_nop 0
	global_load_dwordx4 v[34:37], v[34:35], off nt
	s_and_b64 vcc, exec, s[10:11]
	s_cbranch_vccz .LBB0_622

; #define GAS __attribute__((address_space(1)))
; __global__ void __launch_bounds__(NTHR, 2) fwd_kernel(Args args) {
;     ...
;                 for (int u = 0; u < 16; u += 2) { f32x4 a[2][4], c[2][4]; int isv[2], b[2], j0[2]; bool ok[2];
; #pragma unroll
;                     for (int w2 = 0; w2 < 2; ++w2) { const int it = cbase + wave * 16 + u + w2; ok[w2] = it < NCI; isv[w2] = it >= 16 * (SKS / 4); const int r = isv[w2] ? it - 16 * (SKS / 4) : it; b[w2] = r / (SKS / 4); j0[w2] = 4 * (r % (SKS / 4));
;                         if (j0[w2] >= PAST && j0[w2] < PAST + 16) ok[w2] = false;
; #pragma unroll
;                         for (int e = 0; e < 4; ++e) if (ok[w2] && j0[w2] < PAST) { const float* src = (isv[w2] ? cache_v : cache_k) + (size_t)(b[w2] * PAST + j0[w2] + e) * 512 + lane * 8; a[w2][e] = *(const GAS f32x4*)src; c[w2][e] = *(const GAS f32x4*)(src + 4); } }
.LBB0_620:
	s_or_b32 s36, s24, 2
	s_ashr_i32 s37, s36, 31
	s_lshl_b64 s[36:37], s[36:37], 11
	s_waitcnt vmcnt(0)
	v_lshl_add_u64 v[42:43], v[66:67], 0, s[36:37]
	global_load_dwordx4 v[10:13], v[42:43], off offset:16 nt
	s_nop 0
	global_load_dwordx4 v[42:45], v[42:43], off nt
	s_and_b64 vcc, exec, s[10:11]
	s_cbranch_vccz .LBB0_624
	s_branch .LBB0_625

; #define GAS __attribute__((address_space(1)))
; __global__ void __launch_bounds__(NTHR, 2) fwd_kernel(Args args) {
;     ...
;                 for (int u = 0; u < 16; u += 2) { f32x4 a[2][4], c[2][4]; int isv[2], b[2], j0[2]; bool ok[2];
; #pragma unroll
;                     for (int w2 = 0; w2 < 2; ++w2) { const int it = cbase + wave * 16 + u + w2; ok[w2] = it < NCI; isv[w2] = it >= 16 * (SKS / 4); const int r = isv[w2] ? it - 16 * (SKS / 4) : it; b[w2] = r / (SKS / 4); j0[w2] = 4 * (r % (SKS / 4));
;                         if (j0[w2] >= PAST && j0[w2] < PAST + 16) ok[w2] = false;
; #pragma unroll
;                         for (int e = 0; e < 4; ++e) if (ok[w2] && j0[w2] < PAST) { const float* src = (isv[w2] ? cache_v : cache_k) + (size_t)(b[w2] * PAST + j0[w2] + e) * 512 + lane * 8; a[w2][e] = *(const GAS f32x4*)src; c[w2][e] = *(const GAS f32x4*)(src + 4); } }
.LBB0_622:
	s_or_b32 s36, s24, 1
	s_ashr_i32 s37, s36, 31
	s_lshl_b64 s[36:37], s[36:37], 11
	s_waitcnt vmcnt(0)
	v_lshl_add_u64 v[38:39], v[66:67], 0, s[36:37]
	global_load_dwordx4 v[6:9], v[38:39], off offset:16 nt
	s_nop 0
	global_load_dwordx4 v[38:41], v[38:39], off nt
	s_and_b64 vcc, exec, s[10:11]
	s_cbranch_vccz .LBB0_620

; #define GAS __attribute__((address_space(1)))
; __global__ void __launch_bounds__(NTHR, 2) fwd_kernel(Args args) {
;     ...
;                 for (int u = 0; u < 16; u += 2) { f32x4 a[2][4], c[2][4]; int isv[2], b[2], j0[2]; bool ok[2];
; #pragma unroll
;                     for (int w2 = 0; w2 < 2; ++w2) { const int it = cbase + wave * 16 + u + w2; ok[w2] = it < NCI; isv[w2] = it >= 16 * (SKS / 4); const int r = isv[w2] ? it - 16 * (SKS / 4) : it; b[w2] = r / (SKS / 4); j0[w2] = 4 * (r % (SKS / 4));
;                         if (j0[w2] >= PAST && j0[w2] < PAST + 16) ok[w2] = false;
; #pragma unroll
;                         for (int e = 0; e < 4; ++e) if (ok[w2] && j0[w2] < PAST) { const float* src = (isv[w2] ? cache_v : cache_k) + (size_t)(b[w2] * PAST + j0[w2] + e) * 512 + lane * 8; a[w2][e] = *(const GAS f32x4*)src; c[w2][e] = *(const GAS f32x4*)(src + 4); } }
.LBB0_624:
	s_or_b32 s10, s24, 3
	s_ashr_i32 s11, s10, 31
	s_lshl_b64 s[10:11], s[10:11], 11
	s_waitcnt vmcnt(0)
	v_lshl_add_u64 v[46:47], v[66:67], 0, s[10:11]
	global_load_dwordx4 v[14:17], v[46:47], off offset:16 nt
	s_nop 0
	global_load_dwordx4 v[46:49], v[46:47], off nt
.LBB0_625:
	s_cmpk_lt_i32 s35, 0x41ff
	s_cselect_b64 s[10:11], -1, 0
	s_cmpk_gt_i32 s35, 0x20fe
	s_cselect_b64 s[24:25], -1, 0
	s_and_b64 s[36:37], s[24:25], exec
	s_cselect_b32 s35, 0xffffdf01, 1
	s_cselect_b32 s49, s31, s29
	s_cselect_b32 s48, s30, s28
	s_add_i32 s35, s5, s35
	s_add_i32 s35, s35, s34
	s_mul_hi_i32 s36, s35, 0x3e0f83e1
	s_lshr_b32 s37, s36, 31
	s_ashr_i32 s44, s36, 7
	s_add_i32 s44, s44, s37
	s_mul_i32 s36, s44, 0x210
	s_sub_i32 s45, s35, s36
	s_lshl_b32 s35, s45, 2
	s_and_b32 s36, s45, -4
	s_cmpk_lg_i32 s36, 0x200
	s_cselect_b64 s[36:37], -1, 0
	s_and_b64 s[36:37], s[36:37], s[10:11]
	s_cmpk_lt_i32 s45, 0x200
	s_cselect_b64 s[10:11], -1, 0
	s_and_b64 s[52:53], s[10:11], s[36:37]
	s_lshl_b32 s40, s44, 11
	v_cndmask_b32_e64 v66, 0, 1, s[52:53]
	s_add_i32 s40, s40, s35
	v_cmp_ne_u32_e64 s[10:11], 1, v66
	s_andn2_b64 vcc, exec, s[52:53]
	v_lshl_add_u64 v[66:67], s[48:49], 0, v[72:73]
	s_cbranch_vccnz .LBB0_648
	s_ashr_i32 s41, s40, 31
	s_lshl_b64 s[48:49], s[40:41], 11
	s_waitcnt vmcnt(0)
	v_lshl_add_u64 v[50:51], v[66:67], 0, s[48:49]
	global_load_dwordx4 v[18:21], v[50:51], off offset:16 nt
	s_nop 0
	global_load_dwordx4 v[50:53], v[50:51], off nt
	s_and_b64 vcc, exec, s[10:11]
	s_cbranch_vccz .LBB0_649

; #define GAS __attribute__((address_space(1)))
; __global__ void __launch_bounds__(NTHR, 2) fwd_kernel(Args args) {
;     ...
;                 for (int u = 0; u < 16; u += 2) { f32x4 a[2][4], c[2][4]; int isv[2], b[2], j0[2]; bool ok[2];
; #pragma unroll
;                     for (int w2 = 0; w2 < 2; ++w2) { const int it = cbase + wave * 16 + u + w2; ok[w2] = it < NCI; isv[w2] = it >= 16 * (SKS / 4); const int r = isv[w2] ? it - 16 * (SKS / 4) : it; b[w2] = r / (SKS / 4); j0[w2] = 4 * (r % (SKS / 4));
;                         if (j0[w2] >= PAST && j0[w2] < PAST + 16) ok[w2] = false;
; #pragma unroll
;                         for (int e = 0; e < 4; ++e) if (ok[w2] && j0[w2] < PAST) { const float* src = (isv[w2] ? cache_v : cache_k) + (size_t)(b[w2] * PAST + j0[w2] + e) * 512 + lane * 8; a[w2][e] = *(const GAS f32x4*)src; c[w2][e] = *(const GAS f32x4*)(src + 4); } }
.LBB0_628:
	s_or_b32 s48, s40, 2
	s_ashr_i32 s49, s48, 31
	s_lshl_b64 s[48:49], s[48:49], 11
	s_waitcnt vmcnt(0)
	v_lshl_add_u64 v[58:59], v[66:67], 0, s[48:49]
	global_load_dwordx4 v[26:29], v[58:59], off offset:16 nt
	s_nop 0
	global_load_dwordx4 v[58:61], v[58:59], off nt
	s_and_b64 vcc, exec, s[10:11]
	s_cbranch_vccz .LBB0_651

; #define GAS __attribute__((address_space(1)))
; __global__ void __launch_bounds__(NTHR, 2) fwd_kernel(Args args) {
;     ...
;                 for (int u = 0; u < 16; u += 2) { f32x4 a[2][4], c[2][4]; int isv[2], b[2], j0[2]; bool ok[2];
; #pragma unroll
;                     for (int w2 = 0; w2 < 2; ++w2) { const int it = cbase + wave * 16 + u + w2; ok[w2] = it < NCI; isv[w2] = it >= 16 * (SKS / 4); const int r = isv[w2] ? it - 16 * (SKS / 4) : it; b[w2] = r / (SKS / 4); j0[w2] = 4 * (r % (SKS / 4));
;                         if (j0[w2] >= PAST && j0[w2] < PAST + 16) ok[w2] = false;
; #pragma unroll
;                         for (int e = 0; e < 4; ++e) if (ok[w2] && j0[w2] < PAST) { const float* src = (isv[w2] ? cache_v : cache_k) + (size_t)(b[w2] * PAST + j0[w2] + e) * 512 + lane * 8; a[w2][e] = *(const GAS f32x4*)src; c[w2][e] = *(const GAS f32x4*)(src + 4); } }
.LBB0_649:
	s_or_b32 s48, s40, 1
	s_ashr_i32 s49, s48, 31
	s_lshl_b64 s[48:49], s[48:49], 11
	s_waitcnt vmcnt(0)
	v_lshl_add_u64 v[54:55], v[66:67], 0, s[48:49]
	global_load_dwordx4 v[22:25], v[54:55], off offset:16 nt
	s_nop 0
	global_load_dwordx4 v[54:57], v[54:55], off nt
	s_and_b64 vcc, exec, s[10:11]
	s_cbranch_vccz .LBB0_628

; #define GAS __attribute__((address_space(1)))
; __global__ void __launch_bounds__(NTHR, 2) fwd_kernel(Args args) {
;     ...
;                 for (int u = 0; u < 16; u += 2) { f32x4 a[2][4], c[2][4]; int isv[2], b[2], j0[2]; bool ok[2];
; #pragma unroll
;                     for (int w2 = 0; w2 < 2; ++w2) { const int it = cbase + wave * 16 + u + w2; ok[w2] = it < NCI; isv[w2] = it >= 16 * (SKS / 4); const int r = isv[w2] ? it - 16 * (SKS / 4) : it; b[w2] = r / (SKS / 4); j0[w2] = 4 * (r % (SKS / 4));
;                         if (j0[w2] >= PAST && j0[w2] < PAST + 16) ok[w2] = false;
; #pragma unroll
;                         for (int e = 0; e < 4; ++e) if (ok[w2] && j0[w2] < PAST) { const float* src = (isv[w2] ? cache_v : cache_k) + (size_t)(b[w2] * PAST + j0[w2] + e) * 512 + lane * 8; a[w2][e] = *(const GAS f32x4*)src; c[w2][e] = *(const GAS f32x4*)(src + 4); } }
.LBB0_651:
	s_or_b32 s10, s40, 3
	s_ashr_i32 s11, s10, 31
	s_lshl_b64 s[10:11], s[10:11], 11
	s_waitcnt vmcnt(0)
	v_lshl_add_u64 v[62:63], v[66:67], 0, s[10:11]
	global_load_dwordx4 v[30:33], v[62:63], off offset:16 nt
	s_nop 0
	global_load_dwordx4 v[62:65], v[62:63], off nt
	s_andn2_b64 vcc, exec, s[38:39]
	s_cbranch_vccz .LBB0_630

; __device__ __forceinline__ void tr_load(const TrItem& t, float (&tv)[32], int lane) {
;     const int nn = t.n0 + (lane & 31); const bool ok = nn < t.N;
;     const float* p = t.W + (size_t)(t.k0 + 32 * (lane >> 5)) * t.N + nn; const size_t st = (size_t)t.N;
; #pragma unroll
;     for (int i = 0; i < 32; ++i) { tv[i] = ok ? *p : 0.f; p += st; }
; }
.LBB0_691:
	s_waitcnt vmcnt(1)
	v_cndmask_b32_e64 v2, 0, 1, s[8:9]
	v_and_b32_e32 v1, 31, v71
	v_and_b32_e32 v74, 32, v71
	v_cmp_ne_u32_e64 s[6:7], 1, v2
	s_andn2_b64 vcc, exec, s[8:9]
	v_mov_b32_e32 v2, 0
	s_cbranch_vccnz .LBB0_753
	v_add_u32_e32 v3, s26, v74
	v_add_u32_e32 v4, s5, v1
	v_mad_i64_i32 v[6:7], s[34:35], v3, s28, 0
	v_lshl_add_u64 v[6:7], v[6:7], 2, s[18:19]
	v_ashrrev_i32_e32 v5, 31, v4
	v_cmp_le_i32_e32 vcc, s28, v4
	v_cmp_gt_i32_e64 s[8:9], s28, v4
	s_ashr_i32 s29, s28, 31
	v_lshl_add_u64 v[4:5], v[4:5], 2, v[6:7]
	s_and_saveexec_b64 s[34:35], s[8:9]
	s_cbranch_execz .LBB0_694
	global_load_dword v2, v[4:5], off nt
.LBB0_694:
	s_or_b64 exec, exec, s[34:35]
	v_lshl_add_u64 v[6:7], s[28:29], 2, v[4:5]
	v_mov_b32_e32 v4, 0
	v_mov_b32_e32 v3, 0
	s_and_saveexec_b64 s[34:35], s[8:9]
	s_cbranch_execz .LBB0_696
	global_load_dword v3, v[6:7], off nt
.LBB0_696:
	s_or_b64 exec, exec, s[34:35]
	v_lshl_add_u64 v[6:7], s[28:29], 2, v[6:7]
	s_and_saveexec_b64 s[34:35], s[8:9]
	s_cbranch_execz .LBB0_698
	global_load_dword v4, v[6:7], off nt
.LBB0_698:
	s_or_b64 exec, exec, s[34:35]
	v_lshl_add_u64 v[8:9], s[28:29], 2, v[6:7]
	v_mov_b32_e32 v6, 0
	v_mov_b32_e32 v5, 0
	s_and_saveexec_b64 s[34:35], s[8:9]
	s_cbranch_execz .LBB0_700
	global_load_dword v5, v[8:9], off nt
.LBB0_700:
	s_or_b64 exec, exec, s[34:35]
	v_lshl_add_u64 v[8:9], s[28:29], 2, v[8:9]
	s_and_saveexec_b64 s[34:35], s[8:9]
	s_cbranch_execz .LBB0_702
	global_load_dword v6, v[8:9], off nt
.LBB0_702:
	s_or_b64 exec, exec, s[34:35]
	v_lshl_add_u64 v[10:11], s[28:29], 2, v[8:9]
	v_mov_b32_e32 v8, 0
	v_mov_b32_e32 v7, 0
	s_and_saveexec_b64 s[34:35], s[8:9]
	s_cbranch_execz .LBB0_704
	global_load_dword v7, v[10:11], off nt
.LBB0_704:
	s_or_b64 exec, exec, s[34:35]
	v_lshl_add_u64 v[10:11], s[28:29], 2, v[10:11]
	s_and_saveexec_b64 s[34:35], s[8:9]
	s_cbranch_execz .LBB0_706
	global_load_dword v8, v[10:11], off nt
.LBB0_706:
	s_or_b64 exec, exec, s[34:35]
	v_lshl_add_u64 v[12:13], s[28:29], 2, v[10:11]
	v_mov_b32_e32 v10, 0
	v_mov_b32_e32 v9, 0
	s_and_saveexec_b64 s[34:35], s[8:9]
	s_cbranch_execz .LBB0_708
	global_load_dword v9, v[12:13], off nt
.LBB0_708:
	s_or_b64 exec, exec, s[34:35]
	v_lshl_add_u64 v[12:13], s[28:29], 2, v[12:13]
	s_and_saveexec_b64 s[34:35], s[8:9]
	s_cbranch_execz .LBB0_710
	global_load_dword v10, v[12:13], off nt
.LBB0_710:
	s_or_b64 exec, exec, s[34:35]
	v_lshl_add_u64 v[14:15], s[28:29], 2, v[12:13]
	v_mov_b32_e32 v12, 0
	v_mov_b32_e32 v11, 0
	s_and_saveexec_b64 s[34:35], s[8:9]
	s_cbranch_execz .LBB0_712
	global_load_dword v11, v[14:15], off nt
.LBB0_712:
	s_or_b64 exec, exec, s[34:35]
	v_lshl_add_u64 v[14:15], s[28:29], 2, v[14:15]
	s_and_saveexec_b64 s[34:35], s[8:9]
	s_cbranch_execz .LBB0_714
	global_load_dword v12, v[14:15], off nt
.LBB0_714:
	s_or_b64 exec, exec, s[34:35]
	v_lshl_add_u64 v[16:17], s[28:29], 2, v[14:15]
	v_mov_b32_e32 v14, 0
	v_mov_b32_e32 v13, 0
	s_and_saveexec_b64 s[34:35], s[8:9]
	s_cbranch_execz .LBB0_716
	global_load_dword v13, v[16:17], off nt
.LBB0_716:
	s_or_b64 exec, exec, s[34:35]
	v_lshl_add_u64 v[16:17], s[28:29], 2, v[16:17]
	s_and_saveexec_b64 s[34:35], s[8:9]
	s_cbranch_execz .LBB0_718
	global_load_dword v14, v[16:17], off nt
.LBB0_718:
	s_or_b64 exec, exec, s[34:35]
	v_lshl_add_u64 v[18:19], s[28:29], 2, v[16:17]
	v_mov_b32_e32 v16, 0
	v_mov_b32_e32 v15, 0
	s_and_saveexec_b64 s[34:35], s[8:9]
	s_cbranch_execz .LBB0_720
	global_load_dword v15, v[18:19], off nt
.LBB0_720:
	s_or_b64 exec, exec, s[34:35]
	v_lshl_add_u64 v[18:19], s[28:29], 2, v[18:19]
	s_and_saveexec_b64 s[34:35], s[8:9]
	s_cbranch_execz .LBB0_722
	global_load_dword v16, v[18:19], off nt
.LBB0_722:
	s_or_b64 exec, exec, s[34:35]
	v_lshl_add_u64 v[20:21], s[28:29], 2, v[18:19]
	v_mov_b32_e32 v18, 0
	v_mov_b32_e32 v17, 0
	s_and_saveexec_b64 s[34:35], s[8:9]
	s_cbranch_execz .LBB0_724
	global_load_dword v17, v[20:21], off nt
.LBB0_724:
	s_or_b64 exec, exec, s[34:35]
	v_lshl_add_u64 v[20:21], s[28:29], 2, v[20:21]
	s_and_saveexec_b64 s[34:35], s[8:9]
	s_cbranch_execz .LBB0_726
	global_load_dword v18, v[20:21], off nt
.LBB0_726:
	s_or_b64 exec, exec, s[34:35]
	v_lshl_add_u64 v[22:23], s[28:29], 2, v[20:21]
	v_mov_b32_e32 v20, 0
	v_mov_b32_e32 v19, 0
	s_and_saveexec_b64 s[34:35], s[8:9]
	s_cbranch_execz .LBB0_728
	global_load_dword v19, v[22:23], off nt
.LBB0_728:
	s_or_b64 exec, exec, s[34:35]
	v_lshl_add_u64 v[22:23], s[28:29], 2, v[22:23]
	s_and_saveexec_b64 s[34:35], s[8:9]
	s_cbranch_execz .LBB0_730
	global_load_dword v20, v[22:23], off nt
.LBB0_730:
	s_or_b64 exec, exec, s[34:35]
	v_lshl_add_u64 v[22:23], s[28:29], 2, v[22:23]
	v_mov_b32_e32 v26, 0
	v_mov_b32_e32 v21, 0
	s_and_saveexec_b64 s[34:35], s[8:9]
	s_cbranch_execz .LBB0_732
	global_load_dword v21, v[22:23], off nt
.LBB0_732:
	s_or_b64 exec, exec, s[34:35]
	v_lshl_add_u64 v[22:23], s[28:29], 2, v[22:23]
	s_and_saveexec_b64 s[34:35], s[8:9]
	s_cbranch_execz .LBB0_734
	global_load_dword v26, v[22:23], off nt
.LBB0_734:
	s_or_b64 exec, exec, s[34:35]
	v_lshl_add_u64 v[22:23], s[28:29], 2, v[22:23]
	v_mov_b32_e32 v32, 0
	v_mov_b32_e32 v27, 0
	s_and_saveexec_b64 s[34:35], s[8:9]
	s_cbranch_execz .LBB0_736
	global_load_dword v27, v[22:23], off nt
.LBB0_736:
	s_or_b64 exec, exec, s[34:35]
	v_lshl_add_u64 v[22:23], s[28:29], 2, v[22:23]
	s_and_saveexec_b64 s[34:35], s[8:9]
	s_cbranch_execz .LBB0_738
	global_load_dword v32, v[22:23], off nt
.LBB0_738:
	s_or_b64 exec, exec, s[34:35]
	v_lshl_add_u64 v[22:23], s[28:29], 2, v[22:23]
	s_waitcnt vmcnt(0)
	v_mov_b32_e32 v38, 0
	v_mov_b32_e32 v33, 0
	s_and_saveexec_b64 s[34:35], s[8:9]
	s_cbranch_execz .LBB0_740
	global_load_dword v33, v[22:23], off nt
.LBB0_740:
	s_or_b64 exec, exec, s[34:35]
	v_lshl_add_u64 v[22:23], s[28:29], 2, v[22:23]
	s_and_saveexec_b64 s[34:35], s[8:9]
	s_cbranch_execz .LBB0_742
	global_load_dword v38, v[22:23], off nt
.LBB0_742:
	s_or_b64 exec, exec, s[34:35]
	v_lshl_add_u64 v[22:23], s[28:29], 2, v[22:23]
	v_mov_b32_e32 v44, 0
	v_mov_b32_e32 v39, 0
	s_and_saveexec_b64 s[34:35], s[8:9]
	s_cbranch_execz .LBB0_744
	global_load_dword v39, v[22:23], off nt
.LBB0_744:
	s_or_b64 exec, exec, s[34:35]
	v_lshl_add_u64 v[22:23], s[28:29], 2, v[22:23]
	s_and_saveexec_b64 s[34:35], s[8:9]
	s_cbranch_execz .LBB0_746
	global_load_dword v44, v[22:23], off nt
.LBB0_746:
	s_or_b64 exec, exec, s[34:35]
	v_lshl_add_u64 v[22:23], s[28:29], 2, v[22:23]
	v_mov_b32_e32 v50, 0
	v_mov_b32_e32 v45, 0
	s_and_saveexec_b64 s[34:35], s[8:9]
	s_cbranch_execz .LBB0_986
	global_load_dword v45, v[22:23], off nt
	s_or_b64 exec, exec, s[34:35]
	v_lshl_add_u64 v[22:23], s[28:29], 2, v[22:23]
	s_and_saveexec_b64 s[34:35], s[8:9]
	s_cbranch_execnz .LBB0_987

; __device__ __forceinline__ void tr_load(const TrItem& t, float (&tv)[32], int lane) {
;     const int nn = t.n0 + (lane & 31); const bool ok = nn < t.N;
;     const float* p = t.W + (size_t)(t.k0 + 32 * (lane >> 5)) * t.N + nn; const size_t st = (size_t)t.N;
; #pragma unroll
;     for (int i = 0; i < 32; ++i) { tv[i] = ok ? *p : 0.f; p += st; }
; }
.LBB0_749:
.LBB0_750:
	s_or_saveexec_b64 s[8:9], s[8:9]
	v_mov_b32_e32 v59, 0
	v_mov_b32_e32 v51, 0
	v_mov_b32_e32 v58, 0
	s_xor_b64 exec, exec, s[8:9]
	s_cbranch_execz .LBB0_752
	s_lshl_b64 s[34:35], s[28:29], 2
	v_lshl_add_u64 v[22:23], v[22:23], 0, s[34:35]
	global_load_dword v51, v[22:23], off nt
	v_lshl_add_u64 v[22:23], v[22:23], 0, s[34:35]
	global_load_dword v58, v[22:23], off nt
	v_lshl_add_u64 v[22:23], v[22:23], 0, s[34:35]
	global_load_dword v59, v[22:23], off nt

; __device__ __forceinline__ void tr_load(const TrItem& t, float (&tv)[32], int lane) {
;     const int nn = t.n0 + (lane & 31); const bool ok = nn < t.N;
;     const float* p = t.W + (size_t)(t.k0 + 32 * (lane >> 5)) * t.N + nn; const size_t st = (size_t)t.N;
; #pragma unroll
;     for (int i = 0; i < 32; ++i) { tv[i] = ok ? *p : 0.f; p += st; }
; }
.LBB0_762:
	v_cndmask_b32_e64 v25, 0, 1, s[8:9]
	v_cmp_ne_u32_e64 s[6:7], 1, v25
	s_andn2_b64 vcc, exec, s[8:9]
	s_cbranch_vccnz .LBB0_824
	v_add_u32_e32 v25, s36, v74
	v_add_u32_e32 v28, s48, v1
	v_mad_i64_i32 v[30:31], s[8:9], v25, s40, 0
	v_lshl_add_u64 v[30:31], v[30:31], 2, s[34:35]
	v_ashrrev_i32_e32 v29, 31, v28
	v_cmp_gt_i32_e32 vcc, s40, v28
	v_lshl_add_u64 v[30:31], v[28:29], 2, v[30:31]
	v_mov_b32_e32 v29, 0
	v_mov_b32_e32 v28, 0
	s_and_saveexec_b64 s[8:9], vcc
	s_cbranch_execz .LBB0_765
	global_load_dword v28, v[30:31], off nt
.LBB0_765:
	s_or_b64 exec, exec, s[8:9]
	s_ashr_i32 s41, s40, 31
	v_lshl_add_u64 v[30:31], s[40:41], 2, v[30:31]
	s_and_saveexec_b64 s[8:9], vcc
	s_cbranch_execz .LBB0_767
	global_load_dword v29, v[30:31], off nt
.LBB0_767:
	s_or_b64 exec, exec, s[8:9]
	v_lshl_add_u64 v[34:35], s[40:41], 2, v[30:31]
	v_mov_b32_e32 v31, 0
	v_mov_b32_e32 v30, 0
	s_and_saveexec_b64 s[8:9], vcc
	s_cbranch_execz .LBB0_769
	global_load_dword v30, v[34:35], off nt
.LBB0_769:
	s_or_b64 exec, exec, s[8:9]
	v_lshl_add_u64 v[34:35], s[40:41], 2, v[34:35]
	s_and_saveexec_b64 s[8:9], vcc
	s_cbranch_execz .LBB0_771
	global_load_dword v31, v[34:35], off nt
.LBB0_771:
	s_or_b64 exec, exec, s[8:9]
	v_lshl_add_u64 v[36:37], s[40:41], 2, v[34:35]
	v_mov_b32_e32 v35, 0
	v_mov_b32_e32 v34, 0
	s_and_saveexec_b64 s[8:9], vcc
	s_cbranch_execz .LBB0_773
	global_load_dword v34, v[36:37], off nt
.LBB0_773:
	s_or_b64 exec, exec, s[8:9]
	v_lshl_add_u64 v[36:37], s[40:41], 2, v[36:37]
	s_and_saveexec_b64 s[8:9], vcc
	s_cbranch_execz .LBB0_775
	global_load_dword v35, v[36:37], off nt
.LBB0_775:
	s_or_b64 exec, exec, s[8:9]
	v_lshl_add_u64 v[40:41], s[40:41], 2, v[36:37]
	v_mov_b32_e32 v37, 0
	v_mov_b32_e32 v36, 0
	s_and_saveexec_b64 s[8:9], vcc
	s_cbranch_execz .LBB0_777
	global_load_dword v36, v[40:41], off nt
.LBB0_777:
	s_or_b64 exec, exec, s[8:9]
	v_lshl_add_u64 v[40:41], s[40:41], 2, v[40:41]
	s_and_saveexec_b64 s[8:9], vcc
	s_cbranch_execz .LBB0_779
	global_load_dword v37, v[40:41], off nt
.LBB0_779:
	s_or_b64 exec, exec, s[8:9]
	v_lshl_add_u64 v[42:43], s[40:41], 2, v[40:41]
	v_mov_b32_e32 v41, 0
	v_mov_b32_e32 v40, 0
	s_and_saveexec_b64 s[8:9], vcc
	s_cbranch_execz .LBB0_781
	global_load_dword v40, v[42:43], off nt
.LBB0_781:
	s_or_b64 exec, exec, s[8:9]
	v_lshl_add_u64 v[42:43], s[40:41], 2, v[42:43]
	s_and_saveexec_b64 s[8:9], vcc
	s_cbranch_execz .LBB0_783
	global_load_dword v41, v[42:43], off nt
.LBB0_783:
	s_or_b64 exec, exec, s[8:9]
	v_lshl_add_u64 v[46:47], s[40:41], 2, v[42:43]
	v_mov_b32_e32 v43, 0
	v_mov_b32_e32 v42, 0
	s_and_saveexec_b64 s[8:9], vcc
	s_cbranch_execz .LBB0_785
	global_load_dword v42, v[46:47], off nt
.LBB0_785:
	s_or_b64 exec, exec, s[8:9]
	v_lshl_add_u64 v[46:47], s[40:41], 2, v[46:47]
	s_and_saveexec_b64 s[8:9], vcc
	s_cbranch_execz .LBB0_787
	global_load_dword v43, v[46:47], off nt
.LBB0_787:
	s_or_b64 exec, exec, s[8:9]
	v_lshl_add_u64 v[48:49], s[40:41], 2, v[46:47]
	v_mov_b32_e32 v47, 0
	v_mov_b32_e32 v46, 0
	s_and_saveexec_b64 s[8:9], vcc
	s_cbranch_execz .LBB0_789
	global_load_dword v46, v[48:49], off nt
.LBB0_789:
	s_or_b64 exec, exec, s[8:9]
	v_lshl_add_u64 v[48:49], s[40:41], 2, v[48:49]
	s_and_saveexec_b64 s[8:9], vcc
	s_cbranch_execz .LBB0_791
	global_load_dword v47, v[48:49], off nt
.LBB0_791:
	s_or_b64 exec, exec, s[8:9]
	v_lshl_add_u64 v[52:53], s[40:41], 2, v[48:49]
	v_mov_b32_e32 v49, 0
	v_mov_b32_e32 v48, 0
	s_and_saveexec_b64 s[8:9], vcc
	s_cbranch_execz .LBB0_793
	global_load_dword v48, v[52:53], off nt
.LBB0_793:
	s_or_b64 exec, exec, s[8:9]
	v_lshl_add_u64 v[52:53], s[40:41], 2, v[52:53]
	s_and_saveexec_b64 s[8:9], vcc
	s_cbranch_execz .LBB0_795
	global_load_dword v49, v[52:53], off nt
.LBB0_795:
	s_or_b64 exec, exec, s[8:9]
	v_lshl_add_u64 v[54:55], s[40:41], 2, v[52:53]
	v_mov_b32_e32 v53, 0
	v_mov_b32_e32 v52, 0
	s_and_saveexec_b64 s[8:9], vcc
	s_cbranch_execz .LBB0_797
	global_load_dword v52, v[54:55], off nt
.LBB0_797:
	s_or_b64 exec, exec, s[8:9]
	v_lshl_add_u64 v[54:55], s[40:41], 2, v[54:55]
	s_and_saveexec_b64 s[8:9], vcc
	s_cbranch_execz .LBB0_799
	global_load_dword v53, v[54:55], off nt
.LBB0_799:
	s_or_b64 exec, exec, s[8:9]
	v_lshl_add_u64 v[56:57], s[40:41], 2, v[54:55]
	v_mov_b32_e32 v55, 0
	v_mov_b32_e32 v54, 0
	s_and_saveexec_b64 s[8:9], vcc
	s_cbranch_execz .LBB0_801
	global_load_dword v54, v[56:57], off nt
.LBB0_801:
	s_or_b64 exec, exec, s[8:9]
	v_lshl_add_u64 v[56:57], s[40:41], 2, v[56:57]
	s_and_saveexec_b64 s[8:9], vcc
	s_cbranch_execz .LBB0_803
	global_load_dword v55, v[56:57], off nt
.LBB0_803:
	s_or_b64 exec, exec, s[8:9]
	v_lshl_add_u64 v[60:61], s[40:41], 2, v[56:57]
	v_mov_b32_e32 v57, 0
	v_mov_b32_e32 v56, 0
	s_and_saveexec_b64 s[8:9], vcc
	s_cbranch_execz .LBB0_805
	global_load_dword v56, v[60:61], off nt
.LBB0_805:
	s_or_b64 exec, exec, s[8:9]
	v_lshl_add_u64 v[60:61], s[40:41], 2, v[60:61]
	s_and_saveexec_b64 s[8:9], vcc
	s_cbranch_execz .LBB0_807
	global_load_dword v57, v[60:61], off nt
.LBB0_807:
	s_or_b64 exec, exec, s[8:9]
	v_lshl_add_u64 v[62:63], s[40:41], 2, v[60:61]
	v_mov_b32_e32 v61, 0
	v_mov_b32_e32 v60, 0
	s_and_saveexec_b64 s[8:9], vcc
	s_cbranch_execz .LBB0_809
	global_load_dword v60, v[62:63], off nt
.LBB0_809:
	s_or_b64 exec, exec, s[8:9]
	v_lshl_add_u64 v[62:63], s[40:41], 2, v[62:63]
	s_and_saveexec_b64 s[8:9], vcc
	s_cbranch_execz .LBB0_811
	global_load_dword v61, v[62:63], off nt
.LBB0_811:
	s_or_b64 exec, exec, s[8:9]
	v_lshl_add_u64 v[64:65], s[40:41], 2, v[62:63]
	v_mov_b32_e32 v63, 0
	v_mov_b32_e32 v62, 0
	s_and_saveexec_b64 s[8:9], vcc
	s_cbranch_execz .LBB0_813
	global_load_dword v62, v[64:65], off nt
.LBB0_813:
	s_or_b64 exec, exec, s[8:9]
	v_lshl_add_u64 v[64:65], s[40:41], 2, v[64:65]
	s_and_saveexec_b64 s[8:9], vcc
	s_cbranch_execz .LBB0_815
	global_load_dword v63, v[64:65], off nt
.LBB0_815:
	s_or_b64 exec, exec, s[8:9]
	v_lshl_add_u64 v[66:67], s[40:41], 2, v[64:65]
	v_mov_b32_e32 v65, 0
	v_mov_b32_e32 v64, 0
	s_and_saveexec_b64 s[8:9], vcc
	s_cbranch_execz .LBB0_817
	global_load_dword v64, v[66:67], off nt
.LBB0_817:
	s_or_b64 exec, exec, s[8:9]
	v_lshl_add_u64 v[66:67], s[40:41], 2, v[66:67]
	s_and_saveexec_b64 s[8:9], vcc
	s_cbranch_execz .LBB0_819
	global_load_dword v65, v[66:67], off nt
.LBB0_819:
	s_or_b64 exec, exec, s[8:9]
	v_lshl_add_u64 v[70:71], s[40:41], 2, v[66:67]
	v_mov_b32_e32 v67, 0
	v_mov_b32_e32 v66, 0
	s_and_saveexec_b64 s[8:9], vcc
	s_cbranch_execz .LBB0_821
	global_load_dword v66, v[70:71], off nt
.LBB0_821:
	s_or_b64 exec, exec, s[8:9]
	v_mov_b32_e32 v69, 0
	v_mov_b32_e32 v68, 0
	s_and_saveexec_b64 s[8:9], vcc
	s_cbranch_execz .LBB0_823
	s_lshl_b64 s[44:45], s[40:41], 2
	v_lshl_add_u64 v[68:69], v[70:71], 0, s[44:45]
	v_lshl_add_u64 v[70:71], v[68:69], 0, s[44:45]
	v_lshl_add_u64 v[72:73], v[70:71], 0, s[44:45]
	global_load_dword v67, v[68:69], off nt
	s_nop 0
	global_load_dword v68, v[70:71], off nt
	global_load_dword v69, v[72:73], off nt

; __device__ __forceinline__ void tr_load(const TrItem& t, float (&tv)[32], int lane) {
;     const int nn = t.n0 + (lane & 31); const bool ok = nn < t.N;
;     const float* p = t.W + (size_t)(t.k0 + 32 * (lane >> 5)) * t.N + nn; const size_t st = (size_t)t.N;
; #pragma unroll
;     for (int i = 0; i < 32; ++i) { tv[i] = ok ? *p : 0.f; p += st; }
; }
.LBB0_862:
	s_andn2_b64 vcc, exec, s[6:7]
	s_cbranch_vccnz .LBB0_926
	v_add_u32_e32 v3, s26, v74
	v_add_u32_e32 v2, s5, v1
	v_mad_i64_i32 v[4:5], s[44:45], v3, s28, 0
	v_lshl_add_u64 v[4:5], v[4:5], 2, s[18:19]
	v_ashrrev_i32_e32 v3, 31, v2
	v_cmp_le_i32_e32 vcc, s28, v2
	v_cmp_gt_i32_e64 s[6:7], s28, v2
	v_lshl_add_u64 v[4:5], v[2:3], 2, v[4:5]
	v_mov_b32_e32 v3, 0
	v_mov_b32_e32 v2, 0
	s_and_saveexec_b64 s[44:45], s[6:7]
	s_cbranch_execz .LBB0_865
	global_load_dword v2, v[4:5], off nt
.LBB0_865:
	s_or_b64 exec, exec, s[44:45]
	s_ashr_i32 s29, s28, 31
	v_lshl_add_u64 v[4:5], s[28:29], 2, v[4:5]
	s_and_saveexec_b64 s[44:45], s[6:7]
	s_cbranch_execz .LBB0_867
	global_load_dword v3, v[4:5], off nt
.LBB0_867:
	s_or_b64 exec, exec, s[44:45]
	v_lshl_add_u64 v[6:7], s[28:29], 2, v[4:5]
	v_mov_b32_e32 v5, 0
	v_mov_b32_e32 v4, 0
	s_and_saveexec_b64 s[44:45], s[6:7]
	s_cbranch_execz .LBB0_869
	global_load_dword v4, v[6:7], off nt
.LBB0_869:
	s_or_b64 exec, exec, s[44:45]
	v_lshl_add_u64 v[6:7], s[28:29], 2, v[6:7]
	s_and_saveexec_b64 s[44:45], s[6:7]
	s_cbranch_execz .LBB0_871
	global_load_dword v5, v[6:7], off nt
.LBB0_871:
	s_or_b64 exec, exec, s[44:45]
	v_lshl_add_u64 v[8:9], s[28:29], 2, v[6:7]
	v_mov_b32_e32 v7, 0
	v_mov_b32_e32 v6, 0
	s_and_saveexec_b64 s[44:45], s[6:7]
	s_cbranch_execz .LBB0_873
	global_load_dword v6, v[8:9], off nt
.LBB0_873:
	s_or_b64 exec, exec, s[44:45]
	v_lshl_add_u64 v[8:9], s[28:29], 2, v[8:9]
	s_and_saveexec_b64 s[44:45], s[6:7]
	s_cbranch_execz .LBB0_875
	global_load_dword v7, v[8:9], off nt
.LBB0_875:
	s_or_b64 exec, exec, s[44:45]
	v_lshl_add_u64 v[10:11], s[28:29], 2, v[8:9]
	v_mov_b32_e32 v9, 0
	v_mov_b32_e32 v8, 0
	s_and_saveexec_b64 s[44:45], s[6:7]
	s_cbranch_execz .LBB0_877
	global_load_dword v8, v[10:11], off nt
.LBB0_877:
	s_or_b64 exec, exec, s[44:45]
	v_lshl_add_u64 v[10:11], s[28:29], 2, v[10:11]
	s_and_saveexec_b64 s[44:45], s[6:7]
	s_cbranch_execz .LBB0_879
	global_load_dword v9, v[10:11], off nt
.LBB0_879:
	s_or_b64 exec, exec, s[44:45]
	v_lshl_add_u64 v[12:13], s[28:29], 2, v[10:11]
	v_mov_b32_e32 v11, 0
	v_mov_b32_e32 v10, 0
	s_and_saveexec_b64 s[44:45], s[6:7]
	s_cbranch_execz .LBB0_881
	global_load_dword v10, v[12:13], off nt
.LBB0_881:
	s_or_b64 exec, exec, s[44:45]
	v_lshl_add_u64 v[12:13], s[28:29], 2, v[12:13]
	s_and_saveexec_b64 s[44:45], s[6:7]
	s_cbranch_execz .LBB0_883
	global_load_dword v11, v[12:13], off nt
.LBB0_883:
	s_or_b64 exec, exec, s[44:45]
	v_lshl_add_u64 v[14:15], s[28:29], 2, v[12:13]
	v_mov_b32_e32 v13, 0
	v_mov_b32_e32 v12, 0
	s_and_saveexec_b64 s[44:45], s[6:7]
	s_cbranch_execz .LBB0_885
	global_load_dword v12, v[14:15], off nt
.LBB0_885:
	s_or_b64 exec, exec, s[44:45]
	v_lshl_add_u64 v[14:15], s[28:29], 2, v[14:15]
	s_and_saveexec_b64 s[44:45], s[6:7]
	s_cbranch_execz .LBB0_887
	global_load_dword v13, v[14:15], off nt
.LBB0_887:
	s_or_b64 exec, exec, s[44:45]
	v_lshl_add_u64 v[16:17], s[28:29], 2, v[14:15]
	v_mov_b32_e32 v15, 0
	v_mov_b32_e32 v14, 0
	s_and_saveexec_b64 s[44:45], s[6:7]
	s_cbranch_execz .LBB0_889
	global_load_dword v14, v[16:17], off nt
.LBB0_889:
	s_or_b64 exec, exec, s[44:45]
	v_lshl_add_u64 v[16:17], s[28:29], 2, v[16:17]
	s_and_saveexec_b64 s[44:45], s[6:7]
	s_cbranch_execz .LBB0_891
	global_load_dword v15, v[16:17], off nt
.LBB0_891:
	s_or_b64 exec, exec, s[44:45]
	v_lshl_add_u64 v[18:19], s[28:29], 2, v[16:17]
	v_mov_b32_e32 v17, 0
	v_mov_b32_e32 v16, 0
	s_and_saveexec_b64 s[44:45], s[6:7]
	s_cbranch_execz .LBB0_893
	global_load_dword v16, v[18:19], off nt
.LBB0_893:
	s_or_b64 exec, exec, s[44:45]
	v_lshl_add_u64 v[18:19], s[28:29], 2, v[18:19]
	s_and_saveexec_b64 s[44:45], s[6:7]
	s_cbranch_execz .LBB0_895
	global_load_dword v17, v[18:19], off nt
.LBB0_895:
	s_or_b64 exec, exec, s[44:45]
	v_lshl_add_u64 v[20:21], s[28:29], 2, v[18:19]
	v_mov_b32_e32 v19, 0
	v_mov_b32_e32 v18, 0
	s_and_saveexec_b64 s[44:45], s[6:7]
	s_cbranch_execz .LBB0_897
	global_load_dword v18, v[20:21], off nt
.LBB0_897:
	s_or_b64 exec, exec, s[44:45]
	v_lshl_add_u64 v[20:21], s[28:29], 2, v[20:21]
	s_and_saveexec_b64 s[44:45], s[6:7]
	s_cbranch_execz .LBB0_899
	global_load_dword v19, v[20:21], off nt
.LBB0_899:
	s_or_b64 exec, exec, s[44:45]
	v_lshl_add_u64 v[26:27], s[28:29], 2, v[20:21]
	v_mov_b32_e32 v21, 0
	v_mov_b32_e32 v20, 0
	s_and_saveexec_b64 s[44:45], s[6:7]
	s_cbranch_execz .LBB0_901
	global_load_dword v20, v[26:27], off nt
.LBB0_901:
	s_or_b64 exec, exec, s[44:45]
	v_lshl_add_u64 v[26:27], s[28:29], 2, v[26:27]
	s_and_saveexec_b64 s[44:45], s[6:7]
	s_cbranch_execz .LBB0_903
	global_load_dword v21, v[26:27], off nt
.LBB0_903:
	s_or_b64 exec, exec, s[44:45]
	v_lshl_add_u64 v[32:33], s[28:29], 2, v[26:27]
	v_mov_b32_e32 v27, 0
	v_mov_b32_e32 v26, 0
	s_and_saveexec_b64 s[44:45], s[6:7]
	s_cbranch_execz .LBB0_905
	global_load_dword v26, v[32:33], off nt
.LBB0_905:
	s_or_b64 exec, exec, s[44:45]
	v_lshl_add_u64 v[32:33], s[28:29], 2, v[32:33]
	s_and_saveexec_b64 s[44:45], s[6:7]
	s_cbranch_execz .LBB0_907
	global_load_dword v27, v[32:33], off nt
.LBB0_907:
	s_or_b64 exec, exec, s[44:45]
	v_lshl_add_u64 v[38:39], s[28:29], 2, v[32:33]
	v_mov_b32_e32 v33, 0
	v_mov_b32_e32 v32, 0
	s_and_saveexec_b64 s[44:45], s[6:7]
	s_cbranch_execz .LBB0_909
	global_load_dword v32, v[38:39], off nt
.LBB0_909:
	s_or_b64 exec, exec, s[44:45]
	v_lshl_add_u64 v[38:39], s[28:29], 2, v[38:39]
	s_and_saveexec_b64 s[44:45], s[6:7]
	s_cbranch_execz .LBB0_911
	global_load_dword v33, v[38:39], off nt
.LBB0_911:
	s_or_b64 exec, exec, s[44:45]
	v_lshl_add_u64 v[44:45], s[28:29], 2, v[38:39]
	v_mov_b32_e32 v39, 0
	v_mov_b32_e32 v38, 0
	s_and_saveexec_b64 s[44:45], s[6:7]
	s_cbranch_execz .LBB0_913
	global_load_dword v38, v[44:45], off nt
.LBB0_913:
	s_or_b64 exec, exec, s[44:45]
	v_lshl_add_u64 v[44:45], s[28:29], 2, v[44:45]
	s_and_saveexec_b64 s[44:45], s[6:7]
	s_cbranch_execz .LBB0_915
	global_load_dword v39, v[44:45], off nt
.LBB0_915:
	s_or_b64 exec, exec, s[44:45]
	v_lshl_add_u64 v[50:51], s[28:29], 2, v[44:45]
	v_mov_b32_e32 v45, 0
	v_mov_b32_e32 v44, 0
	s_and_saveexec_b64 s[44:45], s[6:7]
	s_cbranch_execz .LBB0_917
	global_load_dword v44, v[50:51], off nt
.LBB0_917:
	s_or_b64 exec, exec, s[44:45]
	v_lshl_add_u64 v[50:51], s[28:29], 2, v[50:51]
	s_and_saveexec_b64 s[44:45], s[6:7]
	s_cbranch_execz .LBB0_919
	global_load_dword v45, v[50:51], off nt
.LBB0_919:
	s_or_b64 exec, exec, s[44:45]
	v_lshl_add_u64 v[70:71], s[28:29], 2, v[50:51]
	v_mov_b32_e32 v50, 0
	s_and_saveexec_b64 s[44:45], s[6:7]
	s_cbranch_execz .LBB0_921
	global_load_dword v50, v[70:71], off nt

; __device__ __forceinline__ void tr_load(const TrItem& t, float (&tv)[32], int lane) {
;     const int nn = t.n0 + (lane & 31); const bool ok = nn < t.N;
;     const float* p = t.W + (size_t)(t.k0 + 32 * (lane >> 5)) * t.N + nn; const size_t st = (size_t)t.N;
; #pragma unroll
;     for (int i = 0; i < 32; ++i) { tv[i] = ok ? *p : 0.f; p += st; }
; }
.LBB0_1314:
	v_cndmask_b32_e64 v1, 0, 1, s[8:9]
	v_cmp_ne_u32_e64 s[6:7], 1, v1
	s_andn2_b64 vcc, exec, s[8:9]
	v_and_b32_e32 v78, 31, v2
	v_and_b32_e32 v68, 32, v2
	s_cbranch_vccnz .LBB0_1378
	v_add_u32_e32 v1, s38, v68
	s_waitcnt vmcnt(0)
	v_add_u32_e32 v4, s55, v78
	v_mad_i64_i32 v[6:7], s[52:53], v1, s40, 0
	v_lshl_add_u64 v[6:7], v[6:7], 2, s[30:31]
	v_ashrrev_i32_e32 v5, 31, v4
	v_cmp_le_i32_e32 vcc, s40, v4
	v_cmp_gt_i32_e64 s[8:9], s40, v4
	v_lshl_add_u64 v[6:7], v[4:5], 2, v[6:7]
	v_mov_b32_e32 v5, 0
	v_mov_b32_e32 v4, 0
	s_and_saveexec_b64 s[52:53], s[8:9]
	s_cbranch_execz .LBB0_1317
	global_load_dword v4, v[6:7], off nt
.LBB0_1317:
	s_or_b64 exec, exec, s[52:53]
	s_ashr_i32 s41, s40, 31
	v_lshl_add_u64 v[6:7], s[40:41], 2, v[6:7]
	s_and_saveexec_b64 s[52:53], s[8:9]
	s_cbranch_execz .LBB0_1319
	global_load_dword v5, v[6:7], off nt
.LBB0_1319:
	s_or_b64 exec, exec, s[52:53]
	v_lshl_add_u64 v[8:9], s[40:41], 2, v[6:7]
	v_mov_b32_e32 v7, 0
	v_mov_b32_e32 v6, 0
	s_and_saveexec_b64 s[52:53], s[8:9]
	s_cbranch_execz .LBB0_1321
	global_load_dword v6, v[8:9], off nt
.LBB0_1321:
	s_or_b64 exec, exec, s[52:53]
	v_lshl_add_u64 v[8:9], s[40:41], 2, v[8:9]
	s_and_saveexec_b64 s[52:53], s[8:9]
	s_cbranch_execz .LBB0_1323
	global_load_dword v7, v[8:9], off nt
.LBB0_1323:
	s_or_b64 exec, exec, s[52:53]
	v_lshl_add_u64 v[10:11], s[40:41], 2, v[8:9]
	v_mov_b32_e32 v9, 0
	v_mov_b32_e32 v8, 0
	s_and_saveexec_b64 s[52:53], s[8:9]
	s_cbranch_execz .LBB0_1325
	global_load_dword v8, v[10:11], off nt
.LBB0_1325:
	s_or_b64 exec, exec, s[52:53]
	v_lshl_add_u64 v[10:11], s[40:41], 2, v[10:11]
	s_and_saveexec_b64 s[52:53], s[8:9]
	s_cbranch_execz .LBB0_1327
	global_load_dword v9, v[10:11], off nt
.LBB0_1327:
	s_or_b64 exec, exec, s[52:53]
	v_lshl_add_u64 v[12:13], s[40:41], 2, v[10:11]
	v_mov_b32_e32 v11, 0
	v_mov_b32_e32 v10, 0
	s_and_saveexec_b64 s[52:53], s[8:9]
	s_cbranch_execz .LBB0_1329
	global_load_dword v10, v[12:13], off nt
.LBB0_1329:
	s_or_b64 exec, exec, s[52:53]
	v_lshl_add_u64 v[12:13], s[40:41], 2, v[12:13]
	s_and_saveexec_b64 s[52:53], s[8:9]
	s_cbranch_execz .LBB0_1331
	global_load_dword v11, v[12:13], off nt
.LBB0_1331:
	s_or_b64 exec, exec, s[52:53]
	v_lshl_add_u64 v[14:15], s[40:41], 2, v[12:13]
	v_mov_b32_e32 v13, 0
	v_mov_b32_e32 v12, 0
	s_and_saveexec_b64 s[52:53], s[8:9]
	s_cbranch_execz .LBB0_1333
	global_load_dword v12, v[14:15], off nt
.LBB0_1333:
	s_or_b64 exec, exec, s[52:53]
	v_lshl_add_u64 v[14:15], s[40:41], 2, v[14:15]
	s_and_saveexec_b64 s[52:53], s[8:9]
	s_cbranch_execz .LBB0_1335
	global_load_dword v13, v[14:15], off nt
.LBB0_1335:
	s_or_b64 exec, exec, s[52:53]
	v_lshl_add_u64 v[16:17], s[40:41], 2, v[14:15]
	v_mov_b32_e32 v15, 0
	v_mov_b32_e32 v14, 0
	s_and_saveexec_b64 s[52:53], s[8:9]
	s_cbranch_execz .LBB0_1337
	global_load_dword v14, v[16:17], off nt
.LBB0_1337:
	s_or_b64 exec, exec, s[52:53]
	v_lshl_add_u64 v[16:17], s[40:41], 2, v[16:17]
	s_and_saveexec_b64 s[52:53], s[8:9]
	s_cbranch_execz .LBB0_1339
	global_load_dword v15, v[16:17], off nt
.LBB0_1339:
	s_or_b64 exec, exec, s[52:53]
	v_lshl_add_u64 v[18:19], s[40:41], 2, v[16:17]
	v_mov_b32_e32 v17, 0
	v_mov_b32_e32 v16, 0
	s_and_saveexec_b64 s[52:53], s[8:9]
	s_cbranch_execz .LBB0_1341
	global_load_dword v16, v[18:19], off nt
.LBB0_1341:
	s_or_b64 exec, exec, s[52:53]
	v_lshl_add_u64 v[18:19], s[40:41], 2, v[18:19]
	s_and_saveexec_b64 s[52:53], s[8:9]
	s_cbranch_execz .LBB0_1343
	global_load_dword v17, v[18:19], off nt
.LBB0_1343:
	s_or_b64 exec, exec, s[52:53]
	v_lshl_add_u64 v[20:21], s[40:41], 2, v[18:19]
	v_mov_b32_e32 v19, 0
	v_mov_b32_e32 v18, 0
	s_and_saveexec_b64 s[52:53], s[8:9]
	s_cbranch_execz .LBB0_1345
	global_load_dword v18, v[20:21], off nt
; __device__ __forceinline__ void tr_load(const TrItem& t, float (&tv)[32], int lane) {
;     const int nn = t.n0 + (lane & 31); const bool ok = nn < t.N;
;     const float* p = t.W + (size_t)(t.k0 + 32 * (lane >> 5)) * t.N + nn; const size_t st = (size_t)t.N;
; #pragma unroll
;     for (int i = 0; i < 32; ++i) { tv[i] = ok ? *p : 0.f; p += st; }
; }
.LBB0_1345:
	s_or_b64 exec, exec, s[52:53]
	v_lshl_add_u64 v[20:21], s[40:41], 2, v[20:21]
	s_and_saveexec_b64 s[52:53], s[8:9]
	s_cbranch_execz .LBB0_1347
	global_load_dword v19, v[20:21], off nt
.LBB0_1347:
	s_or_b64 exec, exec, s[52:53]
	v_lshl_add_u64 v[22:23], s[40:41], 2, v[20:21]
	v_mov_b32_e32 v21, 0
	v_mov_b32_e32 v20, 0
	s_and_saveexec_b64 s[52:53], s[8:9]
	s_cbranch_execz .LBB0_1349
	global_load_dword v20, v[22:23], off nt
.LBB0_1349:
	s_or_b64 exec, exec, s[52:53]
	v_lshl_add_u64 v[22:23], s[40:41], 2, v[22:23]
	s_and_saveexec_b64 s[52:53], s[8:9]
	s_cbranch_execz .LBB0_1351
	global_load_dword v21, v[22:23], off nt
.LBB0_1351:
	s_or_b64 exec, exec, s[52:53]
	v_lshl_add_u64 v[24:25], s[40:41], 2, v[22:23]
	v_mov_b32_e32 v23, 0
	v_mov_b32_e32 v22, 0
	s_and_saveexec_b64 s[52:53], s[8:9]
	s_cbranch_execz .LBB0_1353
	global_load_dword v22, v[24:25], off nt
.LBB0_1353:
	s_or_b64 exec, exec, s[52:53]
	v_lshl_add_u64 v[24:25], s[40:41], 2, v[24:25]
	s_and_saveexec_b64 s[52:53], s[8:9]
	s_cbranch_execz .LBB0_1355
	global_load_dword v23, v[24:25], off nt
.LBB0_1355:
	s_or_b64 exec, exec, s[52:53]
	v_lshl_add_u64 v[26:27], s[40:41], 2, v[24:25]
	v_mov_b32_e32 v25, 0
	v_mov_b32_e32 v24, 0
	s_and_saveexec_b64 s[52:53], s[8:9]
	s_cbranch_execz .LBB0_1357
	global_load_dword v24, v[26:27], off nt
.LBB0_1357:
	s_or_b64 exec, exec, s[52:53]
	v_lshl_add_u64 v[26:27], s[40:41], 2, v[26:27]
	s_and_saveexec_b64 s[52:53], s[8:9]
	s_cbranch_execz .LBB0_1359
	global_load_dword v25, v[26:27], off nt
.LBB0_1359:
	s_or_b64 exec, exec, s[52:53]
	v_lshl_add_u64 v[28:29], s[40:41], 2, v[26:27]
	v_mov_b32_e32 v27, 0
	v_mov_b32_e32 v26, 0
	s_and_saveexec_b64 s[52:53], s[8:9]
	s_cbranch_execz .LBB0_1361
	global_load_dword v26, v[28:29], off nt
.LBB0_1361:
	s_or_b64 exec, exec, s[52:53]
	v_lshl_add_u64 v[28:29], s[40:41], 2, v[28:29]
	s_and_saveexec_b64 s[52:53], s[8:9]
	s_cbranch_execz .LBB0_1363
	global_load_dword v27, v[28:29], off nt
.LBB0_1363:
	s_or_b64 exec, exec, s[52:53]
	v_lshl_add_u64 v[30:31], s[40:41], 2, v[28:29]
	v_mov_b32_e32 v29, 0
	v_mov_b32_e32 v28, 0
	s_and_saveexec_b64 s[52:53], s[8:9]
	s_cbranch_execz .LBB0_1365
	global_load_dword v28, v[30:31], off nt
.LBB0_1365:
	s_or_b64 exec, exec, s[52:53]
	v_lshl_add_u64 v[30:31], s[40:41], 2, v[30:31]
	s_and_saveexec_b64 s[52:53], s[8:9]
	s_cbranch_execz .LBB0_1367
	global_load_dword v29, v[30:31], off nt
.LBB0_1367:
	s_or_b64 exec, exec, s[52:53]
	v_lshl_add_u64 v[32:33], s[40:41], 2, v[30:31]
	v_mov_b32_e32 v31, 0
	v_mov_b32_e32 v30, 0
	s_and_saveexec_b64 s[52:53], s[8:9]
	s_cbranch_execz .LBB0_1369
	global_load_dword v30, v[32:33], off nt
.LBB0_1369:
	s_or_b64 exec, exec, s[52:53]
	v_lshl_add_u64 v[32:33], s[40:41], 2, v[32:33]
	s_and_saveexec_b64 s[52:53], s[8:9]
	s_cbranch_execz .LBB0_1371
	global_load_dword v31, v[32:33], off nt
.LBB0_1371:
	s_or_b64 exec, exec, s[52:53]
	v_lshl_add_u64 v[70:71], s[40:41], 2, v[32:33]
	v_mov_b32_e32 v32, 0
	s_and_saveexec_b64 s[52:53], s[8:9]
	s_cbranch_execz .LBB0_1373
	global_load_dword v32, v[70:71], off nt
.LBB0_1373:
	s_or_b64 exec, exec, s[52:53]
	s_and_saveexec_b64 s[8:9], vcc
	s_xor_b64 s[8:9], exec, s[8:9]
	s_or_saveexec_b64 s[8:9], s[8:9]
	v_mov_b32_e32 v35, 0
	v_mov_b32_e32 v33, 0
	v_mov_b32_e32 v34, 0
	s_xor_b64 exec, exec, s[8:9]
	s_cbranch_execz .LBB0_1377
	s_lshl_b64 s[52:53], s[40:41], 2
	v_lshl_add_u64 v[34:35], v[70:71], 0, s[52:53]
	v_lshl_add_u64 v[70:71], v[34:35], 0, s[52:53]
	global_load_dword v33, v[34:35], off nt
	s_nop 0
	global_load_dword v34, v[70:71], off nt
	v_lshl_add_u64 v[70:71], v[70:71], 0, s[52:53]
	global_load_dword v35, v[70:71], off nt

; __device__ __forceinline__ void tr_load(const TrItem& t, float (&tv)[32], int lane) {
;     const int nn = t.n0 + (lane & 31); const bool ok = nn < t.N;
;     const float* p = t.W + (size_t)(t.k0 + 32 * (lane >> 5)) * t.N + nn; const size_t st = (size_t)t.N;
; #pragma unroll
;     for (int i = 0; i < 32; ++i) { tv[i] = ok ? *p : 0.f; p += st; }
; }
.LBB0_1386:
	v_cndmask_b32_e64 v1, 0, 1, s[8:9]
	v_cmp_ne_u32_e64 s[6:7], 1, v1
	s_andn2_b64 vcc, exec, s[8:9]
	s_cbranch_vccnz .LBB0_1448
	v_add_u32_e32 v1, s26, v68
	v_add_u32_e32 v36, s1, v78
	v_mad_i64_i32 v[38:39], s[8:9], v1, s28, 0
	v_lshl_add_u64 v[38:39], v[38:39], 2, s[10:11]
	v_ashrrev_i32_e32 v37, 31, v36
	v_cmp_gt_i32_e32 vcc, s28, v36
	v_lshl_add_u64 v[38:39], v[36:37], 2, v[38:39]
	v_mov_b32_e32 v37, 0
	v_mov_b32_e32 v36, 0
	s_and_saveexec_b64 s[8:9], vcc
	s_cbranch_execz .LBB0_1389
	global_load_dword v36, v[38:39], off nt
.LBB0_1389:
	s_or_b64 exec, exec, s[8:9]
	s_ashr_i32 s29, s28, 31
	v_lshl_add_u64 v[38:39], s[28:29], 2, v[38:39]
	s_and_saveexec_b64 s[8:9], vcc
	s_cbranch_execz .LBB0_1391
	global_load_dword v37, v[38:39], off nt
.LBB0_1391:
	s_or_b64 exec, exec, s[8:9]
	v_lshl_add_u64 v[40:41], s[28:29], 2, v[38:39]
	v_mov_b32_e32 v39, 0
	v_mov_b32_e32 v38, 0
	s_and_saveexec_b64 s[8:9], vcc
	s_cbranch_execz .LBB0_1393
	global_load_dword v38, v[40:41], off nt
.LBB0_1393:
	s_or_b64 exec, exec, s[8:9]
	v_lshl_add_u64 v[40:41], s[28:29], 2, v[40:41]
	s_and_saveexec_b64 s[8:9], vcc
	s_cbranch_execz .LBB0_1395
	global_load_dword v39, v[40:41], off nt
.LBB0_1395:
	s_or_b64 exec, exec, s[8:9]
	v_lshl_add_u64 v[42:43], s[28:29], 2, v[40:41]
	v_mov_b32_e32 v41, 0
	v_mov_b32_e32 v40, 0
	s_and_saveexec_b64 s[8:9], vcc
	s_cbranch_execz .LBB0_1397
	global_load_dword v40, v[42:43], off nt
.LBB0_1397:
	s_or_b64 exec, exec, s[8:9]
	v_lshl_add_u64 v[42:43], s[28:29], 2, v[42:43]
	s_and_saveexec_b64 s[8:9], vcc
	s_cbranch_execz .LBB0_1399
	global_load_dword v41, v[42:43], off nt
.LBB0_1399:
	s_or_b64 exec, exec, s[8:9]
	v_lshl_add_u64 v[44:45], s[28:29], 2, v[42:43]
	v_mov_b32_e32 v43, 0
	v_mov_b32_e32 v42, 0
	s_and_saveexec_b64 s[8:9], vcc
	s_cbranch_execz .LBB0_1401
	global_load_dword v42, v[44:45], off nt
.LBB0_1401:
	s_or_b64 exec, exec, s[8:9]
	v_lshl_add_u64 v[44:45], s[28:29], 2, v[44:45]
	s_and_saveexec_b64 s[8:9], vcc
	s_cbranch_execz .LBB0_1403
	global_load_dword v43, v[44:45], off nt
.LBB0_1403:
	s_or_b64 exec, exec, s[8:9]
	v_lshl_add_u64 v[46:47], s[28:29], 2, v[44:45]
	v_mov_b32_e32 v45, 0
	v_mov_b32_e32 v44, 0
	s_and_saveexec_b64 s[8:9], vcc
	s_cbranch_execz .LBB0_1405
	global_load_dword v44, v[46:47], off nt
.LBB0_1405:
	s_or_b64 exec, exec, s[8:9]
	v_lshl_add_u64 v[46:47], s[28:29], 2, v[46:47]
	s_and_saveexec_b64 s[8:9], vcc
	s_cbranch_execz .LBB0_1407
	global_load_dword v45, v[46:47], off nt
.LBB0_1407:
	s_or_b64 exec, exec, s[8:9]
	v_lshl_add_u64 v[48:49], s[28:29], 2, v[46:47]
	v_mov_b32_e32 v47, 0
	v_mov_b32_e32 v46, 0
	s_and_saveexec_b64 s[8:9], vcc
	s_cbranch_execz .LBB0_1409
	global_load_dword v46, v[48:49], off nt
.LBB0_1409:
	s_or_b64 exec, exec, s[8:9]
	v_lshl_add_u64 v[48:49], s[28:29], 2, v[48:49]
	s_and_saveexec_b64 s[8:9], vcc
	s_cbranch_execz .LBB0_1411
	global_load_dword v47, v[48:49], off nt
.LBB0_1411:
	s_or_b64 exec, exec, s[8:9]
	v_lshl_add_u64 v[50:51], s[28:29], 2, v[48:49]
	v_mov_b32_e32 v49, 0
	v_mov_b32_e32 v48, 0
	s_and_saveexec_b64 s[8:9], vcc
	s_cbranch_execz .LBB0_1413
	global_load_dword v48, v[50:51], off nt
.LBB0_1413:
	s_or_b64 exec, exec, s[8:9]
	v_lshl_add_u64 v[50:51], s[28:29], 2, v[50:51]
	s_and_saveexec_b64 s[8:9], vcc
	s_cbranch_execz .LBB0_1415
	global_load_dword v49, v[50:51], off nt
.LBB0_1415:
	s_or_b64 exec, exec, s[8:9]
	v_lshl_add_u64 v[52:53], s[28:29], 2, v[50:51]
	v_mov_b32_e32 v51, 0
	v_mov_b32_e32 v50, 0
	s_and_saveexec_b64 s[8:9], vcc
	s_cbranch_execz .LBB0_1417
	global_load_dword v50, v[52:53], off nt
.LBB0_1417:
	s_or_b64 exec, exec, s[8:9]
	v_lshl_add_u64 v[52:53], s[28:29], 2, v[52:53]
	s_and_saveexec_b64 s[8:9], vcc
	s_cbranch_execz .LBB0_1419
	global_load_dword v51, v[52:53], off nt
.LBB0_1419:
	s_or_b64 exec, exec, s[8:9]
	v_lshl_add_u64 v[54:55], s[28:29], 2, v[52:53]
	v_mov_b32_e32 v53, 0
	v_mov_b32_e32 v52, 0
	s_and_saveexec_b64 s[8:9], vcc
	s_cbranch_execz .LBB0_1421
	global_load_dword v52, v[54:55], off nt
.LBB0_1421:
	s_or_b64 exec, exec, s[8:9]
	v_lshl_add_u64 v[54:55], s[28:29], 2, v[54:55]
	s_and_saveexec_b64 s[8:9], vcc
	s_cbranch_execz .LBB0_1423
	global_load_dword v53, v[54:55], off nt
.LBB0_1423:
	s_or_b64 exec, exec, s[8:9]
	v_lshl_add_u64 v[56:57], s[28:29], 2, v[54:55]
	v_mov_b32_e32 v55, 0
	v_mov_b32_e32 v54, 0
	s_and_saveexec_b64 s[8:9], vcc
	s_cbranch_execz .LBB0_1425
	global_load_dword v54, v[56:57], off nt
.LBB0_1425:
	s_or_b64 exec, exec, s[8:9]
	v_lshl_add_u64 v[56:57], s[28:29], 2, v[56:57]
	s_and_saveexec_b64 s[8:9], vcc
	s_cbranch_execz .LBB0_1427
	global_load_dword v55, v[56:57], off nt
.LBB0_1427:
	s_or_b64 exec, exec, s[8:9]
	v_lshl_add_u64 v[58:59], s[28:29], 2, v[56:57]
	v_mov_b32_e32 v57, 0
	v_mov_b32_e32 v56, 0
	s_and_saveexec_b64 s[8:9], vcc
	s_cbranch_execz .LBB0_1429
	global_load_dword v56, v[58:59], off nt
.LBB0_1429:
	s_or_b64 exec, exec, s[8:9]
	v_lshl_add_u64 v[58:59], s[28:29], 2, v[58:59]
	s_and_saveexec_b64 s[8:9], vcc
	s_cbranch_execz .LBB0_1431
	global_load_dword v57, v[58:59], off nt
.LBB0_1431:
	s_or_b64 exec, exec, s[8:9]
	v_lshl_add_u64 v[60:61], s[28:29], 2, v[58:59]
	v_mov_b32_e32 v59, 0
	v_mov_b32_e32 v58, 0
	s_and_saveexec_b64 s[8:9], vcc
	s_cbranch_execz .LBB0_1433
	global_load_dword v58, v[60:61], off nt
.LBB0_1433:
	s_or_b64 exec, exec, s[8:9]
	v_lshl_add_u64 v[60:61], s[28:29], 2, v[60:61]
	s_and_saveexec_b64 s[8:9], vcc
	s_cbranch_execz .LBB0_1435
	global_load_dword v59, v[60:61], off nt
.LBB0_1435:
	s_or_b64 exec, exec, s[8:9]
	v_lshl_add_u64 v[62:63], s[28:29], 2, v[60:61]
	v_mov_b32_e32 v61, 0
	v_mov_b32_e32 v60, 0
	s_and_saveexec_b64 s[8:9], vcc
	s_cbranch_execz .LBB0_1437
	global_load_dword v60, v[62:63], off nt
.LBB0_1437:
	s_or_b64 exec, exec, s[8:9]
	v_lshl_add_u64 v[62:63], s[28:29], 2, v[62:63]
	s_and_saveexec_b64 s[8:9], vcc
	s_cbranch_execz .LBB0_1439
	global_load_dword v61, v[62:63], off nt
.LBB0_1439:
	s_or_b64 exec, exec, s[8:9]
	v_lshl_add_u64 v[64:65], s[28:29], 2, v[62:63]
	v_mov_b32_e32 v63, 0
	v_mov_b32_e32 v62, 0
	s_and_saveexec_b64 s[8:9], vcc
	s_cbranch_execz .LBB0_1441
	global_load_dword v62, v[64:65], off nt
.LBB0_1441:
	s_or_b64 exec, exec, s[8:9]
	v_lshl_add_u64 v[64:65], s[28:29], 2, v[64:65]
	s_and_saveexec_b64 s[8:9], vcc
	s_cbranch_execz .LBB0_1443
	global_load_dword v63, v[64:65], off nt
.LBB0_1443:
	s_or_b64 exec, exec, s[8:9]
	v_lshl_add_u64 v[74:75], s[28:29], 2, v[64:65]
	v_mov_b32_e32 v2, 0
	s_and_saveexec_b64 s[8:9], vcc
	s_cbranch_execz .LBB0_1445
	global_load_dword v2, v[74:75], off nt
.LBB0_1445:
	s_or_b64 exec, exec, s[8:9]
	v_mov_b32_e32 v64, v3
	v_mov_b32_e32 v65, v3
	s_waitcnt vmcnt(0)
	v_mov_b64_e32 v[66:67], v[2:3]
	s_and_saveexec_b64 s[8:9], vcc
	s_cbranch_execz .LBB0_1447
	s_lshl_b64 s[14:15], s[28:29], 2
	v_lshl_add_u64 v[64:65], v[74:75], 0, s[14:15]
	v_lshl_add_u64 v[74:75], v[64:65], 0, s[14:15]
	v_lshl_add_u64 v[76:77], v[74:75], 0, s[14:15]
	global_load_dword v67, v[64:65], off nt
	s_nop 0
	global_load_dword v64, v[74:75], off nt
	global_load_dword v65, v[76:77], off nt
	v_mov_b32_e32 v66, v2

; __device__ __forceinline__ void tr_load(const TrItem& t, float (&tv)[32], int lane) {
;     const int nn = t.n0 + (lane & 31); const bool ok = nn < t.N;
;     const float* p = t.W + (size_t)(t.k0 + 32 * (lane >> 5)) * t.N + nn; const size_t st = (size_t)t.N;
; #pragma unroll
;     for (int i = 0; i < 32; ++i) { tv[i] = ok ? *p : 0.f; p += st; }
; }
.LBB0_1486:
	s_andn2_b64 vcc, exec, s[6:7]
	s_cbranch_vccnz .LBB0_1550
	v_add_u32_e32 v1, s38, v68
	v_add_u32_e32 v4, s55, v78
	v_mad_i64_i32 v[6:7], s[14:15], v1, s40, 0
	v_lshl_add_u64 v[6:7], v[6:7], 2, s[30:31]
	v_ashrrev_i32_e32 v5, 31, v4
	v_cmp_le_i32_e32 vcc, s40, v4
	v_cmp_gt_i32_e64 s[6:7], s40, v4
	v_lshl_add_u64 v[6:7], v[4:5], 2, v[6:7]
	v_mov_b32_e32 v5, 0
	v_mov_b32_e32 v4, 0
	s_and_saveexec_b64 s[14:15], s[6:7]
	s_cbranch_execz .LBB0_1489
	global_load_dword v4, v[6:7], off nt
.LBB0_1489:
	s_or_b64 exec, exec, s[14:15]
	s_ashr_i32 s41, s40, 31
	v_lshl_add_u64 v[6:7], s[40:41], 2, v[6:7]
	s_and_saveexec_b64 s[14:15], s[6:7]
	s_cbranch_execz .LBB0_1491
	global_load_dword v5, v[6:7], off nt
.LBB0_1491:
	s_or_b64 exec, exec, s[14:15]
	v_lshl_add_u64 v[8:9], s[40:41], 2, v[6:7]
	v_mov_b32_e32 v7, 0
	v_mov_b32_e32 v6, 0
	s_and_saveexec_b64 s[14:15], s[6:7]
	s_cbranch_execz .LBB0_1493
	global_load_dword v6, v[8:9], off nt
.LBB0_1493:
	s_or_b64 exec, exec, s[14:15]
	v_lshl_add_u64 v[8:9], s[40:41], 2, v[8:9]
	s_and_saveexec_b64 s[14:15], s[6:7]
	s_cbranch_execz .LBB0_1495
	global_load_dword v7, v[8:9], off nt
.LBB0_1495:
	s_or_b64 exec, exec, s[14:15]
	v_lshl_add_u64 v[10:11], s[40:41], 2, v[8:9]
	v_mov_b32_e32 v9, 0
	v_mov_b32_e32 v8, 0
	s_and_saveexec_b64 s[14:15], s[6:7]
	s_cbranch_execz .LBB0_1497
	global_load_dword v8, v[10:11], off nt
.LBB0_1497:
	s_or_b64 exec, exec, s[14:15]
	v_lshl_add_u64 v[10:11], s[40:41], 2, v[10:11]
	s_and_saveexec_b64 s[14:15], s[6:7]
	s_cbranch_execz .LBB0_1499
	global_load_dword v9, v[10:11], off nt
.LBB0_1499:
	s_or_b64 exec, exec, s[14:15]
	v_lshl_add_u64 v[12:13], s[40:41], 2, v[10:11]
	v_mov_b32_e32 v11, 0
	v_mov_b32_e32 v10, 0
	s_and_saveexec_b64 s[14:15], s[6:7]
	s_cbranch_execz .LBB0_1501
	global_load_dword v10, v[12:13], off nt
.LBB0_1501:
	s_or_b64 exec, exec, s[14:15]
	v_lshl_add_u64 v[12:13], s[40:41], 2, v[12:13]
	s_and_saveexec_b64 s[14:15], s[6:7]
	s_cbranch_execz .LBB0_1503
	global_load_dword v11, v[12:13], off nt
.LBB0_1503:
	s_or_b64 exec, exec, s[14:15]
	v_lshl_add_u64 v[14:15], s[40:41], 2, v[12:13]
	v_mov_b32_e32 v13, 0
	v_mov_b32_e32 v12, 0
	s_and_saveexec_b64 s[14:15], s[6:7]
	s_cbranch_execz .LBB0_1505
	global_load_dword v12, v[14:15], off nt
.LBB0_1505:
	s_or_b64 exec, exec, s[14:15]
	v_lshl_add_u64 v[14:15], s[40:41], 2, v[14:15]
	s_and_saveexec_b64 s[14:15], s[6:7]
	s_cbranch_execz .LBB0_1507
	global_load_dword v13, v[14:15], off nt
.LBB0_1507:
	s_or_b64 exec, exec, s[14:15]
	v_lshl_add_u64 v[16:17], s[40:41], 2, v[14:15]
	v_mov_b32_e32 v15, 0
	v_mov_b32_e32 v14, 0
	s_and_saveexec_b64 s[14:15], s[6:7]
	s_cbranch_execz .LBB0_1509
	global_load_dword v14, v[16:17], off nt
.LBB0_1509:
	s_or_b64 exec, exec, s[14:15]
	v_lshl_add_u64 v[16:17], s[40:41], 2, v[16:17]
	s_and_saveexec_b64 s[14:15], s[6:7]
	s_cbranch_execz .LBB0_1511
	global_load_dword v15, v[16:17], off nt
.LBB0_1511:
	s_or_b64 exec, exec, s[14:15]
	v_lshl_add_u64 v[18:19], s[40:41], 2, v[16:17]
	v_mov_b32_e32 v17, 0
	v_mov_b32_e32 v16, 0
	s_and_saveexec_b64 s[14:15], s[6:7]
	s_cbranch_execz .LBB0_1513
	global_load_dword v16, v[18:19], off nt
.LBB0_1513:
	s_or_b64 exec, exec, s[14:15]
	v_lshl_add_u64 v[18:19], s[40:41], 2, v[18:19]
	s_and_saveexec_b64 s[14:15], s[6:7]
	s_cbranch_execz .LBB0_1515
	global_load_dword v17, v[18:19], off nt
.LBB0_1515:
	s_or_b64 exec, exec, s[14:15]
	v_lshl_add_u64 v[20:21], s[40:41], 2, v[18:19]
	v_mov_b32_e32 v19, 0
	v_mov_b32_e32 v18, 0
	s_and_saveexec_b64 s[14:15], s[6:7]
	s_cbranch_execz .LBB0_1517
	global_load_dword v18, v[20:21], off nt
.LBB0_1517:
	s_or_b64 exec, exec, s[14:15]
	v_lshl_add_u64 v[20:21], s[40:41], 2, v[20:21]
	s_and_saveexec_b64 s[14:15], s[6:7]
	s_cbranch_execz .LBB0_1519
	global_load_dword v19, v[20:21], off nt
.LBB0_1519:
	s_or_b64 exec, exec, s[14:15]
	v_lshl_add_u64 v[22:23], s[40:41], 2, v[20:21]
	v_mov_b32_e32 v21, 0
	v_mov_b32_e32 v20, 0
	s_and_saveexec_b64 s[14:15], s[6:7]
	s_cbranch_execz .LBB0_1521
	global_load_dword v20, v[22:23], off nt
.LBB0_1521:
	s_or_b64 exec, exec, s[14:15]
	v_lshl_add_u64 v[22:23], s[40:41], 2, v[22:23]
	s_and_saveexec_b64 s[14:15], s[6:7]
	s_cbranch_execz .LBB0_1523
	global_load_dword v21, v[22:23], off nt
.LBB0_1523:
	s_or_b64 exec, exec, s[14:15]
	v_lshl_add_u64 v[24:25], s[40:41], 2, v[22:23]
	v_mov_b32_e32 v23, 0
	v_mov_b32_e32 v22, 0
	s_and_saveexec_b64 s[14:15], s[6:7]
	s_cbranch_execz .LBB0_1525
	global_load_dword v22, v[24:25], off nt
.LBB0_1525:
	s_or_b64 exec, exec, s[14:15]
	v_lshl_add_u64 v[24:25], s[40:41], 2, v[24:25]
	s_and_saveexec_b64 s[14:15], s[6:7]
	s_cbranch_execz .LBB0_1527
	global_load_dword v23, v[24:25], off nt
.LBB0_1527:
	s_or_b64 exec, exec, s[14:15]
	v_lshl_add_u64 v[26:27], s[40:41], 2, v[24:25]
	v_mov_b32_e32 v25, 0
	v_mov_b32_e32 v24, 0
	s_and_saveexec_b64 s[14:15], s[6:7]
	s_cbranch_execz .LBB0_1529
	global_load_dword v24, v[26:27], off nt
.LBB0_1529:
	s_or_b64 exec, exec, s[14:15]
	v_lshl_add_u64 v[26:27], s[40:41], 2, v[26:27]
	s_and_saveexec_b64 s[14:15], s[6:7]
	s_cbranch_execz .LBB0_1531
	global_load_dword v25, v[26:27], off nt
.LBB0_1531:
	s_or_b64 exec, exec, s[14:15]
	v_lshl_add_u64 v[28:29], s[40:41], 2, v[26:27]
	v_mov_b32_e32 v27, 0
	v_mov_b32_e32 v26, 0
	s_and_saveexec_b64 s[14:15], s[6:7]
	s_cbranch_execz .LBB0_1533
	global_load_dword v26, v[28:29], off nt
.LBB0_1533:
	s_or_b64 exec, exec, s[14:15]
	v_lshl_add_u64 v[28:29], s[40:41], 2, v[28:29]
	s_and_saveexec_b64 s[14:15], s[6:7]
	s_cbranch_execz .LBB0_1535
	global_load_dword v27, v[28:29], off nt
.LBB0_1535:
	s_or_b64 exec, exec, s[14:15]
	v_lshl_add_u64 v[30:31], s[40:41], 2, v[28:29]
	v_mov_b32_e32 v29, 0
	v_mov_b32_e32 v28, 0
	s_and_saveexec_b64 s[14:15], s[6:7]
	s_cbranch_execz .LBB0_1537
	global_load_dword v28, v[30:31], off nt
.LBB0_1537:
	s_or_b64 exec, exec, s[14:15]
	v_lshl_add_u64 v[30:31], s[40:41], 2, v[30:31]
	s_and_saveexec_b64 s[14:15], s[6:7]
	s_cbranch_execz .LBB0_1539
	global_load_dword v29, v[30:31], off nt
.LBB0_1539:
	s_or_b64 exec, exec, s[14:15]
	v_lshl_add_u64 v[32:33], s[40:41], 2, v[30:31]
	v_mov_b32_e32 v31, 0
	v_mov_b32_e32 v30, 0
	s_and_saveexec_b64 s[14:15], s[6:7]
	s_cbranch_execz .LBB0_1541
	global_load_dword v30, v[32:33], off nt
.LBB0_1541:
	s_or_b64 exec, exec, s[14:15]
	v_lshl_add_u64 v[32:33], s[40:41], 2, v[32:33]
	s_and_saveexec_b64 s[14:15], s[6:7]
	s_cbranch_execz .LBB0_1543
	global_load_dword v31, v[32:33], off nt
.LBB0_1543:
	s_or_b64 exec, exec, s[14:15]
	v_lshl_add_u64 v[74:75], s[40:41], 2, v[32:33]
	v_mov_b32_e32 v32, 0
	s_and_saveexec_b64 s[14:15], s[6:7]
	s_cbranch_execz .LBB0_1545
	global_load_dword v32, v[74:75], off nt

; __device__ __forceinline__ void tr_load(const TrItem& t, float (&tv)[32], int lane) {
;     const int nn = t.n0 + (lane & 31); const bool ok = nn < t.N;
;     const float* p = t.W + (size_t)(t.k0 + 32 * (lane >> 5)) * t.N + nn; const size_t st = (size_t)t.N;
; #pragma unroll
;     for (int i = 0; i < 32; ++i) { tv[i] = ok ? *p : 0.f; p += st; }
; }
.LBB0_1971:
	v_cndmask_b32_e64 v1, 0, 1, s[8:9]
	v_cmp_ne_u32_e64 s[6:7], 1, v1
	s_andn2_b64 vcc, exec, s[8:9]
	s_waitcnt vmcnt(0)
	v_and_b32_e32 v59, 31, v72
	v_and_b32_e32 v58, 32, v72
	s_cbranch_vccnz .LBB0_2033
	v_add_u32_e32 v1, s36, v58
	v_add_u32_e32 v6, s51, v59
	v_mad_i64_i32 v[14:15], s[8:9], v1, s38, 0
	v_lshl_add_u64 v[14:15], v[14:15], 2, s[28:29]
	v_ashrrev_i32_e32 v7, 31, v6
	v_cmp_gt_i32_e32 vcc, s38, v6
	v_lshl_add_u64 v[14:15], v[6:7], 2, v[14:15]
	v_mov_b32_e32 v7, 0
	v_mov_b32_e32 v6, 0
	s_and_saveexec_b64 s[8:9], vcc
	s_cbranch_execz .LBB0_1974
	global_load_dword v6, v[14:15], off nt
.LBB0_1974:
	s_or_b64 exec, exec, s[8:9]
	s_ashr_i32 s39, s38, 31
	v_lshl_add_u64 v[14:15], s[38:39], 2, v[14:15]
	s_and_saveexec_b64 s[8:9], vcc
	s_cbranch_execz .LBB0_1976
	global_load_dword v7, v[14:15], off nt
.LBB0_1976:
	s_or_b64 exec, exec, s[8:9]
	v_lshl_add_u64 v[20:21], s[38:39], 2, v[14:15]
	v_mov_b32_e32 v15, 0
	v_mov_b32_e32 v14, 0
	s_and_saveexec_b64 s[8:9], vcc
	s_cbranch_execz .LBB0_1978
	global_load_dword v14, v[20:21], off nt
.LBB0_1978:
	s_or_b64 exec, exec, s[8:9]
	v_lshl_add_u64 v[20:21], s[38:39], 2, v[20:21]
	s_and_saveexec_b64 s[8:9], vcc
	s_cbranch_execz .LBB0_1980
	global_load_dword v15, v[20:21], off nt
.LBB0_1980:
	s_or_b64 exec, exec, s[8:9]
	v_lshl_add_u64 v[26:27], s[38:39], 2, v[20:21]
	v_mov_b32_e32 v21, 0
	v_mov_b32_e32 v20, 0
	s_and_saveexec_b64 s[8:9], vcc
	s_cbranch_execz .LBB0_1982
	global_load_dword v20, v[26:27], off nt
.LBB0_1982:
	s_or_b64 exec, exec, s[8:9]
	v_lshl_add_u64 v[26:27], s[38:39], 2, v[26:27]
	s_and_saveexec_b64 s[8:9], vcc
	s_cbranch_execz .LBB0_1984
	global_load_dword v21, v[26:27], off nt
.LBB0_1984:
	s_or_b64 exec, exec, s[8:9]
	v_lshl_add_u64 v[32:33], s[38:39], 2, v[26:27]
	v_mov_b32_e32 v27, 0
	v_mov_b32_e32 v26, 0
	s_and_saveexec_b64 s[8:9], vcc
	s_cbranch_execz .LBB0_1986
	global_load_dword v26, v[32:33], off nt
.LBB0_1986:
	s_or_b64 exec, exec, s[8:9]
	v_lshl_add_u64 v[32:33], s[38:39], 2, v[32:33]
	s_and_saveexec_b64 s[8:9], vcc
	s_cbranch_execz .LBB0_1988
	global_load_dword v27, v[32:33], off nt
.LBB0_1988:
	s_or_b64 exec, exec, s[8:9]
	v_lshl_add_u64 v[38:39], s[38:39], 2, v[32:33]
	v_mov_b32_e32 v33, 0
	v_mov_b32_e32 v32, 0
	s_and_saveexec_b64 s[8:9], vcc
	s_cbranch_execz .LBB0_1990
	global_load_dword v32, v[38:39], off nt
.LBB0_1990:
	s_or_b64 exec, exec, s[8:9]
	v_lshl_add_u64 v[38:39], s[38:39], 2, v[38:39]
	s_and_saveexec_b64 s[8:9], vcc
	s_cbranch_execz .LBB0_1992
	global_load_dword v33, v[38:39], off nt
.LBB0_1992:
	s_or_b64 exec, exec, s[8:9]
	v_lshl_add_u64 v[44:45], s[38:39], 2, v[38:39]
	v_mov_b32_e32 v39, 0
	v_mov_b32_e32 v38, 0
	s_and_saveexec_b64 s[8:9], vcc
	s_cbranch_execz .LBB0_1994
	global_load_dword v38, v[44:45], off nt
.LBB0_1994:
	s_or_b64 exec, exec, s[8:9]
	v_lshl_add_u64 v[44:45], s[38:39], 2, v[44:45]
	s_and_saveexec_b64 s[8:9], vcc
	s_cbranch_execz .LBB0_1996
	global_load_dword v39, v[44:45], off nt
.LBB0_1996:
	s_or_b64 exec, exec, s[8:9]
	v_lshl_add_u64 v[50:51], s[38:39], 2, v[44:45]
	v_mov_b32_e32 v45, 0
	v_mov_b32_e32 v44, 0
	s_and_saveexec_b64 s[8:9], vcc
	s_cbranch_execz .LBB0_1998
	global_load_dword v44, v[50:51], off nt
.LBB0_1998:
	s_or_b64 exec, exec, s[8:9]
	v_lshl_add_u64 v[50:51], s[38:39], 2, v[50:51]
	s_and_saveexec_b64 s[8:9], vcc
	s_cbranch_execz .LBB0_2000
	global_load_dword v45, v[50:51], off nt
.LBB0_2000:
	s_or_b64 exec, exec, s[8:9]
	v_lshl_add_u64 v[52:53], s[38:39], 2, v[50:51]
	v_mov_b32_e32 v51, 0
	v_mov_b32_e32 v50, 0
	s_and_saveexec_b64 s[8:9], vcc
	s_cbranch_execz .LBB0_2002
	global_load_dword v50, v[52:53], off nt
; __device__ __forceinline__ void tr_load(const TrItem& t, float (&tv)[32], int lane) {
;     const int nn = t.n0 + (lane & 31); const bool ok = nn < t.N;
;     const float* p = t.W + (size_t)(t.k0 + 32 * (lane >> 5)) * t.N + nn; const size_t st = (size_t)t.N;
; #pragma unroll
;     for (int i = 0; i < 32; ++i) { tv[i] = ok ? *p : 0.f; p += st; }
; }
.LBB0_2002:
	s_or_b64 exec, exec, s[8:9]
	v_lshl_add_u64 v[52:53], s[38:39], 2, v[52:53]
	s_and_saveexec_b64 s[8:9], vcc
	s_cbranch_execz .LBB0_2004
	global_load_dword v51, v[52:53], off nt
.LBB0_2004:
	s_or_b64 exec, exec, s[8:9]
	v_lshl_add_u64 v[54:55], s[38:39], 2, v[52:53]
	v_mov_b32_e32 v53, 0
	v_mov_b32_e32 v52, 0
	s_and_saveexec_b64 s[8:9], vcc
	s_cbranch_execz .LBB0_2006
	global_load_dword v52, v[54:55], off nt
.LBB0_2006:
	s_or_b64 exec, exec, s[8:9]
	v_lshl_add_u64 v[54:55], s[38:39], 2, v[54:55]
	s_and_saveexec_b64 s[8:9], vcc
	s_cbranch_execz .LBB0_2008
	global_load_dword v53, v[54:55], off nt
.LBB0_2008:
	s_or_b64 exec, exec, s[8:9]
	v_lshl_add_u64 v[56:57], s[38:39], 2, v[54:55]
	v_mov_b32_e32 v55, 0
	v_mov_b32_e32 v54, 0
	s_and_saveexec_b64 s[8:9], vcc
	s_cbranch_execz .LBB0_2010
	global_load_dword v54, v[56:57], off nt
.LBB0_2010:
	s_or_b64 exec, exec, s[8:9]
	v_lshl_add_u64 v[56:57], s[38:39], 2, v[56:57]
	s_and_saveexec_b64 s[8:9], vcc
	s_cbranch_execz .LBB0_2012
	global_load_dword v55, v[56:57], off nt
.LBB0_2012:
	s_or_b64 exec, exec, s[8:9]
	v_lshl_add_u64 v[60:61], s[38:39], 2, v[56:57]
	v_mov_b32_e32 v57, 0
	v_mov_b32_e32 v56, 0
	s_and_saveexec_b64 s[8:9], vcc
	s_cbranch_execz .LBB0_2014
	global_load_dword v56, v[60:61], off nt
.LBB0_2014:
	s_or_b64 exec, exec, s[8:9]
	v_lshl_add_u64 v[60:61], s[38:39], 2, v[60:61]
	s_and_saveexec_b64 s[8:9], vcc
	s_cbranch_execz .LBB0_2016
	global_load_dword v57, v[60:61], off nt
.LBB0_2016:
	s_or_b64 exec, exec, s[8:9]
	v_lshl_add_u64 v[62:63], s[38:39], 2, v[60:61]
	v_mov_b32_e32 v61, 0
	v_mov_b32_e32 v60, 0
	s_and_saveexec_b64 s[8:9], vcc
	s_cbranch_execz .LBB0_2018
	global_load_dword v60, v[62:63], off nt
.LBB0_2018:
	s_or_b64 exec, exec, s[8:9]
	v_lshl_add_u64 v[62:63], s[38:39], 2, v[62:63]
	s_and_saveexec_b64 s[8:9], vcc
	s_cbranch_execz .LBB0_2020
	global_load_dword v61, v[62:63], off nt
.LBB0_2020:
	s_or_b64 exec, exec, s[8:9]
	v_lshl_add_u64 v[64:65], s[38:39], 2, v[62:63]
	v_mov_b32_e32 v63, 0
	v_mov_b32_e32 v62, 0
	s_and_saveexec_b64 s[8:9], vcc
	s_cbranch_execz .LBB0_2022
	global_load_dword v62, v[64:65], off nt
.LBB0_2022:
	s_or_b64 exec, exec, s[8:9]
	v_lshl_add_u64 v[64:65], s[38:39], 2, v[64:65]
	s_and_saveexec_b64 s[8:9], vcc
	s_cbranch_execz .LBB0_2024
	global_load_dword v63, v[64:65], off nt
.LBB0_2024:
	s_or_b64 exec, exec, s[8:9]
	v_lshl_add_u64 v[66:67], s[38:39], 2, v[64:65]
	v_mov_b32_e32 v65, 0
	v_mov_b32_e32 v64, 0
	s_and_saveexec_b64 s[8:9], vcc
	s_cbranch_execz .LBB0_2026
	global_load_dword v64, v[66:67], off nt
.LBB0_2026:
	s_or_b64 exec, exec, s[8:9]
	v_lshl_add_u64 v[66:67], s[38:39], 2, v[66:67]
	s_and_saveexec_b64 s[8:9], vcc
	s_cbranch_execz .LBB0_2028
	global_load_dword v65, v[66:67], off nt
.LBB0_2028:
	s_or_b64 exec, exec, s[8:9]
	v_lshl_add_u64 v[70:71], s[38:39], 2, v[66:67]
	v_mov_b32_e32 v2, 0
	s_and_saveexec_b64 s[8:9], vcc
	s_cbranch_execz .LBB0_2030
	global_load_dword v2, v[70:71], off nt
.LBB0_2030:
	s_or_b64 exec, exec, s[8:9]
	v_mov_b32_e32 v66, v3
	v_mov_b32_e32 v67, v3
	s_waitcnt vmcnt(0)
	v_mov_b64_e32 v[68:69], v[2:3]
	s_and_saveexec_b64 s[8:9], vcc
	s_cbranch_execz .LBB0_2032
	s_lshl_b64 s[54:55], s[38:39], 2
	v_lshl_add_u64 v[66:67], v[70:71], 0, s[54:55]
	v_lshl_add_u64 v[70:71], v[66:67], 0, s[54:55]
	v_lshl_add_u64 v[74:75], v[70:71], 0, s[54:55]
	global_load_dword v69, v[66:67], off nt
	s_nop 0
	global_load_dword v66, v[70:71], off nt
	global_load_dword v67, v[74:75], off nt
	v_mov_b32_e32 v68, v2

; __device__ __forceinline__ void tr_load(const TrItem& t, float (&tv)[32], int lane) {
;     const int nn = t.n0 + (lane & 31); const bool ok = nn < t.N;
;     const float* p = t.W + (size_t)(t.k0 + 32 * (lane >> 5)) * t.N + nn; const size_t st = (size_t)t.N;
; #pragma unroll
;     for (int i = 0; i < 32; ++i) { tv[i] = ok ? *p : 0.f; p += st; }
; }
.LBB0_2041:
	v_cndmask_b32_e64 v1, 0, 1, s[8:9]
	v_cmp_ne_u32_e64 s[6:7], 1, v1
	s_andn2_b64 vcc, exec, s[8:9]
	s_cbranch_vccnz .LBB0_2103
	v_add_u32_e32 v1, s24, v58
	v_add_u32_e32 v4, s1, v59
	v_mad_i64_i32 v[8:9], s[8:9], v1, s26, 0
	v_lshl_add_u64 v[8:9], v[8:9], 2, s[10:11]
	v_ashrrev_i32_e32 v5, 31, v4
	v_cmp_gt_i32_e32 vcc, s26, v4
	v_lshl_add_u64 v[8:9], v[4:5], 2, v[8:9]
	v_mov_b32_e32 v5, 0
	v_mov_b32_e32 v4, 0
	s_and_saveexec_b64 s[8:9], vcc
	s_cbranch_execz .LBB0_2044
	global_load_dword v4, v[8:9], off nt
.LBB0_2044:
	s_or_b64 exec, exec, s[8:9]
	s_ashr_i32 s27, s26, 31
	v_lshl_add_u64 v[8:9], s[26:27], 2, v[8:9]
	s_and_saveexec_b64 s[8:9], vcc
	s_cbranch_execz .LBB0_2046
	global_load_dword v5, v[8:9], off nt
.LBB0_2046:
	s_or_b64 exec, exec, s[8:9]
	v_lshl_add_u64 v[10:11], s[26:27], 2, v[8:9]
	v_mov_b32_e32 v9, 0
	v_mov_b32_e32 v8, 0
	s_and_saveexec_b64 s[8:9], vcc
	s_cbranch_execz .LBB0_2048
	global_load_dword v8, v[10:11], off nt
.LBB0_2048:
	s_or_b64 exec, exec, s[8:9]
	v_lshl_add_u64 v[10:11], s[26:27], 2, v[10:11]
	s_and_saveexec_b64 s[8:9], vcc
	s_cbranch_execz .LBB0_2050
	global_load_dword v9, v[10:11], off nt
.LBB0_2050:
	s_or_b64 exec, exec, s[8:9]
	v_lshl_add_u64 v[12:13], s[26:27], 2, v[10:11]
	v_mov_b32_e32 v11, 0
	v_mov_b32_e32 v10, 0
	s_and_saveexec_b64 s[8:9], vcc
	s_cbranch_execz .LBB0_2052
	global_load_dword v10, v[12:13], off nt
.LBB0_2052:
	s_or_b64 exec, exec, s[8:9]
	v_lshl_add_u64 v[12:13], s[26:27], 2, v[12:13]
	s_and_saveexec_b64 s[8:9], vcc
	s_cbranch_execz .LBB0_2054
	global_load_dword v11, v[12:13], off nt
.LBB0_2054:
	s_or_b64 exec, exec, s[8:9]
	v_lshl_add_u64 v[16:17], s[26:27], 2, v[12:13]
	v_mov_b32_e32 v13, 0
	v_mov_b32_e32 v12, 0
	s_and_saveexec_b64 s[8:9], vcc
	s_cbranch_execz .LBB0_2056
	global_load_dword v12, v[16:17], off nt
.LBB0_2056:
	s_or_b64 exec, exec, s[8:9]
	v_lshl_add_u64 v[16:17], s[26:27], 2, v[16:17]
	s_and_saveexec_b64 s[8:9], vcc
	s_cbranch_execz .LBB0_2058
	global_load_dword v13, v[16:17], off nt
.LBB0_2058:
	s_or_b64 exec, exec, s[8:9]
	v_lshl_add_u64 v[18:19], s[26:27], 2, v[16:17]
	v_mov_b32_e32 v17, 0
	v_mov_b32_e32 v16, 0
	s_and_saveexec_b64 s[8:9], vcc
	s_cbranch_execz .LBB0_2060
	global_load_dword v16, v[18:19], off nt
.LBB0_2060:
	s_or_b64 exec, exec, s[8:9]
	v_lshl_add_u64 v[18:19], s[26:27], 2, v[18:19]
	s_and_saveexec_b64 s[8:9], vcc
	s_cbranch_execz .LBB0_2062
	global_load_dword v17, v[18:19], off nt
.LBB0_2062:
	s_or_b64 exec, exec, s[8:9]
	v_lshl_add_u64 v[22:23], s[26:27], 2, v[18:19]
	v_mov_b32_e32 v19, 0
	v_mov_b32_e32 v18, 0
	s_and_saveexec_b64 s[8:9], vcc
	s_cbranch_execz .LBB0_2064
	global_load_dword v18, v[22:23], off nt
.LBB0_2064:
	s_or_b64 exec, exec, s[8:9]
	v_lshl_add_u64 v[22:23], s[26:27], 2, v[22:23]
	s_and_saveexec_b64 s[8:9], vcc
	s_cbranch_execz .LBB0_2066
	global_load_dword v19, v[22:23], off nt
.LBB0_2066:
	s_or_b64 exec, exec, s[8:9]
	v_lshl_add_u64 v[24:25], s[26:27], 2, v[22:23]
	v_mov_b32_e32 v23, 0
	v_mov_b32_e32 v22, 0
	s_and_saveexec_b64 s[8:9], vcc
	s_cbranch_execz .LBB0_2068
	global_load_dword v22, v[24:25], off nt
.LBB0_2068:
	s_or_b64 exec, exec, s[8:9]
	v_lshl_add_u64 v[24:25], s[26:27], 2, v[24:25]
	s_and_saveexec_b64 s[8:9], vcc
	s_cbranch_execz .LBB0_2070
	global_load_dword v23, v[24:25], off nt
.LBB0_2070:
	s_or_b64 exec, exec, s[8:9]
	v_lshl_add_u64 v[28:29], s[26:27], 2, v[24:25]
	v_mov_b32_e32 v25, 0
	v_mov_b32_e32 v24, 0
	s_and_saveexec_b64 s[8:9], vcc
	s_cbranch_execz .LBB0_2072
	global_load_dword v24, v[28:29], off nt
.LBB0_2072:
	s_or_b64 exec, exec, s[8:9]
	v_lshl_add_u64 v[28:29], s[26:27], 2, v[28:29]
	s_and_saveexec_b64 s[8:9], vcc
	s_cbranch_execz .LBB0_2074
	global_load_dword v25, v[28:29], off nt
.LBB0_2074:
	s_or_b64 exec, exec, s[8:9]
	v_lshl_add_u64 v[30:31], s[26:27], 2, v[28:29]
	v_mov_b32_e32 v29, 0
	v_mov_b32_e32 v28, 0
	s_and_saveexec_b64 s[8:9], vcc
	s_cbranch_execz .LBB0_2076
	global_load_dword v28, v[30:31], off nt
.LBB0_2076:
	s_or_b64 exec, exec, s[8:9]
	v_lshl_add_u64 v[30:31], s[26:27], 2, v[30:31]
	s_and_saveexec_b64 s[8:9], vcc
	s_cbranch_execz .LBB0_2078
	global_load_dword v29, v[30:31], off nt
.LBB0_2078:
	s_or_b64 exec, exec, s[8:9]
	v_lshl_add_u64 v[34:35], s[26:27], 2, v[30:31]
	v_mov_b32_e32 v31, 0
	v_mov_b32_e32 v30, 0
	s_and_saveexec_b64 s[8:9], vcc
	s_cbranch_execz .LBB0_2080
	global_load_dword v30, v[34:35], off nt
.LBB0_2080:
	s_or_b64 exec, exec, s[8:9]
	v_lshl_add_u64 v[34:35], s[26:27], 2, v[34:35]
	s_and_saveexec_b64 s[8:9], vcc
	s_cbranch_execz .LBB0_2082
	global_load_dword v31, v[34:35], off nt
.LBB0_2082:
	s_or_b64 exec, exec, s[8:9]
	v_lshl_add_u64 v[36:37], s[26:27], 2, v[34:35]
	v_mov_b32_e32 v35, 0
	v_mov_b32_e32 v34, 0
	s_and_saveexec_b64 s[8:9], vcc
	s_cbranch_execz .LBB0_2084
	global_load_dword v34, v[36:37], off nt
.LBB0_2084:
	s_or_b64 exec, exec, s[8:9]
	v_lshl_add_u64 v[36:37], s[26:27], 2, v[36:37]
	s_and_saveexec_b64 s[8:9], vcc
	s_cbranch_execz .LBB0_2086
	global_load_dword v35, v[36:37], off nt
.LBB0_2086:
	s_or_b64 exec, exec, s[8:9]
	v_lshl_add_u64 v[40:41], s[26:27], 2, v[36:37]
	v_mov_b32_e32 v37, 0
	v_mov_b32_e32 v36, 0
	s_and_saveexec_b64 s[8:9], vcc
	s_cbranch_execz .LBB0_2088
	global_load_dword v36, v[40:41], off nt
.LBB0_2088:
	s_or_b64 exec, exec, s[8:9]
	v_lshl_add_u64 v[40:41], s[26:27], 2, v[40:41]
	s_and_saveexec_b64 s[8:9], vcc
	s_cbranch_execz .LBB0_2090
	global_load_dword v37, v[40:41], off nt
.LBB0_2090:
	s_or_b64 exec, exec, s[8:9]
	v_lshl_add_u64 v[42:43], s[26:27], 2, v[40:41]
	v_mov_b32_e32 v41, 0
	v_mov_b32_e32 v40, 0
	s_and_saveexec_b64 s[8:9], vcc
	s_cbranch_execz .LBB0_2092
	global_load_dword v40, v[42:43], off nt
.LBB0_2092:
	s_or_b64 exec, exec, s[8:9]
	v_lshl_add_u64 v[42:43], s[26:27], 2, v[42:43]
	s_and_saveexec_b64 s[8:9], vcc
	s_cbranch_execz .LBB0_2094
	global_load_dword v41, v[42:43], off nt
.LBB0_2094:
	s_or_b64 exec, exec, s[8:9]
	v_lshl_add_u64 v[46:47], s[26:27], 2, v[42:43]
	v_mov_b32_e32 v43, 0
	v_mov_b32_e32 v42, 0
	s_and_saveexec_b64 s[8:9], vcc
	s_cbranch_execz .LBB0_2096
	global_load_dword v42, v[46:47], off nt
.LBB0_2096:
	s_or_b64 exec, exec, s[8:9]
	v_lshl_add_u64 v[46:47], s[26:27], 2, v[46:47]
	s_and_saveexec_b64 s[8:9], vcc
	s_cbranch_execz .LBB0_2098
	global_load_dword v43, v[46:47], off nt
.LBB0_2098:
	s_or_b64 exec, exec, s[8:9]
	v_lshl_add_u64 v[74:75], s[26:27], 2, v[46:47]
	v_mov_b32_e32 v2, 0
	s_and_saveexec_b64 s[8:9], vcc
	s_cbranch_execz .LBB0_2100
	global_load_dword v2, v[74:75], off nt
.LBB0_2100:
	s_or_b64 exec, exec, s[8:9]
	v_mov_b32_e32 v46, v3
	v_mov_b32_e32 v47, v3
	s_waitcnt vmcnt(0)
	v_mov_b64_e32 v[48:49], v[2:3]
	s_and_saveexec_b64 s[8:9], vcc
	s_cbranch_execz .LBB0_2102
	s_lshl_b64 s[14:15], s[26:27], 2
	v_lshl_add_u64 v[46:47], v[74:75], 0, s[14:15]
	v_lshl_add_u64 v[74:75], v[46:47], 0, s[14:15]
	v_lshl_add_u64 v[76:77], v[74:75], 0, s[14:15]
	global_load_dword v49, v[46:47], off nt
	s_nop 0
	global_load_dword v46, v[74:75], off nt
	global_load_dword v47, v[76:77], off nt
	v_mov_b32_e32 v48, v2

; __device__ __forceinline__ void tr_load(const TrItem& t, float (&tv)[32], int lane) {
;     const int nn = t.n0 + (lane & 31); const bool ok = nn < t.N;
;     const float* p = t.W + (size_t)(t.k0 + 32 * (lane >> 5)) * t.N + nn; const size_t st = (size_t)t.N;
; #pragma unroll
;     for (int i = 0; i < 32; ++i) { tv[i] = ok ? *p : 0.f; p += st; }
; }
.LBB0_2141:
	s_andn2_b64 vcc, exec, s[6:7]
	s_cbranch_vccnz .LBB0_2203
	v_add_u32_e32 v1, s36, v58
	v_add_u32_e32 v6, s51, v59
	v_mad_i64_i32 v[14:15], s[6:7], v1, s38, 0
	v_lshl_add_u64 v[14:15], v[14:15], 2, s[28:29]
	v_ashrrev_i32_e32 v7, 31, v6
	v_cmp_gt_i32_e32 vcc, s38, v6
	v_lshl_add_u64 v[14:15], v[6:7], 2, v[14:15]
	v_mov_b32_e32 v7, 0
	v_mov_b32_e32 v6, 0
	s_and_saveexec_b64 s[6:7], vcc
	s_cbranch_execz .LBB0_2144
	global_load_dword v6, v[14:15], off nt
.LBB0_2144:
	s_or_b64 exec, exec, s[6:7]
	s_ashr_i32 s39, s38, 31
	v_lshl_add_u64 v[14:15], s[38:39], 2, v[14:15]
	s_and_saveexec_b64 s[6:7], vcc
	s_cbranch_execz .LBB0_2146
	global_load_dword v7, v[14:15], off nt
.LBB0_2146:
	s_or_b64 exec, exec, s[6:7]
	v_lshl_add_u64 v[20:21], s[38:39], 2, v[14:15]
	v_mov_b32_e32 v15, 0
	v_mov_b32_e32 v14, 0
	s_and_saveexec_b64 s[6:7], vcc
	s_cbranch_execz .LBB0_2148
	global_load_dword v14, v[20:21], off nt
.LBB0_2148:
	s_or_b64 exec, exec, s[6:7]
	v_lshl_add_u64 v[20:21], s[38:39], 2, v[20:21]
	s_and_saveexec_b64 s[6:7], vcc
	s_cbranch_execz .LBB0_2150
	global_load_dword v15, v[20:21], off nt
.LBB0_2150:
	s_or_b64 exec, exec, s[6:7]
	v_lshl_add_u64 v[26:27], s[38:39], 2, v[20:21]
	v_mov_b32_e32 v21, 0
	v_mov_b32_e32 v20, 0
	s_and_saveexec_b64 s[6:7], vcc
	s_cbranch_execz .LBB0_2152
	global_load_dword v20, v[26:27], off nt
.LBB0_2152:
	s_or_b64 exec, exec, s[6:7]
	v_lshl_add_u64 v[26:27], s[38:39], 2, v[26:27]
	s_and_saveexec_b64 s[6:7], vcc
	s_cbranch_execz .LBB0_2154
	global_load_dword v21, v[26:27], off nt
.LBB0_2154:
	s_or_b64 exec, exec, s[6:7]
	v_lshl_add_u64 v[32:33], s[38:39], 2, v[26:27]
	v_mov_b32_e32 v27, 0
	v_mov_b32_e32 v26, 0
	s_and_saveexec_b64 s[6:7], vcc
	s_cbranch_execz .LBB0_2156
	global_load_dword v26, v[32:33], off nt
.LBB0_2156:
	s_or_b64 exec, exec, s[6:7]
	v_lshl_add_u64 v[32:33], s[38:39], 2, v[32:33]
	s_and_saveexec_b64 s[6:7], vcc
	s_cbranch_execz .LBB0_2158
	global_load_dword v27, v[32:33], off nt
.LBB0_2158:
	s_or_b64 exec, exec, s[6:7]
	v_lshl_add_u64 v[38:39], s[38:39], 2, v[32:33]
	v_mov_b32_e32 v33, 0
	v_mov_b32_e32 v32, 0
	s_and_saveexec_b64 s[6:7], vcc
	s_cbranch_execz .LBB0_2160
	global_load_dword v32, v[38:39], off nt
.LBB0_2160:
	s_or_b64 exec, exec, s[6:7]
	v_lshl_add_u64 v[38:39], s[38:39], 2, v[38:39]
	s_and_saveexec_b64 s[6:7], vcc
	s_cbranch_execz .LBB0_2162
	global_load_dword v33, v[38:39], off nt
.LBB0_2162:
	s_or_b64 exec, exec, s[6:7]
	v_lshl_add_u64 v[44:45], s[38:39], 2, v[38:39]
	v_mov_b32_e32 v39, 0
	v_mov_b32_e32 v38, 0
	s_and_saveexec_b64 s[6:7], vcc
	s_cbranch_execz .LBB0_2164
	global_load_dword v38, v[44:45], off nt
.LBB0_2164:
	s_or_b64 exec, exec, s[6:7]
	v_lshl_add_u64 v[44:45], s[38:39], 2, v[44:45]
	s_and_saveexec_b64 s[6:7], vcc
	s_cbranch_execz .LBB0_2166
	global_load_dword v39, v[44:45], off nt
.LBB0_2166:
	s_or_b64 exec, exec, s[6:7]
	v_lshl_add_u64 v[50:51], s[38:39], 2, v[44:45]
	v_mov_b32_e32 v45, 0
	v_mov_b32_e32 v44, 0
	s_and_saveexec_b64 s[6:7], vcc
	s_cbranch_execz .LBB0_2168
	global_load_dword v44, v[50:51], off nt
.LBB0_2168:
	s_or_b64 exec, exec, s[6:7]
	v_lshl_add_u64 v[50:51], s[38:39], 2, v[50:51]
	s_and_saveexec_b64 s[6:7], vcc
	s_cbranch_execz .LBB0_2170
	global_load_dword v45, v[50:51], off nt
.LBB0_2170:
	s_or_b64 exec, exec, s[6:7]
	v_lshl_add_u64 v[52:53], s[38:39], 2, v[50:51]
	v_mov_b32_e32 v51, 0
	v_mov_b32_e32 v50, 0
	s_and_saveexec_b64 s[6:7], vcc
	s_cbranch_execz .LBB0_2172
	global_load_dword v50, v[52:53], off nt
.LBB0_2172:
	s_or_b64 exec, exec, s[6:7]
	v_lshl_add_u64 v[52:53], s[38:39], 2, v[52:53]
	s_and_saveexec_b64 s[6:7], vcc
	s_cbranch_execz .LBB0_2174
	global_load_dword v51, v[52:53], off nt
.LBB0_2174:
	s_or_b64 exec, exec, s[6:7]
	v_lshl_add_u64 v[54:55], s[38:39], 2, v[52:53]
	v_mov_b32_e32 v53, 0
	v_mov_b32_e32 v52, 0
	s_and_saveexec_b64 s[6:7], vcc
	s_cbranch_execz .LBB0_2176
	global_load_dword v52, v[54:55], off nt
.LBB0_2176:
	s_or_b64 exec, exec, s[6:7]
	v_lshl_add_u64 v[54:55], s[38:39], 2, v[54:55]
	s_and_saveexec_b64 s[6:7], vcc
	s_cbranch_execz .LBB0_2178
	global_load_dword v53, v[54:55], off nt
.LBB0_2178:
	s_or_b64 exec, exec, s[6:7]
	v_lshl_add_u64 v[56:57], s[38:39], 2, v[54:55]
	v_mov_b32_e32 v55, 0
	v_mov_b32_e32 v54, 0
	s_and_saveexec_b64 s[6:7], vcc
	s_cbranch_execz .LBB0_2180
	global_load_dword v54, v[56:57], off nt
.LBB0_2180:
	s_or_b64 exec, exec, s[6:7]
	v_lshl_add_u64 v[56:57], s[38:39], 2, v[56:57]
	s_and_saveexec_b64 s[6:7], vcc
	s_cbranch_execz .LBB0_2182
	global_load_dword v55, v[56:57], off nt
.LBB0_2182:
	s_or_b64 exec, exec, s[6:7]
	v_lshl_add_u64 v[60:61], s[38:39], 2, v[56:57]
	v_mov_b32_e32 v57, 0
	v_mov_b32_e32 v56, 0
	s_and_saveexec_b64 s[6:7], vcc
	s_cbranch_execz .LBB0_2184
	global_load_dword v56, v[60:61], off nt
.LBB0_2184:
	s_or_b64 exec, exec, s[6:7]
	v_lshl_add_u64 v[60:61], s[38:39], 2, v[60:61]
	s_and_saveexec_b64 s[6:7], vcc
	s_cbranch_execz .LBB0_2186
	global_load_dword v57, v[60:61], off nt
.LBB0_2186:
	s_or_b64 exec, exec, s[6:7]
	v_lshl_add_u64 v[62:63], s[38:39], 2, v[60:61]
	v_mov_b32_e32 v61, 0
	v_mov_b32_e32 v60, 0
	s_and_saveexec_b64 s[6:7], vcc
	s_cbranch_execz .LBB0_2188
	global_load_dword v60, v[62:63], off nt
.LBB0_2188:
	s_or_b64 exec, exec, s[6:7]
	v_lshl_add_u64 v[62:63], s[38:39], 2, v[62:63]
	s_and_saveexec_b64 s[6:7], vcc
	s_cbranch_execz .LBB0_2190
	global_load_dword v61, v[62:63], off nt
.LBB0_2190:
	s_or_b64 exec, exec, s[6:7]
	v_lshl_add_u64 v[64:65], s[38:39], 2, v[62:63]
	v_mov_b32_e32 v63, 0
	v_mov_b32_e32 v62, 0
	s_and_saveexec_b64 s[6:7], vcc
	s_cbranch_execz .LBB0_2192
	global_load_dword v62, v[64:65], off nt
.LBB0_2192:
	s_or_b64 exec, exec, s[6:7]
	v_lshl_add_u64 v[64:65], s[38:39], 2, v[64:65]
	s_and_saveexec_b64 s[6:7], vcc
	s_cbranch_execz .LBB0_2194
	global_load_dword v63, v[64:65], off nt
.LBB0_2194:
	s_or_b64 exec, exec, s[6:7]
	v_lshl_add_u64 v[66:67], s[38:39], 2, v[64:65]
	v_mov_b32_e32 v65, 0
	v_mov_b32_e32 v64, 0
	s_and_saveexec_b64 s[6:7], vcc
	s_cbranch_execz .LBB0_2196
	global_load_dword v64, v[66:67], off nt
.LBB0_2196:
	s_or_b64 exec, exec, s[6:7]
	v_lshl_add_u64 v[66:67], s[38:39], 2, v[66:67]
	s_and_saveexec_b64 s[6:7], vcc
	s_cbranch_execz .LBB0_2198
	global_load_dword v65, v[66:67], off nt
.LBB0_2198:
	s_or_b64 exec, exec, s[6:7]
	v_lshl_add_u64 v[74:75], s[38:39], 2, v[66:67]
	v_mov_b32_e32 v2, 0
	s_and_saveexec_b64 s[6:7], vcc
	s_cbranch_execz .LBB0_2200
	global_load_dword v2, v[74:75], off nt

; __device__ __forceinline__ void tr_load(const TrItem& t, float (&tv)[32], int lane) {
;     const int nn = t.n0 + (lane & 31); const bool ok = nn < t.N;
;     const float* p = t.W + (size_t)(t.k0 + 32 * (lane >> 5)) * t.N + nn; const size_t st = (size_t)t.N;
; #pragma unroll
;     for (int i = 0; i < 32; ++i) { tv[i] = ok ? *p : 0.f; p += st; }
; }
.LBB0_2808:
	v_cndmask_b32_e64 v4, 0, 1, s[10:11]
	v_cmp_ne_u32_e64 s[8:9], 1, v4
	s_andn2_b64 vcc, exec, s[10:11]
	s_cbranch_vccnz .LBB0_2870
	v_add_u32_e32 v4, s48, v2
	s_waitcnt vmcnt(4)
	v_add_u32_e32 v10, s66, v1
	v_mad_i64_i32 v[18:19], s[10:11], v4, s52, 0
	v_lshl_add_u64 v[18:19], v[18:19], 2, s[38:39]
	v_ashrrev_i32_e32 v11, 31, v10
	v_cmp_gt_i32_e32 vcc, s52, v10
	v_lshl_add_u64 v[18:19], v[10:11], 2, v[18:19]
	v_mov_b32_e32 v11, 0
	v_mov_b32_e32 v10, 0
	s_and_saveexec_b64 s[10:11], vcc
	s_cbranch_execz .LBB0_2811
	global_load_dword v10, v[18:19], off nt
.LBB0_2811:
	s_or_b64 exec, exec, s[10:11]
	s_ashr_i32 s53, s52, 31
	v_lshl_add_u64 v[18:19], s[52:53], 2, v[18:19]
	s_and_saveexec_b64 s[10:11], vcc
	s_cbranch_execz .LBB0_2813
	global_load_dword v11, v[18:19], off nt
.LBB0_2813:
	s_or_b64 exec, exec, s[10:11]
	v_lshl_add_u64 v[24:25], s[52:53], 2, v[18:19]
	v_mov_b32_e32 v19, 0
	v_mov_b32_e32 v18, 0
	s_and_saveexec_b64 s[10:11], vcc
	s_cbranch_execz .LBB0_2815
	global_load_dword v18, v[24:25], off nt
.LBB0_2815:
	s_or_b64 exec, exec, s[10:11]
	v_lshl_add_u64 v[24:25], s[52:53], 2, v[24:25]
	s_and_saveexec_b64 s[10:11], vcc
	s_cbranch_execz .LBB0_2817
	global_load_dword v19, v[24:25], off nt
.LBB0_2817:
	s_or_b64 exec, exec, s[10:11]
	v_lshl_add_u64 v[30:31], s[52:53], 2, v[24:25]
	v_mov_b32_e32 v25, 0
	v_mov_b32_e32 v24, 0
	s_and_saveexec_b64 s[10:11], vcc
	s_cbranch_execz .LBB0_2819
	global_load_dword v24, v[30:31], off nt
.LBB0_2819:
	s_or_b64 exec, exec, s[10:11]
	v_lshl_add_u64 v[30:31], s[52:53], 2, v[30:31]
	s_and_saveexec_b64 s[10:11], vcc
	s_cbranch_execz .LBB0_2821
	global_load_dword v25, v[30:31], off nt
.LBB0_2821:
	s_or_b64 exec, exec, s[10:11]
	v_lshl_add_u64 v[36:37], s[52:53], 2, v[30:31]
	v_mov_b32_e32 v31, 0
	v_mov_b32_e32 v30, 0
	s_and_saveexec_b64 s[10:11], vcc
	s_cbranch_execz .LBB0_2823
	global_load_dword v30, v[36:37], off nt
.LBB0_2823:
	s_or_b64 exec, exec, s[10:11]
	v_lshl_add_u64 v[36:37], s[52:53], 2, v[36:37]
	s_and_saveexec_b64 s[10:11], vcc
	s_cbranch_execz .LBB0_2825
	global_load_dword v31, v[36:37], off nt
.LBB0_2825:
	s_or_b64 exec, exec, s[10:11]
	v_lshl_add_u64 v[42:43], s[52:53], 2, v[36:37]
	v_mov_b32_e32 v37, 0
	v_mov_b32_e32 v36, 0
	s_and_saveexec_b64 s[10:11], vcc
	s_cbranch_execz .LBB0_2827
	global_load_dword v36, v[42:43], off nt
.LBB0_2827:
	s_or_b64 exec, exec, s[10:11]
	v_lshl_add_u64 v[42:43], s[52:53], 2, v[42:43]
	s_and_saveexec_b64 s[10:11], vcc
	s_cbranch_execz .LBB0_2829
	global_load_dword v37, v[42:43], off nt
.LBB0_2829:
	s_or_b64 exec, exec, s[10:11]
	v_lshl_add_u64 v[48:49], s[52:53], 2, v[42:43]
	v_mov_b32_e32 v43, 0
	v_mov_b32_e32 v42, 0
	s_and_saveexec_b64 s[10:11], vcc
	s_cbranch_execz .LBB0_2831
	global_load_dword v42, v[48:49], off nt
.LBB0_2831:
	s_or_b64 exec, exec, s[10:11]
	v_lshl_add_u64 v[48:49], s[52:53], 2, v[48:49]
	s_and_saveexec_b64 s[10:11], vcc
	s_cbranch_execz .LBB0_2833
	global_load_dword v43, v[48:49], off nt
.LBB0_2833:
	s_or_b64 exec, exec, s[10:11]
	v_lshl_add_u64 v[54:55], s[52:53], 2, v[48:49]
	v_mov_b32_e32 v49, 0
	v_mov_b32_e32 v48, 0
	s_and_saveexec_b64 s[10:11], vcc
	s_cbranch_execz .LBB0_2835
	global_load_dword v48, v[54:55], off nt
.LBB0_2835:
	s_or_b64 exec, exec, s[10:11]
	v_lshl_add_u64 v[54:55], s[52:53], 2, v[54:55]
	s_and_saveexec_b64 s[10:11], vcc
	s_cbranch_execz .LBB0_2837
	global_load_dword v49, v[54:55], off nt
.LBB0_2837:
	s_or_b64 exec, exec, s[10:11]
	v_lshl_add_u64 v[56:57], s[52:53], 2, v[54:55]
	v_mov_b32_e32 v55, 0
	v_mov_b32_e32 v54, 0
	s_and_saveexec_b64 s[10:11], vcc
	s_cbranch_execz .LBB0_2839
	global_load_dword v54, v[56:57], off nt
; __device__ __forceinline__ void tr_load(const TrItem& t, float (&tv)[32], int lane) {
;     const int nn = t.n0 + (lane & 31); const bool ok = nn < t.N;
;     const float* p = t.W + (size_t)(t.k0 + 32 * (lane >> 5)) * t.N + nn; const size_t st = (size_t)t.N;
; #pragma unroll
;     for (int i = 0; i < 32; ++i) { tv[i] = ok ? *p : 0.f; p += st; }
; }
.LBB0_2839:
	s_or_b64 exec, exec, s[10:11]
	v_lshl_add_u64 v[56:57], s[52:53], 2, v[56:57]
	s_and_saveexec_b64 s[10:11], vcc
	s_cbranch_execz .LBB0_2841
	global_load_dword v55, v[56:57], off nt
.LBB0_2841:
	s_or_b64 exec, exec, s[10:11]
	v_lshl_add_u64 v[58:59], s[52:53], 2, v[56:57]
	v_mov_b32_e32 v57, 0
	v_mov_b32_e32 v56, 0
	s_and_saveexec_b64 s[10:11], vcc
	s_cbranch_execz .LBB0_2843
	global_load_dword v56, v[58:59], off nt
.LBB0_2843:
	s_or_b64 exec, exec, s[10:11]
	v_lshl_add_u64 v[58:59], s[52:53], 2, v[58:59]
	s_and_saveexec_b64 s[10:11], vcc
	s_cbranch_execz .LBB0_2845
	global_load_dword v57, v[58:59], off nt
.LBB0_2845:
	s_or_b64 exec, exec, s[10:11]
	v_lshl_add_u64 v[60:61], s[52:53], 2, v[58:59]
	v_mov_b32_e32 v59, 0
	v_mov_b32_e32 v58, 0
	s_and_saveexec_b64 s[10:11], vcc
	s_cbranch_execz .LBB0_2847
	global_load_dword v58, v[60:61], off nt
.LBB0_2847:
	s_or_b64 exec, exec, s[10:11]
	v_lshl_add_u64 v[60:61], s[52:53], 2, v[60:61]
	s_and_saveexec_b64 s[10:11], vcc
	s_cbranch_execz .LBB0_2849
	global_load_dword v59, v[60:61], off nt
.LBB0_2849:
	s_or_b64 exec, exec, s[10:11]
	v_lshl_add_u64 v[62:63], s[52:53], 2, v[60:61]
	v_mov_b32_e32 v61, 0
	v_mov_b32_e32 v60, 0
	s_and_saveexec_b64 s[10:11], vcc
	s_cbranch_execz .LBB0_2851
	global_load_dword v60, v[62:63], off nt
.LBB0_2851:
	s_or_b64 exec, exec, s[10:11]
	v_lshl_add_u64 v[62:63], s[52:53], 2, v[62:63]
	s_and_saveexec_b64 s[10:11], vcc
	s_cbranch_execz .LBB0_2853
	global_load_dword v61, v[62:63], off nt
.LBB0_2853:
	s_or_b64 exec, exec, s[10:11]
	v_lshl_add_u64 v[64:65], s[52:53], 2, v[62:63]
	v_mov_b32_e32 v63, 0
	v_mov_b32_e32 v62, 0
	s_and_saveexec_b64 s[10:11], vcc
	s_cbranch_execz .LBB0_2855
	global_load_dword v62, v[64:65], off nt
.LBB0_2855:
	s_or_b64 exec, exec, s[10:11]
	v_lshl_add_u64 v[64:65], s[52:53], 2, v[64:65]
	s_and_saveexec_b64 s[10:11], vcc
	s_cbranch_execz .LBB0_2857
	global_load_dword v63, v[64:65], off nt
.LBB0_2857:
	s_or_b64 exec, exec, s[10:11]
	v_lshl_add_u64 v[66:67], s[52:53], 2, v[64:65]
	v_mov_b32_e32 v65, 0
	v_mov_b32_e32 v64, 0
	s_and_saveexec_b64 s[10:11], vcc
	s_cbranch_execz .LBB0_2859
	global_load_dword v64, v[66:67], off nt
.LBB0_2859:
	s_or_b64 exec, exec, s[10:11]
	v_lshl_add_u64 v[66:67], s[52:53], 2, v[66:67]
	s_and_saveexec_b64 s[10:11], vcc
	s_cbranch_execz .LBB0_2861
	global_load_dword v65, v[66:67], off nt
.LBB0_2861:
	s_or_b64 exec, exec, s[10:11]
	s_waitcnt vmcnt(2)
	v_lshl_add_u64 v[68:69], s[52:53], 2, v[66:67]
	v_mov_b32_e32 v67, 0
	v_mov_b32_e32 v66, 0
	s_and_saveexec_b64 s[10:11], vcc
	s_cbranch_execz .LBB0_2863
	global_load_dword v66, v[68:69], off nt
.LBB0_2863:
	s_or_b64 exec, exec, s[10:11]
	v_lshl_add_u64 v[68:69], s[52:53], 2, v[68:69]
	s_and_saveexec_b64 s[10:11], vcc
	s_cbranch_execz .LBB0_2865
	global_load_dword v67, v[68:69], off nt
.LBB0_2865:
	s_or_b64 exec, exec, s[10:11]
	v_lshl_add_u64 v[72:73], s[52:53], 2, v[68:69]
	v_mov_b32_e32 v4, 0
	s_and_saveexec_b64 s[10:11], vcc
	s_cbranch_execz .LBB0_2867
	global_load_dword v4, v[72:73], off nt
.LBB0_2867:
	s_or_b64 exec, exec, s[10:11]
	s_waitcnt vmcnt(1)
	v_mov_b32_e32 v70, v5
	s_waitcnt vmcnt(0)
	v_mov_b32_e32 v71, v5
	s_waitcnt vmcnt(0)
	v_mov_b64_e32 v[68:69], v[4:5]
	s_and_saveexec_b64 s[10:11], vcc
	s_cbranch_execz .LBB0_2869
	s_lshl_b64 s[64:65], s[52:53], 2
	v_lshl_add_u64 v[68:69], v[72:73], 0, s[64:65]
	v_lshl_add_u64 v[70:71], v[68:69], 0, s[64:65]
	v_lshl_add_u64 v[72:73], v[70:71], 0, s[64:65]
	global_load_dword v69, v[68:69], off nt
	s_nop 0
	global_load_dword v70, v[70:71], off nt
	s_nop 0
	global_load_dword v71, v[72:73], off nt
	v_mov_b32_e32 v68, v4

; __device__ __forceinline__ void tr_load(const TrItem& t, float (&tv)[32], int lane) {
;     const int nn = t.n0 + (lane & 31); const bool ok = nn < t.N;
;     const float* p = t.W + (size_t)(t.k0 + 32 * (lane >> 5)) * t.N + nn; const size_t st = (size_t)t.N;
; #pragma unroll
;     for (int i = 0; i < 32; ++i) { tv[i] = ok ? *p : 0.f; p += st; }
; }
.LBB0_2880:
	v_cndmask_b32_e64 v4, 0, 1, s[10:11]
	v_cmp_ne_u32_e64 s[8:9], 1, v4
	s_andn2_b64 vcc, exec, s[10:11]
	s_cbranch_vccnz .LBB0_2942
	v_add_u32_e32 v4, s40, v2
	v_add_u32_e32 v8, s61, v1
	v_mad_i64_i32 v[12:13], s[10:11], v4, s46, 0
	v_lshl_add_u64 v[12:13], v[12:13], 2, s[14:15]
	v_ashrrev_i32_e32 v9, 31, v8
	v_cmp_gt_i32_e32 vcc, s46, v8
	v_lshl_add_u64 v[12:13], v[8:9], 2, v[12:13]
	v_mov_b32_e32 v9, 0
	v_mov_b32_e32 v8, 0
	s_and_saveexec_b64 s[10:11], vcc
	s_cbranch_execz .LBB0_2883
	global_load_dword v8, v[12:13], off nt
.LBB0_2883:
	s_or_b64 exec, exec, s[10:11]
	s_ashr_i32 s47, s46, 31
	v_lshl_add_u64 v[12:13], s[46:47], 2, v[12:13]
	s_and_saveexec_b64 s[10:11], vcc
	s_cbranch_execz .LBB0_2885
	global_load_dword v9, v[12:13], off nt
.LBB0_2885:
	s_or_b64 exec, exec, s[10:11]
	v_lshl_add_u64 v[14:15], s[46:47], 2, v[12:13]
	v_mov_b32_e32 v13, 0
	v_mov_b32_e32 v12, 0
	s_and_saveexec_b64 s[10:11], vcc
	s_cbranch_execz .LBB0_2887
	global_load_dword v12, v[14:15], off nt
.LBB0_2887:
	s_or_b64 exec, exec, s[10:11]
	v_lshl_add_u64 v[14:15], s[46:47], 2, v[14:15]
	s_and_saveexec_b64 s[10:11], vcc
	s_cbranch_execz .LBB0_2889
	global_load_dword v13, v[14:15], off nt
.LBB0_2889:
	s_or_b64 exec, exec, s[10:11]
	v_lshl_add_u64 v[16:17], s[46:47], 2, v[14:15]
	v_mov_b32_e32 v15, 0
	v_mov_b32_e32 v14, 0
	s_and_saveexec_b64 s[10:11], vcc
	s_cbranch_execz .LBB0_2891
	global_load_dword v14, v[16:17], off nt
.LBB0_2891:
	s_or_b64 exec, exec, s[10:11]
	v_lshl_add_u64 v[16:17], s[46:47], 2, v[16:17]
	s_and_saveexec_b64 s[10:11], vcc
	s_cbranch_execz .LBB0_2893
	global_load_dword v15, v[16:17], off nt
.LBB0_2893:
	s_or_b64 exec, exec, s[10:11]
	v_lshl_add_u64 v[20:21], s[46:47], 2, v[16:17]
	v_mov_b32_e32 v17, 0
	v_mov_b32_e32 v16, 0
	s_and_saveexec_b64 s[10:11], vcc
	s_cbranch_execz .LBB0_2895
	global_load_dword v16, v[20:21], off nt
.LBB0_2895:
	s_or_b64 exec, exec, s[10:11]
	v_lshl_add_u64 v[20:21], s[46:47], 2, v[20:21]
	s_and_saveexec_b64 s[10:11], vcc
	s_cbranch_execz .LBB0_2897
	global_load_dword v17, v[20:21], off nt
.LBB0_2897:
	s_or_b64 exec, exec, s[10:11]
	v_lshl_add_u64 v[22:23], s[46:47], 2, v[20:21]
	v_mov_b32_e32 v21, 0
	v_mov_b32_e32 v20, 0
	s_and_saveexec_b64 s[10:11], vcc
	s_cbranch_execz .LBB0_2899
	global_load_dword v20, v[22:23], off nt
.LBB0_2899:
	s_or_b64 exec, exec, s[10:11]
	v_lshl_add_u64 v[22:23], s[46:47], 2, v[22:23]
	s_and_saveexec_b64 s[10:11], vcc
	s_cbranch_execz .LBB0_2901
	global_load_dword v21, v[22:23], off nt
.LBB0_2901:
	s_or_b64 exec, exec, s[10:11]
	v_lshl_add_u64 v[26:27], s[46:47], 2, v[22:23]
	v_mov_b32_e32 v23, 0
	v_mov_b32_e32 v22, 0
	s_and_saveexec_b64 s[10:11], vcc
	s_cbranch_execz .LBB0_2903
	global_load_dword v22, v[26:27], off nt
.LBB0_2903:
	s_or_b64 exec, exec, s[10:11]
	v_lshl_add_u64 v[26:27], s[46:47], 2, v[26:27]
	s_and_saveexec_b64 s[10:11], vcc
	s_cbranch_execz .LBB0_2905
	global_load_dword v23, v[26:27], off nt
.LBB0_2905:
	s_or_b64 exec, exec, s[10:11]
	v_lshl_add_u64 v[28:29], s[46:47], 2, v[26:27]
	v_mov_b32_e32 v27, 0
	v_mov_b32_e32 v26, 0
	s_and_saveexec_b64 s[10:11], vcc
	s_cbranch_execz .LBB0_2907
	global_load_dword v26, v[28:29], off nt
.LBB0_2907:
	s_or_b64 exec, exec, s[10:11]
	v_lshl_add_u64 v[28:29], s[46:47], 2, v[28:29]
	s_and_saveexec_b64 s[10:11], vcc
	s_cbranch_execz .LBB0_2909
	global_load_dword v27, v[28:29], off nt
.LBB0_2909:
	s_or_b64 exec, exec, s[10:11]
	v_lshl_add_u64 v[32:33], s[46:47], 2, v[28:29]
	v_mov_b32_e32 v29, 0
	v_mov_b32_e32 v28, 0
	s_and_saveexec_b64 s[10:11], vcc
	s_cbranch_execz .LBB0_2911
	global_load_dword v28, v[32:33], off nt
; __device__ __forceinline__ void tr_load(const TrItem& t, float (&tv)[32], int lane) {
;     const int nn = t.n0 + (lane & 31); const bool ok = nn < t.N;
;     const float* p = t.W + (size_t)(t.k0 + 32 * (lane >> 5)) * t.N + nn; const size_t st = (size_t)t.N;
; #pragma unroll
;     for (int i = 0; i < 32; ++i) { tv[i] = ok ? *p : 0.f; p += st; }
; }
.LBB0_2911:
	s_or_b64 exec, exec, s[10:11]
	v_lshl_add_u64 v[32:33], s[46:47], 2, v[32:33]
	s_and_saveexec_b64 s[10:11], vcc
	s_cbranch_execz .LBB0_2913
	global_load_dword v29, v[32:33], off nt
.LBB0_2913:
	s_or_b64 exec, exec, s[10:11]
	v_lshl_add_u64 v[34:35], s[46:47], 2, v[32:33]
	v_mov_b32_e32 v33, 0
	v_mov_b32_e32 v32, 0
	s_and_saveexec_b64 s[10:11], vcc
	s_cbranch_execz .LBB0_2915
	global_load_dword v32, v[34:35], off nt
.LBB0_2915:
	s_or_b64 exec, exec, s[10:11]
	v_lshl_add_u64 v[34:35], s[46:47], 2, v[34:35]
	s_and_saveexec_b64 s[10:11], vcc
	s_cbranch_execz .LBB0_2917
	global_load_dword v33, v[34:35], off nt
.LBB0_2917:
	s_or_b64 exec, exec, s[10:11]
	v_lshl_add_u64 v[38:39], s[46:47], 2, v[34:35]
	v_mov_b32_e32 v35, 0
	v_mov_b32_e32 v34, 0
	s_and_saveexec_b64 s[10:11], vcc
	s_cbranch_execz .LBB0_2919
	global_load_dword v34, v[38:39], off nt
.LBB0_2919:
	s_or_b64 exec, exec, s[10:11]
	v_lshl_add_u64 v[38:39], s[46:47], 2, v[38:39]
	s_and_saveexec_b64 s[10:11], vcc
	s_cbranch_execz .LBB0_2921
	global_load_dword v35, v[38:39], off nt
.LBB0_2921:
	s_or_b64 exec, exec, s[10:11]
	v_lshl_add_u64 v[40:41], s[46:47], 2, v[38:39]
	v_mov_b32_e32 v39, 0
	v_mov_b32_e32 v38, 0
	s_and_saveexec_b64 s[10:11], vcc
	s_cbranch_execz .LBB0_2923
	global_load_dword v38, v[40:41], off nt
.LBB0_2923:
	s_or_b64 exec, exec, s[10:11]
	v_lshl_add_u64 v[40:41], s[46:47], 2, v[40:41]
	s_and_saveexec_b64 s[10:11], vcc
	s_cbranch_execz .LBB0_2925
	global_load_dword v39, v[40:41], off nt
.LBB0_2925:
	s_or_b64 exec, exec, s[10:11]
	v_lshl_add_u64 v[44:45], s[46:47], 2, v[40:41]
	v_mov_b32_e32 v41, 0
	v_mov_b32_e32 v40, 0
	s_and_saveexec_b64 s[10:11], vcc
	s_cbranch_execz .LBB0_2927
	global_load_dword v40, v[44:45], off nt
.LBB0_2927:
	s_or_b64 exec, exec, s[10:11]
	v_lshl_add_u64 v[44:45], s[46:47], 2, v[44:45]
	s_and_saveexec_b64 s[10:11], vcc
	s_cbranch_execz .LBB0_2929
	global_load_dword v41, v[44:45], off nt
.LBB0_2929:
	s_or_b64 exec, exec, s[10:11]
	v_lshl_add_u64 v[46:47], s[46:47], 2, v[44:45]
	v_mov_b32_e32 v45, 0
	v_mov_b32_e32 v44, 0
	s_and_saveexec_b64 s[10:11], vcc
	s_cbranch_execz .LBB0_2931
	global_load_dword v44, v[46:47], off nt
.LBB0_2931:
	s_or_b64 exec, exec, s[10:11]
	v_lshl_add_u64 v[46:47], s[46:47], 2, v[46:47]
	s_and_saveexec_b64 s[10:11], vcc
	s_cbranch_execz .LBB0_2933
	global_load_dword v45, v[46:47], off nt
.LBB0_2933:
	s_or_b64 exec, exec, s[10:11]
	v_lshl_add_u64 v[50:51], s[46:47], 2, v[46:47]
	v_mov_b32_e32 v47, 0
	v_mov_b32_e32 v46, 0
	s_and_saveexec_b64 s[10:11], vcc
	s_cbranch_execz .LBB0_2935
	global_load_dword v46, v[50:51], off nt
.LBB0_2935:
	s_or_b64 exec, exec, s[10:11]
	v_lshl_add_u64 v[50:51], s[46:47], 2, v[50:51]
	s_and_saveexec_b64 s[10:11], vcc
	s_cbranch_execz .LBB0_2937
	global_load_dword v47, v[50:51], off nt
.LBB0_2937:
	s_or_b64 exec, exec, s[10:11]
	v_lshl_add_u64 v[72:73], s[46:47], 2, v[50:51]
	v_mov_b32_e32 v4, 0
	s_and_saveexec_b64 s[10:11], vcc
	s_cbranch_execz .LBB0_2939
	global_load_dword v4, v[72:73], off nt
.LBB0_2939:
	s_or_b64 exec, exec, s[10:11]
	v_mov_b32_e32 v50, v5
	v_mov_b32_e32 v51, v5
	s_waitcnt vmcnt(0)
	v_mov_b64_e32 v[52:53], v[4:5]
	s_and_saveexec_b64 s[10:11], vcc
	s_cbranch_execz .LBB0_2941
	s_lshl_b64 s[64:65], s[46:47], 2
	v_lshl_add_u64 v[50:51], v[72:73], 0, s[64:65]
	v_lshl_add_u64 v[72:73], v[50:51], 0, s[64:65]
	v_lshl_add_u64 v[74:75], v[72:73], 0, s[64:65]
	global_load_dword v53, v[50:51], off nt
	s_nop 0
	global_load_dword v50, v[72:73], off nt
	global_load_dword v51, v[74:75], off nt
	v_mov_b32_e32 v52, v4

; __device__ __forceinline__ void tr_load(const TrItem& t, float (&tv)[32], int lane) {
;     const int nn = t.n0 + (lane & 31); const bool ok = nn < t.N;
;     const float* p = t.W + (size_t)(t.k0 + 32 * (lane >> 5)) * t.N + nn; const size_t st = (size_t)t.N;
; #pragma unroll
;     for (int i = 0; i < 32; ++i) { tv[i] = ok ? *p : 0.f; p += st; }
; }
.LBB0_2984:
	s_andn2_b64 vcc, exec, s[8:9]
	s_cbranch_vccnz .LBB0_3046
	v_add_u32_e32 v11, s48, v2
	v_add_u32_e32 v10, s66, v1
	v_mad_i64_i32 v[18:19], s[8:9], v11, s52, 0
	v_lshl_add_u64 v[18:19], v[18:19], 2, s[38:39]
	v_ashrrev_i32_e32 v11, 31, v10
	v_cmp_gt_i32_e32 vcc, s52, v10
	v_lshl_add_u64 v[18:19], v[10:11], 2, v[18:19]
	v_mov_b32_e32 v11, 0
	v_mov_b32_e32 v10, 0
	s_and_saveexec_b64 s[8:9], vcc
	s_cbranch_execz .LBB0_2987
	global_load_dword v10, v[18:19], off nt
.LBB0_2987:
	s_or_b64 exec, exec, s[8:9]
	s_ashr_i32 s53, s52, 31
	v_lshl_add_u64 v[18:19], s[52:53], 2, v[18:19]
	s_and_saveexec_b64 s[8:9], vcc
	s_cbranch_execz .LBB0_2989
	global_load_dword v11, v[18:19], off nt
.LBB0_2989:
	s_or_b64 exec, exec, s[8:9]
	v_lshl_add_u64 v[24:25], s[52:53], 2, v[18:19]
	v_mov_b32_e32 v19, 0
	v_mov_b32_e32 v18, 0
	s_and_saveexec_b64 s[8:9], vcc
	s_cbranch_execz .LBB0_2991
	global_load_dword v18, v[24:25], off nt
.LBB0_2991:
	s_or_b64 exec, exec, s[8:9]
	v_lshl_add_u64 v[24:25], s[52:53], 2, v[24:25]
	s_and_saveexec_b64 s[8:9], vcc
	s_cbranch_execz .LBB0_2993
	global_load_dword v19, v[24:25], off nt
.LBB0_2993:
	s_or_b64 exec, exec, s[8:9]
	v_lshl_add_u64 v[30:31], s[52:53], 2, v[24:25]
	v_mov_b32_e32 v25, 0
	v_mov_b32_e32 v24, 0
	s_and_saveexec_b64 s[8:9], vcc
	s_cbranch_execz .LBB0_2995
	global_load_dword v24, v[30:31], off nt
.LBB0_2995:
	s_or_b64 exec, exec, s[8:9]
	v_lshl_add_u64 v[30:31], s[52:53], 2, v[30:31]
	s_and_saveexec_b64 s[8:9], vcc
	s_cbranch_execz .LBB0_2997
	global_load_dword v25, v[30:31], off nt
.LBB0_2997:
	s_or_b64 exec, exec, s[8:9]
	v_lshl_add_u64 v[36:37], s[52:53], 2, v[30:31]
	v_mov_b32_e32 v31, 0
	v_mov_b32_e32 v30, 0
	s_and_saveexec_b64 s[8:9], vcc
	s_cbranch_execz .LBB0_2999
	global_load_dword v30, v[36:37], off nt
.LBB0_2999:
	s_or_b64 exec, exec, s[8:9]
	v_lshl_add_u64 v[36:37], s[52:53], 2, v[36:37]
	s_and_saveexec_b64 s[8:9], vcc
	s_cbranch_execz .LBB0_3001
	global_load_dword v31, v[36:37], off nt
.LBB0_3001:
	s_or_b64 exec, exec, s[8:9]
	v_lshl_add_u64 v[42:43], s[52:53], 2, v[36:37]
	v_mov_b32_e32 v37, 0
	v_mov_b32_e32 v36, 0
	s_and_saveexec_b64 s[8:9], vcc
	s_cbranch_execz .LBB0_3003
	global_load_dword v36, v[42:43], off nt
.LBB0_3003:
	s_or_b64 exec, exec, s[8:9]
	v_lshl_add_u64 v[42:43], s[52:53], 2, v[42:43]
	s_and_saveexec_b64 s[8:9], vcc
	s_cbranch_execz .LBB0_3005
	global_load_dword v37, v[42:43], off nt
.LBB0_3005:
	s_or_b64 exec, exec, s[8:9]
	v_lshl_add_u64 v[48:49], s[52:53], 2, v[42:43]
	v_mov_b32_e32 v43, 0
	v_mov_b32_e32 v42, 0
	s_and_saveexec_b64 s[8:9], vcc
	s_cbranch_execz .LBB0_3007
	global_load_dword v42, v[48:49], off nt
.LBB0_3007:
	s_or_b64 exec, exec, s[8:9]
	v_lshl_add_u64 v[48:49], s[52:53], 2, v[48:49]
	s_and_saveexec_b64 s[8:9], vcc
	s_cbranch_execz .LBB0_3009
	global_load_dword v43, v[48:49], off nt
.LBB0_3009:
	s_or_b64 exec, exec, s[8:9]
	v_lshl_add_u64 v[54:55], s[52:53], 2, v[48:49]
	v_mov_b32_e32 v49, 0
	v_mov_b32_e32 v48, 0
	s_and_saveexec_b64 s[8:9], vcc
	s_cbranch_execz .LBB0_3011
	global_load_dword v48, v[54:55], off nt
.LBB0_3011:
	s_or_b64 exec, exec, s[8:9]
	v_lshl_add_u64 v[54:55], s[52:53], 2, v[54:55]
	s_and_saveexec_b64 s[8:9], vcc
	s_cbranch_execz .LBB0_3013
	global_load_dword v49, v[54:55], off nt
.LBB0_3013:
	s_or_b64 exec, exec, s[8:9]
	v_lshl_add_u64 v[56:57], s[52:53], 2, v[54:55]
	v_mov_b32_e32 v55, 0
	v_mov_b32_e32 v54, 0
	s_and_saveexec_b64 s[8:9], vcc
	s_cbranch_execz .LBB0_3015
	global_load_dword v54, v[56:57], off nt
.LBB0_3015:
	s_or_b64 exec, exec, s[8:9]
	v_lshl_add_u64 v[56:57], s[52:53], 2, v[56:57]
	s_and_saveexec_b64 s[8:9], vcc
	s_cbranch_execz .LBB0_3017
	global_load_dword v55, v[56:57], off nt
.LBB0_3017:
	s_or_b64 exec, exec, s[8:9]
	v_lshl_add_u64 v[58:59], s[52:53], 2, v[56:57]
	v_mov_b32_e32 v57, 0
	v_mov_b32_e32 v56, 0
	s_and_saveexec_b64 s[8:9], vcc
	s_cbranch_execz .LBB0_3019
	global_load_dword v56, v[58:59], off nt
.LBB0_3019:
	s_or_b64 exec, exec, s[8:9]
	v_lshl_add_u64 v[58:59], s[52:53], 2, v[58:59]
	s_and_saveexec_b64 s[8:9], vcc
	s_cbranch_execz .LBB0_3021
	global_load_dword v57, v[58:59], off nt

; __device__ __forceinline__ void tr_load(const TrItem& t, float (&tv)[32], int lane) {
;     const int nn = t.n0 + (lane & 31); const bool ok = nn < t.N;
;     const float* p = t.W + (size_t)(t.k0 + 32 * (lane >> 5)) * t.N + nn; const size_t st = (size_t)t.N;
; #pragma unroll
;     for (int i = 0; i < 32; ++i) { tv[i] = ok ? *p : 0.f; p += st; }
; }
.LBB0_3041:
	s_or_b64 exec, exec, s[8:9]
	v_lshl_add_u64 v[74:75], s[52:53], 2, v[68:69]
	v_mov_b32_e32 v68, 0
	s_and_saveexec_b64 s[8:9], vcc
	s_cbranch_execz .LBB0_3043
	global_load_dword v68, v[74:75], off nt

; __device__ __forceinline__ void tr_load(const TrItem& t, float (&tv)[32], int lane) {
;     const int nn = t.n0 + (lane & 31); const bool ok = nn < t.N;
;     const float* p = t.W + (size_t)(t.k0 + 32 * (lane >> 5)) * t.N + nn; const size_t st = (size_t)t.N;
; #pragma unroll
;     for (int i = 0; i < 32; ++i) { tv[i] = ok ? *p : 0.f; p += st; }
; }
.LBB0_3150:
	v_cndmask_b32_e64 v4, 0, 1, s[10:11]
	v_cmp_ne_u32_e64 s[8:9], 1, v4
	s_andn2_b64 vcc, exec, s[10:11]
	s_cbranch_vccnz .LBB0_3212
	v_add_u32_e32 v4, s52, v2
	s_waitcnt vmcnt(4)
	v_add_u32_e32 v10, s63, v1
	v_mad_i64_i32 v[18:19], s[10:11], v4, s64, 0
	v_lshl_add_u64 v[18:19], v[18:19], 2, s[42:43]
	v_ashrrev_i32_e32 v11, 31, v10
	v_cmp_gt_i32_e32 vcc, s64, v10
	v_lshl_add_u64 v[18:19], v[10:11], 2, v[18:19]
	v_mov_b32_e32 v11, 0
	v_mov_b32_e32 v10, 0
	s_and_saveexec_b64 s[10:11], vcc
	s_cbranch_execz .LBB0_3153
	global_load_dword v10, v[18:19], off nt
.LBB0_3153:
	s_or_b64 exec, exec, s[10:11]
	s_ashr_i32 s65, s64, 31
	v_lshl_add_u64 v[18:19], s[64:65], 2, v[18:19]
	s_and_saveexec_b64 s[10:11], vcc
	s_cbranch_execz .LBB0_3155
	global_load_dword v11, v[18:19], off nt
.LBB0_3155:
	s_or_b64 exec, exec, s[10:11]
	v_lshl_add_u64 v[24:25], s[64:65], 2, v[18:19]
	v_mov_b32_e32 v19, 0
	v_mov_b32_e32 v18, 0
	s_and_saveexec_b64 s[10:11], vcc
	s_cbranch_execz .LBB0_3157
	global_load_dword v18, v[24:25], off nt
.LBB0_3157:
	s_or_b64 exec, exec, s[10:11]
	v_lshl_add_u64 v[24:25], s[64:65], 2, v[24:25]
	s_and_saveexec_b64 s[10:11], vcc
	s_cbranch_execz .LBB0_3159
	global_load_dword v19, v[24:25], off nt
.LBB0_3159:
	s_or_b64 exec, exec, s[10:11]
	v_lshl_add_u64 v[30:31], s[64:65], 2, v[24:25]
	v_mov_b32_e32 v25, 0
	v_mov_b32_e32 v24, 0
	s_and_saveexec_b64 s[10:11], vcc
	s_cbranch_execz .LBB0_3161
	global_load_dword v24, v[30:31], off nt
.LBB0_3161:
	s_or_b64 exec, exec, s[10:11]
	v_lshl_add_u64 v[30:31], s[64:65], 2, v[30:31]
	s_and_saveexec_b64 s[10:11], vcc
	s_cbranch_execz .LBB0_3163
	global_load_dword v25, v[30:31], off nt
.LBB0_3163:
	s_or_b64 exec, exec, s[10:11]
	v_lshl_add_u64 v[36:37], s[64:65], 2, v[30:31]
	v_mov_b32_e32 v31, 0
	v_mov_b32_e32 v30, 0
	s_and_saveexec_b64 s[10:11], vcc
	s_cbranch_execz .LBB0_3165
	global_load_dword v30, v[36:37], off nt
.LBB0_3165:
	s_or_b64 exec, exec, s[10:11]
	v_lshl_add_u64 v[36:37], s[64:65], 2, v[36:37]
	s_and_saveexec_b64 s[10:11], vcc
	s_cbranch_execz .LBB0_3167
	global_load_dword v31, v[36:37], off nt
.LBB0_3167:
	s_or_b64 exec, exec, s[10:11]
	v_lshl_add_u64 v[42:43], s[64:65], 2, v[36:37]
	v_mov_b32_e32 v37, 0
	v_mov_b32_e32 v36, 0
	s_and_saveexec_b64 s[10:11], vcc
	s_cbranch_execz .LBB0_3169
	global_load_dword v36, v[42:43], off nt
.LBB0_3169:
	s_or_b64 exec, exec, s[10:11]
	v_lshl_add_u64 v[42:43], s[64:65], 2, v[42:43]
	s_and_saveexec_b64 s[10:11], vcc
	s_cbranch_execz .LBB0_3171
	global_load_dword v37, v[42:43], off nt
.LBB0_3171:
	s_or_b64 exec, exec, s[10:11]
	v_lshl_add_u64 v[48:49], s[64:65], 2, v[42:43]
	v_mov_b32_e32 v43, 0
	v_mov_b32_e32 v42, 0
	s_and_saveexec_b64 s[10:11], vcc
	s_cbranch_execz .LBB0_3173
	global_load_dword v42, v[48:49], off nt
.LBB0_3173:
	s_or_b64 exec, exec, s[10:11]
	v_lshl_add_u64 v[48:49], s[64:65], 2, v[48:49]
	s_and_saveexec_b64 s[10:11], vcc
	s_cbranch_execz .LBB0_3175
	global_load_dword v43, v[48:49], off nt
.LBB0_3175:
	s_or_b64 exec, exec, s[10:11]
	v_lshl_add_u64 v[54:55], s[64:65], 2, v[48:49]
	v_mov_b32_e32 v49, 0
	v_mov_b32_e32 v48, 0
	s_and_saveexec_b64 s[10:11], vcc
	s_cbranch_execz .LBB0_3177
	global_load_dword v48, v[54:55], off nt
.LBB0_3177:
	s_or_b64 exec, exec, s[10:11]
	v_lshl_add_u64 v[54:55], s[64:65], 2, v[54:55]
	s_and_saveexec_b64 s[10:11], vcc
	s_cbranch_execz .LBB0_3179
	global_load_dword v49, v[54:55], off nt
.LBB0_3179:
	s_or_b64 exec, exec, s[10:11]
	v_lshl_add_u64 v[56:57], s[64:65], 2, v[54:55]
	v_mov_b32_e32 v55, 0
	v_mov_b32_e32 v54, 0
	s_and_saveexec_b64 s[10:11], vcc
	s_cbranch_execz .LBB0_3181
	global_load_dword v54, v[56:57], off nt
; __device__ __forceinline__ void tr_load(const TrItem& t, float (&tv)[32], int lane) {
;     const int nn = t.n0 + (lane & 31); const bool ok = nn < t.N;
;     const float* p = t.W + (size_t)(t.k0 + 32 * (lane >> 5)) * t.N + nn; const size_t st = (size_t)t.N;
; #pragma unroll
;     for (int i = 0; i < 32; ++i) { tv[i] = ok ? *p : 0.f; p += st; }
; }
.LBB0_3181:
	s_or_b64 exec, exec, s[10:11]
	v_lshl_add_u64 v[56:57], s[64:65], 2, v[56:57]
	s_and_saveexec_b64 s[10:11], vcc
	s_cbranch_execz .LBB0_3183
	global_load_dword v55, v[56:57], off nt
.LBB0_3183:
	s_or_b64 exec, exec, s[10:11]
	v_lshl_add_u64 v[58:59], s[64:65], 2, v[56:57]
	v_mov_b32_e32 v57, 0
	v_mov_b32_e32 v56, 0
	s_and_saveexec_b64 s[10:11], vcc
	s_cbranch_execz .LBB0_3185
	global_load_dword v56, v[58:59], off nt
.LBB0_3185:
	s_or_b64 exec, exec, s[10:11]
	v_lshl_add_u64 v[58:59], s[64:65], 2, v[58:59]
	s_and_saveexec_b64 s[10:11], vcc
	s_cbranch_execz .LBB0_3187
	global_load_dword v57, v[58:59], off nt
.LBB0_3187:
	s_or_b64 exec, exec, s[10:11]
	v_lshl_add_u64 v[60:61], s[64:65], 2, v[58:59]
	v_mov_b32_e32 v59, 0
	v_mov_b32_e32 v58, 0
	s_and_saveexec_b64 s[10:11], vcc
	s_cbranch_execz .LBB0_3189
	global_load_dword v58, v[60:61], off nt
.LBB0_3189:
	s_or_b64 exec, exec, s[10:11]
	v_lshl_add_u64 v[60:61], s[64:65], 2, v[60:61]
	s_and_saveexec_b64 s[10:11], vcc
	s_cbranch_execz .LBB0_3191
	global_load_dword v59, v[60:61], off nt
.LBB0_3191:
	s_or_b64 exec, exec, s[10:11]
	v_lshl_add_u64 v[62:63], s[64:65], 2, v[60:61]
	v_mov_b32_e32 v61, 0
	v_mov_b32_e32 v60, 0
	s_and_saveexec_b64 s[10:11], vcc
	s_cbranch_execz .LBB0_3193
	global_load_dword v60, v[62:63], off nt
.LBB0_3193:
	s_or_b64 exec, exec, s[10:11]
	v_lshl_add_u64 v[62:63], s[64:65], 2, v[62:63]
	s_and_saveexec_b64 s[10:11], vcc
	s_cbranch_execz .LBB0_3195
	global_load_dword v61, v[62:63], off nt
.LBB0_3195:
	s_or_b64 exec, exec, s[10:11]
	v_lshl_add_u64 v[64:65], s[64:65], 2, v[62:63]
	v_mov_b32_e32 v63, 0
	v_mov_b32_e32 v62, 0
	s_and_saveexec_b64 s[10:11], vcc
	s_cbranch_execz .LBB0_3197
	global_load_dword v62, v[64:65], off nt
.LBB0_3197:
	s_or_b64 exec, exec, s[10:11]
	v_lshl_add_u64 v[64:65], s[64:65], 2, v[64:65]
	s_and_saveexec_b64 s[10:11], vcc
	s_cbranch_execz .LBB0_3199
	global_load_dword v63, v[64:65], off nt
.LBB0_3199:
	s_or_b64 exec, exec, s[10:11]
	v_lshl_add_u64 v[66:67], s[64:65], 2, v[64:65]
	v_mov_b32_e32 v65, 0
	v_mov_b32_e32 v64, 0
	s_and_saveexec_b64 s[10:11], vcc
	s_cbranch_execz .LBB0_3201
	global_load_dword v64, v[66:67], off nt
.LBB0_3201:
	s_or_b64 exec, exec, s[10:11]
	v_lshl_add_u64 v[66:67], s[64:65], 2, v[66:67]
	s_and_saveexec_b64 s[10:11], vcc
	s_cbranch_execz .LBB0_3203
	global_load_dword v65, v[66:67], off nt
.LBB0_3203:
	s_or_b64 exec, exec, s[10:11]
	s_waitcnt vmcnt(2)
	v_lshl_add_u64 v[68:69], s[64:65], 2, v[66:67]
	v_mov_b32_e32 v67, 0
	v_mov_b32_e32 v66, 0
	s_and_saveexec_b64 s[10:11], vcc
	s_cbranch_execz .LBB0_3205
	global_load_dword v66, v[68:69], off nt
.LBB0_3205:
	s_or_b64 exec, exec, s[10:11]
	v_lshl_add_u64 v[68:69], s[64:65], 2, v[68:69]
	s_and_saveexec_b64 s[10:11], vcc
	s_cbranch_execz .LBB0_3207
	global_load_dword v67, v[68:69], off nt
.LBB0_3207:
	s_or_b64 exec, exec, s[10:11]
	v_lshl_add_u64 v[72:73], s[64:65], 2, v[68:69]
	v_mov_b32_e32 v4, 0
	s_and_saveexec_b64 s[10:11], vcc
	s_cbranch_execz .LBB0_3209
	global_load_dword v4, v[72:73], off nt
.LBB0_3209:
	s_or_b64 exec, exec, s[10:11]
	s_waitcnt vmcnt(1)
	v_mov_b32_e32 v70, v5
	s_waitcnt vmcnt(0)
	v_mov_b32_e32 v71, v5
	v_mov_b64_e32 v[68:69], v[4:5]
	s_and_saveexec_b64 s[10:11], vcc
	s_cbranch_execz .LBB0_3211
	s_lshl_b64 s[68:69], s[64:65], 2
	v_lshl_add_u64 v[68:69], v[72:73], 0, s[68:69]
	v_lshl_add_u64 v[70:71], v[68:69], 0, s[68:69]
	v_lshl_add_u64 v[72:73], v[70:71], 0, s[68:69]
	global_load_dword v69, v[68:69], off nt
	s_nop 0
	global_load_dword v70, v[70:71], off nt
	s_nop 0
	global_load_dword v71, v[72:73], off nt
	v_mov_b32_e32 v68, v4

; __device__ __forceinline__ void tr_load(const TrItem& t, float (&tv)[32], int lane) {
;     const int nn = t.n0 + (lane & 31); const bool ok = nn < t.N;
;     const float* p = t.W + (size_t)(t.k0 + 32 * (lane >> 5)) * t.N + nn; const size_t st = (size_t)t.N;
; #pragma unroll
;     for (int i = 0; i < 32; ++i) { tv[i] = ok ? *p : 0.f; p += st; }
; }
.LBB0_3222:
	v_cndmask_b32_e64 v4, 0, 1, s[10:11]
	v_cmp_ne_u32_e64 s[8:9], 1, v4
	s_andn2_b64 vcc, exec, s[10:11]
	s_cbranch_vccnz .LBB0_3284
	v_add_u32_e32 v4, s44, v2
	v_add_u32_e32 v8, s60, v1
	v_mad_i64_i32 v[12:13], s[10:11], v4, s50, 0
	v_lshl_add_u64 v[12:13], v[12:13], 2, s[14:15]
	v_ashrrev_i32_e32 v9, 31, v8
	v_cmp_gt_i32_e32 vcc, s50, v8
	v_lshl_add_u64 v[12:13], v[8:9], 2, v[12:13]
	v_mov_b32_e32 v9, 0
	v_mov_b32_e32 v8, 0
	s_and_saveexec_b64 s[10:11], vcc
	s_cbranch_execz .LBB0_3225
	global_load_dword v8, v[12:13], off nt
.LBB0_3225:
	s_or_b64 exec, exec, s[10:11]
	s_ashr_i32 s51, s50, 31
	v_lshl_add_u64 v[12:13], s[50:51], 2, v[12:13]
	s_and_saveexec_b64 s[10:11], vcc
	s_cbranch_execz .LBB0_3227
	global_load_dword v9, v[12:13], off nt
.LBB0_3227:
	s_or_b64 exec, exec, s[10:11]
	v_lshl_add_u64 v[14:15], s[50:51], 2, v[12:13]
	v_mov_b32_e32 v13, 0
	v_mov_b32_e32 v12, 0
	s_and_saveexec_b64 s[10:11], vcc
	s_cbranch_execz .LBB0_3229
	global_load_dword v12, v[14:15], off nt
.LBB0_3229:
	s_or_b64 exec, exec, s[10:11]
	v_lshl_add_u64 v[14:15], s[50:51], 2, v[14:15]
	s_and_saveexec_b64 s[10:11], vcc
	s_cbranch_execz .LBB0_3231
	global_load_dword v13, v[14:15], off nt
.LBB0_3231:
	s_or_b64 exec, exec, s[10:11]
	v_lshl_add_u64 v[16:17], s[50:51], 2, v[14:15]
	v_mov_b32_e32 v15, 0
	v_mov_b32_e32 v14, 0
	s_and_saveexec_b64 s[10:11], vcc
	s_cbranch_execz .LBB0_3233
	global_load_dword v14, v[16:17], off nt
.LBB0_3233:
	s_or_b64 exec, exec, s[10:11]
	v_lshl_add_u64 v[16:17], s[50:51], 2, v[16:17]
	s_and_saveexec_b64 s[10:11], vcc
	s_cbranch_execz .LBB0_3235
	global_load_dword v15, v[16:17], off nt
.LBB0_3235:
	s_or_b64 exec, exec, s[10:11]
	v_lshl_add_u64 v[20:21], s[50:51], 2, v[16:17]
	v_mov_b32_e32 v17, 0
	v_mov_b32_e32 v16, 0
	s_and_saveexec_b64 s[10:11], vcc
	s_cbranch_execz .LBB0_3237
	global_load_dword v16, v[20:21], off nt
.LBB0_3237:
	s_or_b64 exec, exec, s[10:11]
	v_lshl_add_u64 v[20:21], s[50:51], 2, v[20:21]
	s_and_saveexec_b64 s[10:11], vcc
	s_cbranch_execz .LBB0_3239
	global_load_dword v17, v[20:21], off nt
.LBB0_3239:
	s_or_b64 exec, exec, s[10:11]
	v_lshl_add_u64 v[22:23], s[50:51], 2, v[20:21]
	v_mov_b32_e32 v21, 0
	v_mov_b32_e32 v20, 0
	s_and_saveexec_b64 s[10:11], vcc
	s_cbranch_execz .LBB0_3241
	global_load_dword v20, v[22:23], off nt
.LBB0_3241:
	s_or_b64 exec, exec, s[10:11]
	v_lshl_add_u64 v[22:23], s[50:51], 2, v[22:23]
	s_and_saveexec_b64 s[10:11], vcc
	s_cbranch_execz .LBB0_3243
	global_load_dword v21, v[22:23], off nt
.LBB0_3243:
	s_or_b64 exec, exec, s[10:11]
	v_lshl_add_u64 v[26:27], s[50:51], 2, v[22:23]
	v_mov_b32_e32 v23, 0
	v_mov_b32_e32 v22, 0
	s_and_saveexec_b64 s[10:11], vcc
	s_cbranch_execz .LBB0_3245
	global_load_dword v22, v[26:27], off nt
.LBB0_3245:
	s_or_b64 exec, exec, s[10:11]
	v_lshl_add_u64 v[26:27], s[50:51], 2, v[26:27]
	s_and_saveexec_b64 s[10:11], vcc
	s_cbranch_execz .LBB0_3247
	global_load_dword v23, v[26:27], off nt
.LBB0_3247:
	s_or_b64 exec, exec, s[10:11]
	v_lshl_add_u64 v[28:29], s[50:51], 2, v[26:27]
	v_mov_b32_e32 v27, 0
	v_mov_b32_e32 v26, 0
	s_and_saveexec_b64 s[10:11], vcc
	s_cbranch_execz .LBB0_3249
	global_load_dword v26, v[28:29], off nt
.LBB0_3249:
	s_or_b64 exec, exec, s[10:11]
	v_lshl_add_u64 v[28:29], s[50:51], 2, v[28:29]
	s_and_saveexec_b64 s[10:11], vcc
	s_cbranch_execz .LBB0_3251
	global_load_dword v27, v[28:29], off nt
.LBB0_3251:
	s_or_b64 exec, exec, s[10:11]
	v_lshl_add_u64 v[32:33], s[50:51], 2, v[28:29]
	v_mov_b32_e32 v29, 0
	v_mov_b32_e32 v28, 0
	s_and_saveexec_b64 s[10:11], vcc
	s_cbranch_execz .LBB0_3253
	global_load_dword v28, v[32:33], off nt
; __device__ __forceinline__ void tr_load(const TrItem& t, float (&tv)[32], int lane) {
;     const int nn = t.n0 + (lane & 31); const bool ok = nn < t.N;
;     const float* p = t.W + (size_t)(t.k0 + 32 * (lane >> 5)) * t.N + nn; const size_t st = (size_t)t.N;
; #pragma unroll
;     for (int i = 0; i < 32; ++i) { tv[i] = ok ? *p : 0.f; p += st; }
; }
.LBB0_3253:
	s_or_b64 exec, exec, s[10:11]
	v_lshl_add_u64 v[32:33], s[50:51], 2, v[32:33]
	s_and_saveexec_b64 s[10:11], vcc
	s_cbranch_execz .LBB0_3255
	global_load_dword v29, v[32:33], off nt
.LBB0_3255:
	s_or_b64 exec, exec, s[10:11]
	v_lshl_add_u64 v[34:35], s[50:51], 2, v[32:33]
	v_mov_b32_e32 v33, 0
	v_mov_b32_e32 v32, 0
	s_and_saveexec_b64 s[10:11], vcc
	s_cbranch_execz .LBB0_3257
	global_load_dword v32, v[34:35], off nt
.LBB0_3257:
	s_or_b64 exec, exec, s[10:11]
	v_lshl_add_u64 v[34:35], s[50:51], 2, v[34:35]
	s_and_saveexec_b64 s[10:11], vcc
	s_cbranch_execz .LBB0_3259
	global_load_dword v33, v[34:35], off nt
.LBB0_3259:
	s_or_b64 exec, exec, s[10:11]
	v_lshl_add_u64 v[38:39], s[50:51], 2, v[34:35]
	v_mov_b32_e32 v35, 0
	v_mov_b32_e32 v34, 0
	s_and_saveexec_b64 s[10:11], vcc
	s_cbranch_execz .LBB0_3261
	global_load_dword v34, v[38:39], off nt
.LBB0_3261:
	s_or_b64 exec, exec, s[10:11]
	v_lshl_add_u64 v[38:39], s[50:51], 2, v[38:39]
	s_and_saveexec_b64 s[10:11], vcc
	s_cbranch_execz .LBB0_3263
	global_load_dword v35, v[38:39], off nt
.LBB0_3263:
	s_or_b64 exec, exec, s[10:11]
	v_lshl_add_u64 v[40:41], s[50:51], 2, v[38:39]
	v_mov_b32_e32 v39, 0
	v_mov_b32_e32 v38, 0
	s_and_saveexec_b64 s[10:11], vcc
	s_cbranch_execz .LBB0_3265
	global_load_dword v38, v[40:41], off nt
.LBB0_3265:
	s_or_b64 exec, exec, s[10:11]
	v_lshl_add_u64 v[40:41], s[50:51], 2, v[40:41]
	s_and_saveexec_b64 s[10:11], vcc
	s_cbranch_execz .LBB0_3267
	global_load_dword v39, v[40:41], off nt
.LBB0_3267:
	s_or_b64 exec, exec, s[10:11]
	v_lshl_add_u64 v[44:45], s[50:51], 2, v[40:41]
	v_mov_b32_e32 v41, 0
	v_mov_b32_e32 v40, 0
	s_and_saveexec_b64 s[10:11], vcc
	s_cbranch_execz .LBB0_3269
	global_load_dword v40, v[44:45], off nt
.LBB0_3269:
	s_or_b64 exec, exec, s[10:11]
	v_lshl_add_u64 v[44:45], s[50:51], 2, v[44:45]
	s_and_saveexec_b64 s[10:11], vcc
	s_cbranch_execz .LBB0_3271
	global_load_dword v41, v[44:45], off nt
.LBB0_3271:
	s_or_b64 exec, exec, s[10:11]
	v_lshl_add_u64 v[46:47], s[50:51], 2, v[44:45]
	v_mov_b32_e32 v45, 0
	v_mov_b32_e32 v44, 0
	s_and_saveexec_b64 s[10:11], vcc
	s_cbranch_execz .LBB0_3273
	global_load_dword v44, v[46:47], off nt
.LBB0_3273:
	s_or_b64 exec, exec, s[10:11]
	v_lshl_add_u64 v[46:47], s[50:51], 2, v[46:47]
	s_and_saveexec_b64 s[10:11], vcc
	s_cbranch_execz .LBB0_3275
	global_load_dword v45, v[46:47], off nt
.LBB0_3275:
	s_or_b64 exec, exec, s[10:11]
	v_lshl_add_u64 v[50:51], s[50:51], 2, v[46:47]
	v_mov_b32_e32 v47, 0
	v_mov_b32_e32 v46, 0
	s_and_saveexec_b64 s[10:11], vcc
	s_cbranch_execz .LBB0_3277
	global_load_dword v46, v[50:51], off nt
.LBB0_3277:
	s_or_b64 exec, exec, s[10:11]
	v_lshl_add_u64 v[50:51], s[50:51], 2, v[50:51]
	s_and_saveexec_b64 s[10:11], vcc
	s_cbranch_execz .LBB0_3279
	global_load_dword v47, v[50:51], off nt
.LBB0_3279:
	s_or_b64 exec, exec, s[10:11]
	v_lshl_add_u64 v[72:73], s[50:51], 2, v[50:51]
	v_mov_b32_e32 v4, 0
	s_and_saveexec_b64 s[10:11], vcc
	s_cbranch_execz .LBB0_3281
	global_load_dword v4, v[72:73], off nt
.LBB0_3281:
	s_or_b64 exec, exec, s[10:11]
	v_mov_b32_e32 v50, v5
	v_mov_b32_e32 v51, v5
	s_waitcnt vmcnt(0)
	v_mov_b64_e32 v[52:53], v[4:5]
	s_and_saveexec_b64 s[10:11], vcc
	s_cbranch_execz .LBB0_3283
	s_lshl_b64 s[68:69], s[50:51], 2
	v_lshl_add_u64 v[50:51], v[72:73], 0, s[68:69]
	v_lshl_add_u64 v[72:73], v[50:51], 0, s[68:69]
	v_lshl_add_u64 v[74:75], v[72:73], 0, s[68:69]
	global_load_dword v53, v[50:51], off nt
	s_nop 0
	global_load_dword v50, v[72:73], off nt
	global_load_dword v51, v[74:75], off nt
	v_mov_b32_e32 v52, v4

; __device__ __forceinline__ void tr_load(const TrItem& t, float (&tv)[32], int lane) {
;     const int nn = t.n0 + (lane & 31); const bool ok = nn < t.N;
;     const float* p = t.W + (size_t)(t.k0 + 32 * (lane >> 5)) * t.N + nn; const size_t st = (size_t)t.N;
; #pragma unroll
;     for (int i = 0; i < 32; ++i) { tv[i] = ok ? *p : 0.f; p += st; }
; }
.LBB0_3326:
	s_andn2_b64 vcc, exec, s[8:9]
	s_cbranch_vccnz .LBB0_3388
	v_add_u32_e32 v11, s52, v2
	v_add_u32_e32 v10, s63, v1
	v_mad_i64_i32 v[18:19], s[8:9], v11, s64, 0
	v_lshl_add_u64 v[18:19], v[18:19], 2, s[42:43]
	v_ashrrev_i32_e32 v11, 31, v10
	v_cmp_gt_i32_e32 vcc, s64, v10
	v_lshl_add_u64 v[18:19], v[10:11], 2, v[18:19]
	v_mov_b32_e32 v11, 0
	v_mov_b32_e32 v10, 0
	s_and_saveexec_b64 s[8:9], vcc
	s_cbranch_execz .LBB0_3329
	global_load_dword v10, v[18:19], off nt
.LBB0_3329:
	s_or_b64 exec, exec, s[8:9]
	s_ashr_i32 s65, s64, 31
	v_lshl_add_u64 v[18:19], s[64:65], 2, v[18:19]
	s_and_saveexec_b64 s[8:9], vcc
	s_cbranch_execz .LBB0_3331
	global_load_dword v11, v[18:19], off nt
.LBB0_3331:
	s_or_b64 exec, exec, s[8:9]
	v_lshl_add_u64 v[24:25], s[64:65], 2, v[18:19]
	v_mov_b32_e32 v19, 0
	v_mov_b32_e32 v18, 0
	s_and_saveexec_b64 s[8:9], vcc
	s_cbranch_execz .LBB0_3333
	global_load_dword v18, v[24:25], off nt
.LBB0_3333:
	s_or_b64 exec, exec, s[8:9]
	v_lshl_add_u64 v[24:25], s[64:65], 2, v[24:25]
	s_and_saveexec_b64 s[8:9], vcc
	s_cbranch_execz .LBB0_3335
	global_load_dword v19, v[24:25], off nt
.LBB0_3335:
	s_or_b64 exec, exec, s[8:9]
	v_lshl_add_u64 v[30:31], s[64:65], 2, v[24:25]
	v_mov_b32_e32 v25, 0
	v_mov_b32_e32 v24, 0
	s_and_saveexec_b64 s[8:9], vcc
	s_cbranch_execz .LBB0_3337
	global_load_dword v24, v[30:31], off nt
.LBB0_3337:
	s_or_b64 exec, exec, s[8:9]
	v_lshl_add_u64 v[30:31], s[64:65], 2, v[30:31]
	s_and_saveexec_b64 s[8:9], vcc
	s_cbranch_execz .LBB0_3339
	global_load_dword v25, v[30:31], off nt
.LBB0_3339:
	s_or_b64 exec, exec, s[8:9]
	v_lshl_add_u64 v[36:37], s[64:65], 2, v[30:31]
	v_mov_b32_e32 v31, 0
	v_mov_b32_e32 v30, 0
	s_and_saveexec_b64 s[8:9], vcc
	s_cbranch_execz .LBB0_3341
	global_load_dword v30, v[36:37], off nt
.LBB0_3341:
	s_or_b64 exec, exec, s[8:9]
	v_lshl_add_u64 v[36:37], s[64:65], 2, v[36:37]
	s_and_saveexec_b64 s[8:9], vcc
	s_cbranch_execz .LBB0_3343
	global_load_dword v31, v[36:37], off nt
.LBB0_3343:
	s_or_b64 exec, exec, s[8:9]
	v_lshl_add_u64 v[42:43], s[64:65], 2, v[36:37]
	v_mov_b32_e32 v37, 0
	v_mov_b32_e32 v36, 0
	s_and_saveexec_b64 s[8:9], vcc
	s_cbranch_execz .LBB0_3345
	global_load_dword v36, v[42:43], off nt
.LBB0_3345:
	s_or_b64 exec, exec, s[8:9]
	v_lshl_add_u64 v[42:43], s[64:65], 2, v[42:43]
	s_and_saveexec_b64 s[8:9], vcc
	s_cbranch_execz .LBB0_3347
	global_load_dword v37, v[42:43], off nt
.LBB0_3347:
	s_or_b64 exec, exec, s[8:9]
	v_lshl_add_u64 v[48:49], s[64:65], 2, v[42:43]
	v_mov_b32_e32 v43, 0
	v_mov_b32_e32 v42, 0
	s_and_saveexec_b64 s[8:9], vcc
	s_cbranch_execz .LBB0_3349
	global_load_dword v42, v[48:49], off nt
.LBB0_3349:
	s_or_b64 exec, exec, s[8:9]
	v_lshl_add_u64 v[48:49], s[64:65], 2, v[48:49]
	s_and_saveexec_b64 s[8:9], vcc
	s_cbranch_execz .LBB0_3351
	global_load_dword v43, v[48:49], off nt
.LBB0_3351:
	s_or_b64 exec, exec, s[8:9]
	v_lshl_add_u64 v[54:55], s[64:65], 2, v[48:49]
	v_mov_b32_e32 v49, 0
	v_mov_b32_e32 v48, 0
	s_and_saveexec_b64 s[8:9], vcc
	s_cbranch_execz .LBB0_3353
	global_load_dword v48, v[54:55], off nt
.LBB0_3353:
	s_or_b64 exec, exec, s[8:9]
	v_lshl_add_u64 v[54:55], s[64:65], 2, v[54:55]
	s_and_saveexec_b64 s[8:9], vcc
	s_cbranch_execz .LBB0_3355
	global_load_dword v49, v[54:55], off nt
.LBB0_3355:
	s_or_b64 exec, exec, s[8:9]
	v_lshl_add_u64 v[56:57], s[64:65], 2, v[54:55]
	v_mov_b32_e32 v55, 0
	v_mov_b32_e32 v54, 0
	s_and_saveexec_b64 s[8:9], vcc
	s_cbranch_execz .LBB0_3357
	global_load_dword v54, v[56:57], off nt
.LBB0_3357:
	s_or_b64 exec, exec, s[8:9]
	v_lshl_add_u64 v[56:57], s[64:65], 2, v[56:57]
	s_and_saveexec_b64 s[8:9], vcc
	s_cbranch_execz .LBB0_3359
	global_load_dword v55, v[56:57], off nt
.LBB0_3359:
	s_or_b64 exec, exec, s[8:9]
	v_lshl_add_u64 v[58:59], s[64:65], 2, v[56:57]
	v_mov_b32_e32 v57, 0
	v_mov_b32_e32 v56, 0
	s_and_saveexec_b64 s[8:9], vcc
	s_cbranch_execz .LBB0_3361
	global_load_dword v56, v[58:59], off nt
.LBB0_3361:
	s_or_b64 exec, exec, s[8:9]
	v_lshl_add_u64 v[58:59], s[64:65], 2, v[58:59]
	s_and_saveexec_b64 s[8:9], vcc
	s_cbranch_execz .LBB0_3363
	global_load_dword v57, v[58:59], off nt
.LBB0_3363:
	s_or_b64 exec, exec, s[8:9]
	v_lshl_add_u64 v[60:61], s[64:65], 2, v[58:59]
	v_mov_b32_e32 v59, 0
	v_mov_b32_e32 v58, 0
	s_and_saveexec_b64 s[8:9], vcc
	s_cbranch_execz .LBB0_3365
	global_load_dword v58, v[60:61], off nt
.LBB0_3365:
	s_or_b64 exec, exec, s[8:9]
	v_lshl_add_u64 v[60:61], s[64:65], 2, v[60:61]
	s_and_saveexec_b64 s[8:9], vcc
	s_cbranch_execz .LBB0_3367
	global_load_dword v59, v[60:61], off nt
.LBB0_3367:
	s_or_b64 exec, exec, s[8:9]
	v_lshl_add_u64 v[62:63], s[64:65], 2, v[60:61]
	v_mov_b32_e32 v61, 0
	v_mov_b32_e32 v60, 0
	s_and_saveexec_b64 s[8:9], vcc
	s_cbranch_execz .LBB0_3369
	global_load_dword v60, v[62:63], off nt
.LBB0_3369:
	s_or_b64 exec, exec, s[8:9]
	v_lshl_add_u64 v[62:63], s[64:65], 2, v[62:63]
	s_and_saveexec_b64 s[8:9], vcc
	s_cbranch_execz .LBB0_3371
	global_load_dword v61, v[62:63], off nt
.LBB0_3371:
	s_or_b64 exec, exec, s[8:9]
	v_lshl_add_u64 v[64:65], s[64:65], 2, v[62:63]
	v_mov_b32_e32 v63, 0
	v_mov_b32_e32 v62, 0
	s_and_saveexec_b64 s[8:9], vcc
	s_cbranch_execz .LBB0_3373
	global_load_dword v62, v[64:65], off nt
.LBB0_3373:
	s_or_b64 exec, exec, s[8:9]
	v_lshl_add_u64 v[64:65], s[64:65], 2, v[64:65]
	s_and_saveexec_b64 s[8:9], vcc
	s_cbranch_execz .LBB0_3375
	global_load_dword v63, v[64:65], off nt
.LBB0_3375:
	s_or_b64 exec, exec, s[8:9]
	v_lshl_add_u64 v[66:67], s[64:65], 2, v[64:65]
	v_mov_b32_e32 v65, 0
	v_mov_b32_e32 v64, 0
	s_and_saveexec_b64 s[8:9], vcc
	s_cbranch_execz .LBB0_3377
	global_load_dword v64, v[66:67], off nt
.LBB0_3377:
	s_or_b64 exec, exec, s[8:9]
	v_lshl_add_u64 v[66:67], s[64:65], 2, v[66:67]
	s_and_saveexec_b64 s[8:9], vcc
	s_cbranch_execz .LBB0_3379
	global_load_dword v65, v[66:67], off nt
.LBB0_3379:
	s_or_b64 exec, exec, s[8:9]
	v_lshl_add_u64 v[68:69], s[64:65], 2, v[66:67]
	v_mov_b32_e32 v67, 0
	v_mov_b32_e32 v66, 0
	s_and_saveexec_b64 s[8:9], vcc
	s_cbranch_execz .LBB0_3381
	global_load_dword v66, v[68:69], off nt
.LBB0_3381:
	s_or_b64 exec, exec, s[8:9]
	v_lshl_add_u64 v[68:69], s[64:65], 2, v[68:69]
	s_and_saveexec_b64 s[8:9], vcc
	s_cbranch_execz .LBB0_3383
	global_load_dword v67, v[68:69], off nt
.LBB0_3383:
	s_or_b64 exec, exec, s[8:9]
	v_lshl_add_u64 v[74:75], s[64:65], 2, v[68:69]
	v_mov_b32_e32 v68, 0
	s_and_saveexec_b64 s[8:9], vcc
	s_cbranch_execz .LBB0_3385
	global_load_dword v68, v[74:75], off nt
